# PH2 GEMM loop converted to SGPR-base LDS-DMA addressing; LDS read address adds folded into ds_read offsets in 6 GEMM loops
# baseline (speedup 1.0000x reference)
; #define PG8_STAGE(bufoff, gbase, RR, ld) do { _Pragma("unroll") for (int _i = 0; _i < 2; ++_i) \
;         __builtin_amdgcn_global_load_lds((const unsigned*)((const char*)(gbase) + (RR)[_i] * (ld) + C2[_i]), (LAS unsigned*)(lds + (bufoff) + ldsw + _i * 8192), 16, 0, 0); } while (0)
; #define PG8_LDA(dst, b, h) do { _Pragma("unroll") for (int m = 0; m < 4; ++m) _Pragma("unroll") for (int k = 0; k < 2; ++k) dst[m][k] = *(const LAS bf16x8*)(lds + PG8_SA(b, h) + aoff + m * 2048 + k * 1024); } while (0)
; #define PG8_LDB(dst, b, h) do { _Pragma("unroll") for (int n = 0; n < 2; ++n) _Pragma("unroll") for (int k = 0; k < 2; ++k) dst[n][k] = *(const LAS bf16x8*)(lds + PG8_SB(b, h) + boff + n * 2048 + k * 1024); } while (0)
; #define PG8_WAIT_V(n) asm volatile("s_waitcnt vmcnt(" #n ")" ::: "memory")
; #define PG8_WAIT_L(n) asm volatile("s_waitcnt lgkmcnt(" #n ")" ::: "memory")
; #define PG8_BAR __builtin_amdgcn_s_barrier()
; #define PG8_SCHED __builtin_amdgcn_sched_barrier(0)
; template <class Sched, class Epi>
; __device__ __forceinline__ void gemm_run(LAS unsigned char* lds, const Sched& S, const Epi& E) {
;     ...
;     for (;;) {
;         const bool has_next = S.next(ui + 1, nxt);
;         const char* nA = has_next ? nxt.A : cA; const char* nB = has_next ? nxt.B : cB; const unsigned nlda = has_next ? nxt.lda : lda, nldb = has_next ? nxt.ldb : ldb;
;         const int nt = cur.nt;
;         for (int t = 0; t < nt; t += 2) {
;             const bool last = (t == nt - 2);
;             const char* a1 = cA + (size_t)(t + 1) * kstep;
;             const char* a2 = last ? nA : cA + (size_t)(t + 2) * kstep; const char* b2 = last ? nB : cB + (size_t)(t + 2) * kstep;
;             const unsigned la2 = last ? nlda : lda, lb2 = last ? nldb : ldb;
;             const char* a3 = a2 + kstep; const char* b3 = b2 + kstep;
;             PG8_LDB(B0, 0, 0); PG8_LDB(B1, 0, 1); PG8_SCHED; PG8_LDA(At, 0, 0); PG8_STAGE(PG8_SA(1, 1), a1 + (size_t)HALF * lda, RA, lda);
;             PG8_WAIT_V(8); PG8_WAIT_L(0); PG8_BAR; PG8_MMA(0, 0, At, B0); PG8_MMA(0, 1, At, B1); PG8_BAR; PG8_SCHED;
;             PG8_LDA(At, 0, 1); PG8_STAGE(PG8_SB(0, 0), b2, RB, lb2); PG8_STAGE(PG8_SB(0, 1), b2 + (size_t)HALF * lb2, RB, lb2); PG8_STAGE(PG8_SA(0, 0), a2, RA, la2);
;             PG8_WAIT_V(8); PG8_WAIT_L(0); PG8_BAR; PG8_MMA(1, 0, At, B0); PG8_MMA(1, 1, At, B1); PG8_BAR; PG8_SCHED;
.LBB0_245:
	s_add_u32 s12, s54, 0x100
	s_addc_u32 s33, s55, 0
	s_mov_b32 s38, -2
	s_mov_b64 s[54:55], 0
	s_waitcnt lgkmcnt(0)
	s_waitcnt vmcnt(0)
	ds_read_b128 v[154:157], v182
	ds_read_b128 v[158:161], v182 offset:1024
	ds_read_b128 v[162:165], v182 offset:2048
	ds_read_b128 v[166:169], v182 offset:3072
	ds_read_b128 v[170:173], v183
	ds_read_b128 v[186:189], v183 offset:1024
	ds_read_b128 v[190:193], v183 offset:2048
	ds_read_b128 v[194:197], v183 offset:3072
	s_add_u32 s39, s6, s54
	s_addc_u32 s40, s7, s55
	s_mov_b32 s98, s39
	s_mov_b32 s99, s40
	s_add_u32 s39, s39, 0x100
	s_addc_u32 s40, s40, 0
	s_add_u32 s41, s12, s54
	s_addc_u32 s42, s33, s55
	s_cmpk_eq_i32 s54, 0xf00
	s_cselect_b32 s59, s29, s40
	s_cselect_b32 s58, s28, s39
	s_cselect_b32 s57, s37, s42
	s_cselect_b32 s56, s36, s41
	s_add_i32 m0, s21, 0xc000
	ds_read_b128 v[198:201], v184
	ds_read_b128 v[202:205], v184 offset:1024
	ds_read_b128 v[206:209], v184 offset:2048
	ds_read_b128 v[210:213], v184 offset:3072
	ds_read_b128 v[214:217], v184 offset:4096
	ds_read_b128 v[218:221], v184 offset:5120
	ds_read_b128 v[222:225], v184 offset:6144
	ds_read_b128 v[226:229], v184 offset:7168
	global_load_lds_dwordx4 v146, s[98:99]
	s_add_i32 m0, s21, 0xe000
	s_nop 0
	global_load_lds_dwordx4 v148, s[98:99]
	s_waitcnt vmcnt(8)
	s_waitcnt lgkmcnt(0)
	s_barrier
	s_waitcnt lgkmcnt(0)
	v_mfma_f32_16x16x32_bf16 v[126:129], v[154:157], v[198:201], 0
	v_mfma_f32_16x16x32_bf16 v[122:125], v[162:165], v[198:201], 0
	v_mfma_f32_16x16x32_bf16 v[110:113], v[154:157], v[206:209], 0
	v_mfma_f32_16x16x32_bf16 v[106:109], v[162:165], v[206:209], 0
	v_mfma_f32_16x16x32_bf16 v[94:97], v[154:157], v[214:217], 0
	v_mfma_f32_16x16x32_bf16 v[90:93], v[162:165], v[214:217], 0
	v_mfma_f32_16x16x32_bf16 v[78:81], v[154:157], v[222:225], 0
	v_mfma_f32_16x16x32_bf16 v[74:77], v[162:165], v[222:225], 0
	v_mfma_f32_16x16x32_bf16 v[126:129], v[158:161], v[202:205], v[126:129]
	v_mfma_f32_16x16x32_bf16 v[122:125], v[166:169], v[202:205], v[122:125]
	v_mfma_f32_16x16x32_bf16 v[110:113], v[158:161], v[210:213], v[110:113]
	v_mfma_f32_16x16x32_bf16 v[106:109], v[166:169], v[210:213], v[106:109]
	v_mfma_f32_16x16x32_bf16 v[94:97], v[158:161], v[218:221], v[94:97]
	v_mfma_f32_16x16x32_bf16 v[90:93], v[166:169], v[218:221], v[90:93]
	v_mfma_f32_16x16x32_bf16 v[78:81], v[158:161], v[226:229], v[78:81]
	v_mfma_f32_16x16x32_bf16 v[74:77], v[166:169], v[226:229], v[74:77]
	v_mfma_f32_16x16x32_bf16 v[118:121], v[170:173], v[198:201], 0
	v_mfma_f32_16x16x32_bf16 v[114:117], v[190:193], v[198:201], 0
	v_mfma_f32_16x16x32_bf16 v[102:105], v[170:173], v[206:209], 0
	v_mfma_f32_16x16x32_bf16 v[98:101], v[190:193], v[206:209], 0
	v_mfma_f32_16x16x32_bf16 v[86:89], v[170:173], v[214:217], 0
	v_mfma_f32_16x16x32_bf16 v[82:85], v[190:193], v[214:217], 0
	v_mfma_f32_16x16x32_bf16 v[70:73], v[170:173], v[222:225], 0
	v_mfma_f32_16x16x32_bf16 v[66:69], v[190:193], v[222:225], 0
	v_mfma_f32_16x16x32_bf16 v[118:121], v[186:189], v[202:205], v[118:121]
	v_mfma_f32_16x16x32_bf16 v[114:117], v[194:197], v[202:205], v[114:117]
	v_mfma_f32_16x16x32_bf16 v[102:105], v[186:189], v[210:213], v[102:105]
	v_mfma_f32_16x16x32_bf16 v[98:101], v[194:197], v[210:213], v[98:101]
	v_mfma_f32_16x16x32_bf16 v[86:89], v[186:189], v[218:221], v[86:89]
	v_mfma_f32_16x16x32_bf16 v[82:85], v[194:197], v[218:221], v[82:85]
	v_mfma_f32_16x16x32_bf16 v[70:73], v[186:189], v[226:229], v[70:73]
	v_mfma_f32_16x16x32_bf16 v[66:69], v[194:197], v[226:229], v[66:69]
	s_barrier
	s_add_i32 s39, s71, s3
	s_mov_b32 m0, s39
	ds_read_b128 v[198:201], v184 offset:16384
	ds_read_b128 v[202:205], v184 offset:17408
	ds_read_b128 v[206:209], v184 offset:18432
	ds_read_b128 v[210:213], v184 offset:19456
	ds_read_b128 v[214:217], v184 offset:20480
	ds_read_b128 v[218:221], v184 offset:21504
	ds_read_b128 v[222:225], v184 offset:22528
	ds_read_b128 v[226:229], v184 offset:23552
	global_load_lds_dwordx4 v132, s[56:57]
	s_add_i32 m0, s39, 0x2000
	s_add_u32 s40, s56, 0x80000
	s_addc_u32 s41, s57, 0
	s_add_i32 s39, s72, s3
	global_load_lds_dwordx4 v136, s[56:57]
	s_mov_b32 m0, s39
	s_nop 0
	global_load_lds_dwordx4 v132, s[40:41]
	s_add_i32 m0, s39, 0x2000
	s_nop 0
	global_load_lds_dwordx4 v136, s[40:41]
	s_mov_b32 m0, s21
	s_nop 0
	global_load_lds_dwordx4 v138, s[58:59]
	s_mov_b32 m0, s35
	s_nop 0
	global_load_lds_dwordx4 v140, s[58:59]
	s_waitcnt vmcnt(8)
	s_waitcnt lgkmcnt(0)
	s_barrier
	s_waitcnt lgkmcnt(0)
	v_mfma_f32_16x16x32_bf16 v[62:65], v[154:157], v[198:201], 0
	v_mfma_f32_16x16x32_bf16 v[58:61], v[162:165], v[198:201], 0
	v_mfma_f32_16x16x32_bf16 v[46:49], v[154:157], v[206:209], 0
	v_mfma_f32_16x16x32_bf16 v[42:45], v[162:165], v[206:209], 0
	v_mfma_f32_16x16x32_bf16 v[30:33], v[154:157], v[214:217], 0
	v_mfma_f32_16x16x32_bf16 v[26:29], v[162:165], v[214:217], 0
	v_mfma_f32_16x16x32_bf16 v[14:17], v[154:157], v[222:225], 0
	v_mfma_f32_16x16x32_bf16 v[10:13], v[162:165], v[222:225], 0
	v_mfma_f32_16x16x32_bf16 v[62:65], v[158:161], v[202:205], v[62:65]
	v_mfma_f32_16x16x32_bf16 v[58:61], v[166:169], v[202:205], v[58:61]
	v_mfma_f32_16x16x32_bf16 v[46:49], v[158:161], v[210:213], v[46:49]
	v_mfma_f32_16x16x32_bf16 v[42:45], v[166:169], v[210:213], v[42:45]
	v_mfma_f32_16x16x32_bf16 v[30:33], v[158:161], v[218:221], v[30:33]
	v_mfma_f32_16x16x32_bf16 v[26:29], v[166:169], v[218:221], v[26:29]
	v_mfma_f32_16x16x32_bf16 v[14:17], v[158:161], v[226:229], v[14:17]
	v_mfma_f32_16x16x32_bf16 v[10:13], v[166:169], v[226:229], v[10:13]
	v_mfma_f32_16x16x32_bf16 v[54:57], v[170:173], v[198:201], 0
	v_mfma_f32_16x16x32_bf16 v[50:53], v[190:193], v[198:201], 0
	v_mfma_f32_16x16x32_bf16 v[38:41], v[170:173], v[206:209], 0
	v_mfma_f32_16x16x32_bf16 v[34:37], v[190:193], v[206:209], 0
	v_mfma_f32_16x16x32_bf16 v[22:25], v[170:173], v[214:217], 0
	v_mfma_f32_16x16x32_bf16 v[18:21], v[190:193], v[214:217], 0
	v_mfma_f32_16x16x32_bf16 v[6:9], v[170:173], v[222:225], 0
	v_mfma_f32_16x16x32_bf16 v[2:5], v[190:193], v[222:225], 0
	v_mfma_f32_16x16x32_bf16 v[54:57], v[186:189], v[202:205], v[54:57]
	v_mfma_f32_16x16x32_bf16 v[50:53], v[194:197], v[202:205], v[50:53]
	v_mfma_f32_16x16x32_bf16 v[38:41], v[186:189], v[210:213], v[38:41]
	v_mfma_f32_16x16x32_bf16 v[34:37], v[194:197], v[210:213], v[34:37]
	v_mfma_f32_16x16x32_bf16 v[22:25], v[186:189], v[218:221], v[22:25]
	v_mfma_f32_16x16x32_bf16 v[18:21], v[194:197], v[218:221], v[18:21]
	v_mfma_f32_16x16x32_bf16 v[6:9], v[186:189], v[226:229], v[6:9]
	v_mfma_f32_16x16x32_bf16 v[2:5], v[194:197], v[226:229], v[2:5]
	s_barrier
; #define PG8_STAGE(bufoff, gbase, RR, ld) do { _Pragma("unroll") for (int _i = 0; _i < 2; ++_i) \
;         __builtin_amdgcn_global_load_lds((const unsigned*)((const char*)(gbase) + (RR)[_i] * (ld) + C2[_i]), (LAS unsigned*)(lds + (bufoff) + ldsw + _i * 8192), 16, 0, 0); } while (0)
; #define PG8_LDA(dst, b, h) do { _Pragma("unroll") for (int m = 0; m < 4; ++m) _Pragma("unroll") for (int k = 0; k < 2; ++k) dst[m][k] = *(const LAS bf16x8*)(lds + PG8_SA(b, h) + aoff + m * 2048 + k * 1024); } while (0)
; #define PG8_LDB(dst, b, h) do { _Pragma("unroll") for (int n = 0; n < 2; ++n) _Pragma("unroll") for (int k = 0; k < 2; ++k) dst[n][k] = *(const LAS bf16x8*)(lds + PG8_SB(b, h) + boff + n * 2048 + k * 1024); } while (0)
; #define PG8_MMA(ai, bj, At, Bt) do { __builtin_amdgcn_s_setprio(1); _Pragma("unroll") for (int m = 0; m < 4; ++m) _Pragma("unroll") for (int n = 0; n < 2; ++n) _Pragma("unroll") for (int k = 0; k < 2; ++k) \
;         acc[ai][bj][m][n] = __builtin_amdgcn_mfma_f32_16x16x32_bf16(Bt[n][k], At[m][k], acc[ai][bj][m][n], 0, 0, 0); __builtin_amdgcn_s_setprio(0); } while (0)
; #define PG8_WAIT_V(n) asm volatile("s_waitcnt vmcnt(" #n ")" ::: "memory")
; #define PG8_WAIT_L(n) asm volatile("s_waitcnt lgkmcnt(" #n ")" ::: "memory")
; #define PG8_BAR __builtin_amdgcn_s_barrier()
; #define PG8_SCHED __builtin_amdgcn_sched_barrier(0)
; template <class Sched, class Epi>
; __device__ __forceinline__ void gemm_run(LAS unsigned char* lds, const Sched& S, const Epi& E) {
;     ...
;             PG8_LDB(B0, 1, 0); PG8_LDB(B1, 1, 1); PG8_SCHED; PG8_LDA(At, 1, 0); PG8_STAGE(PG8_SA(0, 1), a2 + (size_t)HALF * la2, RA, la2);
;             PG8_WAIT_V(8); PG8_WAIT_L(0); PG8_BAR; PG8_MMA(0, 0, At, B0); PG8_MMA(0, 1, At, B1); PG8_BAR; PG8_SCHED;
;             PG8_LDA(At, 1, 1); PG8_STAGE(PG8_SB(1, 0), b3, RB, lb2); PG8_STAGE(PG8_SB(1, 1), b3 + (size_t)HALF * lb2, RB, lb2); PG8_STAGE(PG8_SA(1, 0), a3, RA, la2);
;             PG8_WAIT_V(8); PG8_WAIT_L(0); PG8_BAR; PG8_MMA(1, 0, At, B0); PG8_MMA(1, 1, At, B1); PG8_BAR; PG8_SCHED;
;         }
	s_add_i32 s39, 0, 0x18000
	s_add_i32 s42, 0, 0x1c000
	ds_read_b128 v[154:157], v182 offset:32768
	ds_read_b128 v[158:161], v182 offset:33792
	ds_read_b128 v[162:165], v182 offset:34816
	ds_read_b128 v[166:169], v182 offset:35840
	ds_read_b128 v[170:173], v183 offset:32768
	ds_read_b128 v[186:189], v183 offset:33792
	ds_read_b128 v[190:193], v183 offset:34816
	ds_read_b128 v[194:197], v183 offset:35840
	s_add_u32 s40, s58, 0x80000
	s_addc_u32 s41, s59, 0
	s_mov_b32 m0, s60
	ds_read_b128 v[198:201], v184 offset:32768
	ds_read_b128 v[202:205], v184 offset:33792
	ds_read_b128 v[206:209], v184 offset:34816
	ds_read_b128 v[210:213], v184 offset:35840
	ds_read_b128 v[214:217], v184 offset:36864
	ds_read_b128 v[218:221], v184 offset:37888
	ds_read_b128 v[222:225], v184 offset:38912
	ds_read_b128 v[226:229], v184 offset:39936
	global_load_lds_dwordx4 v138, s[40:41]
	s_mov_b32 m0, s61
	s_nop 0
	global_load_lds_dwordx4 v140, s[40:41]
	s_waitcnt vmcnt(8)
	s_waitcnt lgkmcnt(0)
	s_barrier
	s_waitcnt lgkmcnt(0)
	v_mfma_f32_16x16x32_bf16 v[126:129], v[154:157], v[198:201], v[126:129]
	v_mfma_f32_16x16x32_bf16 v[122:125], v[162:165], v[198:201], v[122:125]
	v_mfma_f32_16x16x32_bf16 v[110:113], v[154:157], v[206:209], v[110:113]
	v_mfma_f32_16x16x32_bf16 v[106:109], v[162:165], v[206:209], v[106:109]
	v_mfma_f32_16x16x32_bf16 v[94:97], v[154:157], v[214:217], v[94:97]
	v_mfma_f32_16x16x32_bf16 v[90:93], v[162:165], v[214:217], v[90:93]
	v_mfma_f32_16x16x32_bf16 v[78:81], v[154:157], v[222:225], v[78:81]
	v_mfma_f32_16x16x32_bf16 v[74:77], v[162:165], v[222:225], v[74:77]
	v_mfma_f32_16x16x32_bf16 v[126:129], v[158:161], v[202:205], v[126:129]
	v_mfma_f32_16x16x32_bf16 v[122:125], v[166:169], v[202:205], v[122:125]
	v_mfma_f32_16x16x32_bf16 v[110:113], v[158:161], v[210:213], v[110:113]
	v_mfma_f32_16x16x32_bf16 v[106:109], v[166:169], v[210:213], v[106:109]
	v_mfma_f32_16x16x32_bf16 v[94:97], v[158:161], v[218:221], v[94:97]
	v_mfma_f32_16x16x32_bf16 v[90:93], v[166:169], v[218:221], v[90:93]
	v_mfma_f32_16x16x32_bf16 v[78:81], v[158:161], v[226:229], v[78:81]
	v_mfma_f32_16x16x32_bf16 v[74:77], v[166:169], v[226:229], v[74:77]
	v_mfma_f32_16x16x32_bf16 v[118:121], v[170:173], v[198:201], v[118:121]
	v_mfma_f32_16x16x32_bf16 v[114:117], v[190:193], v[198:201], v[114:117]
	v_mfma_f32_16x16x32_bf16 v[102:105], v[170:173], v[206:209], v[102:105]
	v_mfma_f32_16x16x32_bf16 v[98:101], v[190:193], v[206:209], v[98:101]
	v_mfma_f32_16x16x32_bf16 v[86:89], v[170:173], v[214:217], v[86:89]
	v_mfma_f32_16x16x32_bf16 v[82:85], v[190:193], v[214:217], v[82:85]
	v_mfma_f32_16x16x32_bf16 v[70:73], v[170:173], v[222:225], v[70:73]
	v_mfma_f32_16x16x32_bf16 v[66:69], v[190:193], v[222:225], v[66:69]
	v_mfma_f32_16x16x32_bf16 v[118:121], v[186:189], v[202:205], v[118:121]
	v_mfma_f32_16x16x32_bf16 v[114:117], v[194:197], v[202:205], v[114:117]
	v_mfma_f32_16x16x32_bf16 v[102:105], v[186:189], v[210:213], v[102:105]
	v_mfma_f32_16x16x32_bf16 v[98:101], v[194:197], v[210:213], v[98:101]
	v_mfma_f32_16x16x32_bf16 v[86:89], v[186:189], v[218:221], v[86:89]
	v_mfma_f32_16x16x32_bf16 v[82:85], v[194:197], v[218:221], v[82:85]
	v_mfma_f32_16x16x32_bf16 v[70:73], v[186:189], v[226:229], v[70:73]
	v_mfma_f32_16x16x32_bf16 v[66:69], v[194:197], v[226:229], v[66:69]
	s_barrier
	s_add_i32 s39, s39, s3
	s_mov_b32 m0, s39
	ds_read_b128 v[198:201], v184 offset:49152
	ds_read_b128 v[202:205], v184 offset:50176
	ds_read_b128 v[206:209], v184 offset:51200
	ds_read_b128 v[210:213], v184 offset:52224
	ds_read_b128 v[214:217], v184 offset:53248
	ds_read_b128 v[218:221], v184 offset:54272
	ds_read_b128 v[222:225], v184 offset:55296
	ds_read_b128 v[226:229], v184 offset:56320
	s_add_u32 s98, s56, 0x80
	s_addc_u32 s99, s57, 0
	global_load_lds_dwordx4 v132, s[98:99]
	s_add_i32 m0, s39, 0x2000
	s_add_u32 s40, s56, 0x80080
	s_addc_u32 s41, s57, 0
	global_load_lds_dwordx4 v136, s[98:99]
	s_add_i32 s39, s42, s3
	s_mov_b32 m0, s39
	s_nop 0
	global_load_lds_dwordx4 v132, s[40:41]
	s_add_i32 m0, s39, 0x2000
	s_nop 0
	global_load_lds_dwordx4 v136, s[40:41]
	s_mov_b32 m0, s64
	s_nop 0
	s_add_u32 s100, s58, 0x80
	s_addc_u32 s101, s59, 0
	global_load_lds_dwordx4 v138, s[100:101]
	s_mov_b32 m0, s65
	s_nop 0
	global_load_lds_dwordx4 v140, s[100:101]
	s_waitcnt vmcnt(8)
	s_waitcnt lgkmcnt(0)
	s_barrier
	s_waitcnt lgkmcnt(0)
	v_mfma_f32_16x16x32_bf16 v[62:65], v[154:157], v[198:201], v[62:65]
	v_mfma_f32_16x16x32_bf16 v[58:61], v[162:165], v[198:201], v[58:61]
	v_mfma_f32_16x16x32_bf16 v[46:49], v[154:157], v[206:209], v[46:49]
	v_mfma_f32_16x16x32_bf16 v[42:45], v[162:165], v[206:209], v[42:45]
	v_mfma_f32_16x16x32_bf16 v[30:33], v[154:157], v[214:217], v[30:33]
	v_mfma_f32_16x16x32_bf16 v[26:29], v[162:165], v[214:217], v[26:29]
	v_mfma_f32_16x16x32_bf16 v[14:17], v[154:157], v[222:225], v[14:17]
	v_mfma_f32_16x16x32_bf16 v[10:13], v[162:165], v[222:225], v[10:13]
	v_mfma_f32_16x16x32_bf16 v[62:65], v[158:161], v[202:205], v[62:65]
	v_mfma_f32_16x16x32_bf16 v[58:61], v[166:169], v[202:205], v[58:61]
	v_mfma_f32_16x16x32_bf16 v[46:49], v[158:161], v[210:213], v[46:49]
	v_mfma_f32_16x16x32_bf16 v[42:45], v[166:169], v[210:213], v[42:45]
	v_mfma_f32_16x16x32_bf16 v[30:33], v[158:161], v[218:221], v[30:33]
	v_mfma_f32_16x16x32_bf16 v[26:29], v[166:169], v[218:221], v[26:29]
	v_mfma_f32_16x16x32_bf16 v[14:17], v[158:161], v[226:229], v[14:17]
	v_mfma_f32_16x16x32_bf16 v[10:13], v[166:169], v[226:229], v[10:13]
	v_mfma_f32_16x16x32_bf16 v[54:57], v[170:173], v[198:201], v[54:57]
	v_mfma_f32_16x16x32_bf16 v[50:53], v[190:193], v[198:201], v[50:53]
	v_mfma_f32_16x16x32_bf16 v[38:41], v[170:173], v[206:209], v[38:41]
	v_mfma_f32_16x16x32_bf16 v[34:37], v[190:193], v[206:209], v[34:37]
	v_mfma_f32_16x16x32_bf16 v[22:25], v[170:173], v[214:217], v[22:25]
	v_mfma_f32_16x16x32_bf16 v[18:21], v[190:193], v[214:217], v[18:21]
	v_mfma_f32_16x16x32_bf16 v[6:9], v[170:173], v[222:225], v[6:9]
	v_mfma_f32_16x16x32_bf16 v[2:5], v[190:193], v[222:225], v[2:5]
	v_mfma_f32_16x16x32_bf16 v[54:57], v[186:189], v[202:205], v[54:57]
	v_mfma_f32_16x16x32_bf16 v[50:53], v[194:197], v[202:205], v[50:53]
	v_mfma_f32_16x16x32_bf16 v[38:41], v[186:189], v[210:213], v[38:41]
	v_mfma_f32_16x16x32_bf16 v[34:37], v[194:197], v[210:213], v[34:37]
	v_mfma_f32_16x16x32_bf16 v[22:25], v[186:189], v[218:221], v[22:25]
	v_mfma_f32_16x16x32_bf16 v[18:21], v[194:197], v[218:221], v[18:21]
	v_mfma_f32_16x16x32_bf16 v[6:9], v[186:189], v[226:229], v[6:9]
	v_mfma_f32_16x16x32_bf16 v[2:5], v[194:197], v[226:229], v[2:5]
	s_barrier
	s_add_i32 s38, s38, 2
	s_add_u32 s54, s54, 0x100
	s_addc_u32 s55, s55, 0
	s_cmp_gt_u32 s38, 29
	s_cbranch_scc0 .LBB0_246
	.p2align 6
; #define PG8_STAGE(bufoff, gbase, RR, ld) do { _Pragma("unroll") for (int _i = 0; _i < 2; ++_i) \
;         __builtin_amdgcn_global_load_lds((const unsigned*)((const char*)(gbase) + (RR)[_i] * (ld) + C2[_i]), (LAS unsigned*)(lds + (bufoff) + ldsw + _i * 8192), 16, 0, 0); } while (0)
; #define PG8_LDA(dst, b, h) do { _Pragma("unroll") for (int m = 0; m < 4; ++m) _Pragma("unroll") for (int k = 0; k < 2; ++k) dst[m][k] = *(const LAS bf16x8*)(lds + PG8_SA(b, h) + aoff + m * 2048 + k * 1024); } while (0)
; #define PG8_LDB(dst, b, h) do { _Pragma("unroll") for (int n = 0; n < 2; ++n) _Pragma("unroll") for (int k = 0; k < 2; ++k) dst[n][k] = *(const LAS bf16x8*)(lds + PG8_SB(b, h) + boff + n * 2048 + k * 1024); } while (0)
; #define PG8_MMA(ai, bj, At, Bt) do { __builtin_amdgcn_s_setprio(1); _Pragma("unroll") for (int m = 0; m < 4; ++m) _Pragma("unroll") for (int n = 0; n < 2; ++n) _Pragma("unroll") for (int k = 0; k < 2; ++k) \
;         acc[ai][bj][m][n] = __builtin_amdgcn_mfma_f32_16x16x32_bf16(Bt[n][k], At[m][k], acc[ai][bj][m][n], 0, 0, 0); __builtin_amdgcn_s_setprio(0); } while (0)
; #define PG8_WAIT_V(n) asm volatile("s_waitcnt vmcnt(" #n ")" ::: "memory")
; #define PG8_WAIT_L(n) asm volatile("s_waitcnt lgkmcnt(" #n ")" ::: "memory")
; #define PG8_BAR __builtin_amdgcn_s_barrier()
; #define PG8_SCHED __builtin_amdgcn_sched_barrier(0)
; template <class Sched, class Epi>
; __device__ __forceinline__ void gemm_run(LAS unsigned char* lds, const Sched& S, const Epi& E) {
;     ...
;             PG8_LDB(B0, 0, 0); PG8_LDB(B1, 0, 1); PG8_SCHED; PG8_LDA(At, 0, 0); PG8_STAGE(PG8_SA(1, 1), a1 + (size_t)HALF * lda, RA, lda);
;             PG8_WAIT_V(8); PG8_WAIT_L(0); PG8_BAR; PG8_MMA(0, 0, At, B0); PG8_MMA(0, 1, At, B1); PG8_BAR; PG8_SCHED;
;             PG8_LDA(At, 0, 1); PG8_STAGE(PG8_SB(0, 0), b2, RB, lb2); PG8_STAGE(PG8_SB(0, 1), b2 + (size_t)HALF * lb2, RB, lb2); PG8_STAGE(PG8_SA(0, 0), a2, RA, la2);
;             PG8_WAIT_V(8); PG8_WAIT_L(0); PG8_BAR; PG8_MMA(1, 0, At, B0); PG8_MMA(1, 1, At, B1); PG8_BAR; PG8_SCHED;
.LBB0_246:
	ds_read_b128 v[154:157], v182
	ds_read_b128 v[158:161], v182 offset:1024
	ds_read_b128 v[162:165], v182 offset:2048
	ds_read_b128 v[166:169], v182 offset:3072
	ds_read_b128 v[170:173], v183
	ds_read_b128 v[186:189], v183 offset:1024
	ds_read_b128 v[190:193], v183 offset:2048
	ds_read_b128 v[194:197], v183 offset:3072
	s_add_u32 s39, s6, s54
	s_addc_u32 s40, s7, s55
	s_mov_b32 s98, s39
	s_mov_b32 s99, s40
	s_add_u32 s39, s39, 0x100
	s_addc_u32 s40, s40, 0
	s_add_u32 s41, s12, s54
	s_addc_u32 s42, s33, s55
	s_cmpk_eq_i32 s54, 0xf00
	s_cselect_b32 s59, s29, s40
	s_cselect_b32 s58, s28, s39
	s_cselect_b32 s57, s37, s42
	s_cselect_b32 s56, s36, s41
	s_add_i32 m0, s21, 0xc000
	ds_read_b128 v[198:201], v184
	ds_read_b128 v[202:205], v184 offset:1024
	ds_read_b128 v[206:209], v184 offset:2048
	ds_read_b128 v[210:213], v184 offset:3072
	ds_read_b128 v[214:217], v184 offset:4096
	ds_read_b128 v[218:221], v184 offset:5120
	ds_read_b128 v[222:225], v184 offset:6144
	ds_read_b128 v[226:229], v184 offset:7168
	global_load_lds_dwordx4 v146, s[98:99]
	s_add_i32 m0, s21, 0xe000
	s_nop 0
	global_load_lds_dwordx4 v148, s[98:99]
	s_waitcnt vmcnt(8)
	s_waitcnt lgkmcnt(0)
	s_barrier
	s_waitcnt lgkmcnt(0)
	v_mfma_f32_16x16x32_bf16 v[126:129], v[154:157], v[198:201], v[126:129]
	v_mfma_f32_16x16x32_bf16 v[122:125], v[162:165], v[198:201], v[122:125]
	v_mfma_f32_16x16x32_bf16 v[110:113], v[154:157], v[206:209], v[110:113]
	v_mfma_f32_16x16x32_bf16 v[106:109], v[162:165], v[206:209], v[106:109]
	v_mfma_f32_16x16x32_bf16 v[94:97], v[154:157], v[214:217], v[94:97]
	v_mfma_f32_16x16x32_bf16 v[90:93], v[162:165], v[214:217], v[90:93]
	v_mfma_f32_16x16x32_bf16 v[78:81], v[154:157], v[222:225], v[78:81]
	v_mfma_f32_16x16x32_bf16 v[74:77], v[162:165], v[222:225], v[74:77]
	v_mfma_f32_16x16x32_bf16 v[126:129], v[158:161], v[202:205], v[126:129]
	v_mfma_f32_16x16x32_bf16 v[122:125], v[166:169], v[202:205], v[122:125]
	v_mfma_f32_16x16x32_bf16 v[110:113], v[158:161], v[210:213], v[110:113]
	v_mfma_f32_16x16x32_bf16 v[106:109], v[166:169], v[210:213], v[106:109]
	v_mfma_f32_16x16x32_bf16 v[94:97], v[158:161], v[218:221], v[94:97]
	v_mfma_f32_16x16x32_bf16 v[90:93], v[166:169], v[218:221], v[90:93]
	v_mfma_f32_16x16x32_bf16 v[78:81], v[158:161], v[226:229], v[78:81]
	v_mfma_f32_16x16x32_bf16 v[74:77], v[166:169], v[226:229], v[74:77]
	v_mfma_f32_16x16x32_bf16 v[118:121], v[170:173], v[198:201], v[118:121]
	v_mfma_f32_16x16x32_bf16 v[114:117], v[190:193], v[198:201], v[114:117]
	v_mfma_f32_16x16x32_bf16 v[102:105], v[170:173], v[206:209], v[102:105]
	v_mfma_f32_16x16x32_bf16 v[98:101], v[190:193], v[206:209], v[98:101]
	v_mfma_f32_16x16x32_bf16 v[86:89], v[170:173], v[214:217], v[86:89]
	v_mfma_f32_16x16x32_bf16 v[82:85], v[190:193], v[214:217], v[82:85]
	v_mfma_f32_16x16x32_bf16 v[70:73], v[170:173], v[222:225], v[70:73]
	v_mfma_f32_16x16x32_bf16 v[66:69], v[190:193], v[222:225], v[66:69]
	v_mfma_f32_16x16x32_bf16 v[118:121], v[186:189], v[202:205], v[118:121]
	v_mfma_f32_16x16x32_bf16 v[114:117], v[194:197], v[202:205], v[114:117]
	v_mfma_f32_16x16x32_bf16 v[102:105], v[186:189], v[210:213], v[102:105]
	v_mfma_f32_16x16x32_bf16 v[98:101], v[194:197], v[210:213], v[98:101]
	v_mfma_f32_16x16x32_bf16 v[86:89], v[186:189], v[218:221], v[86:89]
	v_mfma_f32_16x16x32_bf16 v[82:85], v[194:197], v[218:221], v[82:85]
	v_mfma_f32_16x16x32_bf16 v[70:73], v[186:189], v[226:229], v[70:73]
	v_mfma_f32_16x16x32_bf16 v[66:69], v[194:197], v[226:229], v[66:69]
	s_barrier
	s_add_i32 s39, s71, s3
	s_mov_b32 m0, s39
	ds_read_b128 v[198:201], v184 offset:16384
	ds_read_b128 v[202:205], v184 offset:17408
	ds_read_b128 v[206:209], v184 offset:18432
	ds_read_b128 v[210:213], v184 offset:19456
	ds_read_b128 v[214:217], v184 offset:20480
	ds_read_b128 v[218:221], v184 offset:21504
	ds_read_b128 v[222:225], v184 offset:22528
	ds_read_b128 v[226:229], v184 offset:23552
	global_load_lds_dwordx4 v132, s[56:57]
	s_add_i32 m0, s39, 0x2000
	s_add_u32 s40, s56, 0x80000
	s_addc_u32 s41, s57, 0
	s_add_i32 s39, s72, s3
	global_load_lds_dwordx4 v136, s[56:57]
	s_mov_b32 m0, s39
	s_nop 0
	global_load_lds_dwordx4 v132, s[40:41]
	s_add_i32 m0, s39, 0x2000
	s_nop 0
	global_load_lds_dwordx4 v136, s[40:41]
	s_mov_b32 m0, s21
	s_nop 0
	global_load_lds_dwordx4 v138, s[58:59]
	s_mov_b32 m0, s35
	s_nop 0
	global_load_lds_dwordx4 v140, s[58:59]
	s_waitcnt vmcnt(8)
	s_waitcnt lgkmcnt(0)
	s_barrier
	s_waitcnt lgkmcnt(0)
	v_mfma_f32_16x16x32_bf16 v[62:65], v[154:157], v[198:201], v[62:65]
	v_mfma_f32_16x16x32_bf16 v[58:61], v[162:165], v[198:201], v[58:61]
	v_mfma_f32_16x16x32_bf16 v[46:49], v[154:157], v[206:209], v[46:49]
	v_mfma_f32_16x16x32_bf16 v[42:45], v[162:165], v[206:209], v[42:45]
	v_mfma_f32_16x16x32_bf16 v[30:33], v[154:157], v[214:217], v[30:33]
	v_mfma_f32_16x16x32_bf16 v[26:29], v[162:165], v[214:217], v[26:29]
	v_mfma_f32_16x16x32_bf16 v[14:17], v[154:157], v[222:225], v[14:17]
	v_mfma_f32_16x16x32_bf16 v[10:13], v[162:165], v[222:225], v[10:13]
	v_mfma_f32_16x16x32_bf16 v[62:65], v[158:161], v[202:205], v[62:65]
	v_mfma_f32_16x16x32_bf16 v[58:61], v[166:169], v[202:205], v[58:61]
	v_mfma_f32_16x16x32_bf16 v[46:49], v[158:161], v[210:213], v[46:49]
	v_mfma_f32_16x16x32_bf16 v[42:45], v[166:169], v[210:213], v[42:45]
	v_mfma_f32_16x16x32_bf16 v[30:33], v[158:161], v[218:221], v[30:33]
	v_mfma_f32_16x16x32_bf16 v[26:29], v[166:169], v[218:221], v[26:29]
	v_mfma_f32_16x16x32_bf16 v[14:17], v[158:161], v[226:229], v[14:17]
	v_mfma_f32_16x16x32_bf16 v[10:13], v[166:169], v[226:229], v[10:13]
	v_mfma_f32_16x16x32_bf16 v[54:57], v[170:173], v[198:201], v[54:57]
	v_mfma_f32_16x16x32_bf16 v[50:53], v[190:193], v[198:201], v[50:53]
	v_mfma_f32_16x16x32_bf16 v[38:41], v[170:173], v[206:209], v[38:41]
	v_mfma_f32_16x16x32_bf16 v[34:37], v[190:193], v[206:209], v[34:37]
	v_mfma_f32_16x16x32_bf16 v[22:25], v[170:173], v[214:217], v[22:25]
	v_mfma_f32_16x16x32_bf16 v[18:21], v[190:193], v[214:217], v[18:21]
	v_mfma_f32_16x16x32_bf16 v[6:9], v[170:173], v[222:225], v[6:9]
	v_mfma_f32_16x16x32_bf16 v[2:5], v[190:193], v[222:225], v[2:5]
	v_mfma_f32_16x16x32_bf16 v[54:57], v[186:189], v[202:205], v[54:57]
	v_mfma_f32_16x16x32_bf16 v[50:53], v[194:197], v[202:205], v[50:53]
	v_mfma_f32_16x16x32_bf16 v[38:41], v[186:189], v[210:213], v[38:41]
	v_mfma_f32_16x16x32_bf16 v[34:37], v[194:197], v[210:213], v[34:37]
	v_mfma_f32_16x16x32_bf16 v[22:25], v[186:189], v[218:221], v[22:25]
	v_mfma_f32_16x16x32_bf16 v[18:21], v[194:197], v[218:221], v[18:21]
	v_mfma_f32_16x16x32_bf16 v[6:9], v[186:189], v[226:229], v[6:9]
	v_mfma_f32_16x16x32_bf16 v[2:5], v[194:197], v[226:229], v[2:5]
	s_barrier
; #define PG8_STAGE(bufoff, gbase, RR, ld) do { _Pragma("unroll") for (int _i = 0; _i < 2; ++_i) \
;         __builtin_amdgcn_global_load_lds((const unsigned*)((const char*)(gbase) + (RR)[_i] * (ld) + C2[_i]), (LAS unsigned*)(lds + (bufoff) + ldsw + _i * 8192), 16, 0, 0); } while (0)
; #define PG8_LDA(dst, b, h) do { _Pragma("unroll") for (int m = 0; m < 4; ++m) _Pragma("unroll") for (int k = 0; k < 2; ++k) dst[m][k] = *(const LAS bf16x8*)(lds + PG8_SA(b, h) + aoff + m * 2048 + k * 1024); } while (0)
; #define PG8_LDB(dst, b, h) do { _Pragma("unroll") for (int n = 0; n < 2; ++n) _Pragma("unroll") for (int k = 0; k < 2; ++k) dst[n][k] = *(const LAS bf16x8*)(lds + PG8_SB(b, h) + boff + n * 2048 + k * 1024); } while (0)
; #define PG8_MMA(ai, bj, At, Bt) do { __builtin_amdgcn_s_setprio(1); _Pragma("unroll") for (int m = 0; m < 4; ++m) _Pragma("unroll") for (int n = 0; n < 2; ++n) _Pragma("unroll") for (int k = 0; k < 2; ++k) \
;         acc[ai][bj][m][n] = __builtin_amdgcn_mfma_f32_16x16x32_bf16(Bt[n][k], At[m][k], acc[ai][bj][m][n], 0, 0, 0); __builtin_amdgcn_s_setprio(0); } while (0)
; #define PG8_WAIT_V(n) asm volatile("s_waitcnt vmcnt(" #n ")" ::: "memory")
; #define PG8_WAIT_L(n) asm volatile("s_waitcnt lgkmcnt(" #n ")" ::: "memory")
; #define PG8_BAR __builtin_amdgcn_s_barrier()
; #define PG8_SCHED __builtin_amdgcn_sched_barrier(0)
; template <class Sched, class Epi>
; __device__ __forceinline__ void gemm_run(LAS unsigned char* lds, const Sched& S, const Epi& E) {
;     ...
;             PG8_LDB(B0, 1, 0); PG8_LDB(B1, 1, 1); PG8_SCHED; PG8_LDA(At, 1, 0); PG8_STAGE(PG8_SA(0, 1), a2 + (size_t)HALF * la2, RA, la2);
;             PG8_WAIT_V(8); PG8_WAIT_L(0); PG8_BAR; PG8_MMA(0, 0, At, B0); PG8_MMA(0, 1, At, B1); PG8_BAR; PG8_SCHED;
;             PG8_LDA(At, 1, 1); PG8_STAGE(PG8_SB(1, 0), b3, RB, lb2); PG8_STAGE(PG8_SB(1, 1), b3 + (size_t)HALF * lb2, RB, lb2); PG8_STAGE(PG8_SA(1, 0), a3, RA, la2);
;             PG8_WAIT_V(8); PG8_WAIT_L(0); PG8_BAR; PG8_MMA(1, 0, At, B0); PG8_MMA(1, 1, At, B1); PG8_BAR; PG8_SCHED;
;         }
;         if (wr == 0) PG8_BAR;
	s_add_i32 s39, 0, 0x18000
	s_add_i32 s42, 0, 0x1c000
	ds_read_b128 v[154:157], v182 offset:32768
	ds_read_b128 v[158:161], v182 offset:33792
	ds_read_b128 v[162:165], v182 offset:34816
	ds_read_b128 v[166:169], v182 offset:35840
	ds_read_b128 v[170:173], v183 offset:32768
	ds_read_b128 v[186:189], v183 offset:33792
	ds_read_b128 v[190:193], v183 offset:34816
	ds_read_b128 v[194:197], v183 offset:35840
	s_add_u32 s40, s58, 0x80000
	s_addc_u32 s41, s59, 0
	s_mov_b32 m0, s60
	ds_read_b128 v[198:201], v184 offset:32768
	ds_read_b128 v[202:205], v184 offset:33792
	ds_read_b128 v[206:209], v184 offset:34816
	ds_read_b128 v[210:213], v184 offset:35840
	ds_read_b128 v[214:217], v184 offset:36864
	ds_read_b128 v[218:221], v184 offset:37888
	ds_read_b128 v[222:225], v184 offset:38912
	ds_read_b128 v[226:229], v184 offset:39936
	global_load_lds_dwordx4 v138, s[40:41]
	s_mov_b32 m0, s61
	s_nop 0
	global_load_lds_dwordx4 v140, s[40:41]
	s_waitcnt vmcnt(8)
	s_waitcnt lgkmcnt(0)
	s_barrier
	s_waitcnt lgkmcnt(0)
	v_mfma_f32_16x16x32_bf16 v[126:129], v[154:157], v[198:201], v[126:129]
	v_mfma_f32_16x16x32_bf16 v[122:125], v[162:165], v[198:201], v[122:125]
	v_mfma_f32_16x16x32_bf16 v[110:113], v[154:157], v[206:209], v[110:113]
	v_mfma_f32_16x16x32_bf16 v[106:109], v[162:165], v[206:209], v[106:109]
	v_mfma_f32_16x16x32_bf16 v[94:97], v[154:157], v[214:217], v[94:97]
	v_mfma_f32_16x16x32_bf16 v[90:93], v[162:165], v[214:217], v[90:93]
	v_mfma_f32_16x16x32_bf16 v[78:81], v[154:157], v[222:225], v[78:81]
	v_mfma_f32_16x16x32_bf16 v[74:77], v[162:165], v[222:225], v[74:77]
	v_mfma_f32_16x16x32_bf16 v[126:129], v[158:161], v[202:205], v[126:129]
	v_mfma_f32_16x16x32_bf16 v[122:125], v[166:169], v[202:205], v[122:125]
	v_mfma_f32_16x16x32_bf16 v[110:113], v[158:161], v[210:213], v[110:113]
	v_mfma_f32_16x16x32_bf16 v[106:109], v[166:169], v[210:213], v[106:109]
	v_mfma_f32_16x16x32_bf16 v[94:97], v[158:161], v[218:221], v[94:97]
	v_mfma_f32_16x16x32_bf16 v[90:93], v[166:169], v[218:221], v[90:93]
	v_mfma_f32_16x16x32_bf16 v[78:81], v[158:161], v[226:229], v[78:81]
	v_mfma_f32_16x16x32_bf16 v[74:77], v[166:169], v[226:229], v[74:77]
	v_mfma_f32_16x16x32_bf16 v[118:121], v[170:173], v[198:201], v[118:121]
	v_mfma_f32_16x16x32_bf16 v[114:117], v[190:193], v[198:201], v[114:117]
	v_mfma_f32_16x16x32_bf16 v[102:105], v[170:173], v[206:209], v[102:105]
	v_mfma_f32_16x16x32_bf16 v[98:101], v[190:193], v[206:209], v[98:101]
	v_mfma_f32_16x16x32_bf16 v[86:89], v[170:173], v[214:217], v[86:89]
	v_mfma_f32_16x16x32_bf16 v[82:85], v[190:193], v[214:217], v[82:85]
	v_mfma_f32_16x16x32_bf16 v[70:73], v[170:173], v[222:225], v[70:73]
	v_mfma_f32_16x16x32_bf16 v[66:69], v[190:193], v[222:225], v[66:69]
	v_mfma_f32_16x16x32_bf16 v[118:121], v[186:189], v[202:205], v[118:121]
	v_mfma_f32_16x16x32_bf16 v[114:117], v[194:197], v[202:205], v[114:117]
	v_mfma_f32_16x16x32_bf16 v[102:105], v[186:189], v[210:213], v[102:105]
	v_mfma_f32_16x16x32_bf16 v[98:101], v[194:197], v[210:213], v[98:101]
	v_mfma_f32_16x16x32_bf16 v[86:89], v[186:189], v[218:221], v[86:89]
	v_mfma_f32_16x16x32_bf16 v[82:85], v[194:197], v[218:221], v[82:85]
	v_mfma_f32_16x16x32_bf16 v[70:73], v[186:189], v[226:229], v[70:73]
	v_mfma_f32_16x16x32_bf16 v[66:69], v[194:197], v[226:229], v[66:69]
	s_barrier
	s_add_i32 s39, s39, s3
	s_mov_b32 m0, s39
	ds_read_b128 v[198:201], v184 offset:49152
	ds_read_b128 v[202:205], v184 offset:50176
	ds_read_b128 v[206:209], v184 offset:51200
	ds_read_b128 v[210:213], v184 offset:52224
	ds_read_b128 v[214:217], v184 offset:53248
	ds_read_b128 v[218:221], v184 offset:54272
	ds_read_b128 v[222:225], v184 offset:55296
	ds_read_b128 v[226:229], v184 offset:56320
	s_add_u32 s98, s56, 0x80
	s_addc_u32 s99, s57, 0
	global_load_lds_dwordx4 v132, s[98:99]
	s_add_i32 m0, s39, 0x2000
	s_add_u32 s40, s56, 0x80080
	s_addc_u32 s41, s57, 0
	global_load_lds_dwordx4 v136, s[98:99]
	s_add_i32 s39, s42, s3
	s_mov_b32 m0, s39
	s_nop 0
	global_load_lds_dwordx4 v132, s[40:41]
	s_add_i32 m0, s39, 0x2000
	s_nop 0
	global_load_lds_dwordx4 v136, s[40:41]
	s_mov_b32 m0, s64
	s_nop 0
	s_add_u32 s100, s58, 0x80
	s_addc_u32 s101, s59, 0
	global_load_lds_dwordx4 v138, s[100:101]
	s_mov_b32 m0, s65
	s_nop 0
	global_load_lds_dwordx4 v140, s[100:101]
	s_waitcnt vmcnt(8)
	s_waitcnt lgkmcnt(0)
	s_barrier
	s_waitcnt lgkmcnt(0)
	v_mfma_f32_16x16x32_bf16 v[62:65], v[154:157], v[198:201], v[62:65]
	v_mfma_f32_16x16x32_bf16 v[58:61], v[162:165], v[198:201], v[58:61]
	v_mfma_f32_16x16x32_bf16 v[46:49], v[154:157], v[206:209], v[46:49]
	v_mfma_f32_16x16x32_bf16 v[42:45], v[162:165], v[206:209], v[42:45]
	v_mfma_f32_16x16x32_bf16 v[30:33], v[154:157], v[214:217], v[30:33]
	v_mfma_f32_16x16x32_bf16 v[26:29], v[162:165], v[214:217], v[26:29]
	v_mfma_f32_16x16x32_bf16 v[14:17], v[154:157], v[222:225], v[14:17]
	v_mfma_f32_16x16x32_bf16 v[10:13], v[162:165], v[222:225], v[10:13]
	v_mfma_f32_16x16x32_bf16 v[62:65], v[158:161], v[202:205], v[62:65]
	v_mfma_f32_16x16x32_bf16 v[58:61], v[166:169], v[202:205], v[58:61]
	v_mfma_f32_16x16x32_bf16 v[46:49], v[158:161], v[210:213], v[46:49]
	v_mfma_f32_16x16x32_bf16 v[42:45], v[166:169], v[210:213], v[42:45]
	v_mfma_f32_16x16x32_bf16 v[30:33], v[158:161], v[218:221], v[30:33]
	v_mfma_f32_16x16x32_bf16 v[26:29], v[166:169], v[218:221], v[26:29]
	v_mfma_f32_16x16x32_bf16 v[14:17], v[158:161], v[226:229], v[14:17]
	v_mfma_f32_16x16x32_bf16 v[10:13], v[166:169], v[226:229], v[10:13]
	v_mfma_f32_16x16x32_bf16 v[54:57], v[170:173], v[198:201], v[54:57]
	v_mfma_f32_16x16x32_bf16 v[50:53], v[190:193], v[198:201], v[50:53]
	v_mfma_f32_16x16x32_bf16 v[38:41], v[170:173], v[206:209], v[38:41]
	v_mfma_f32_16x16x32_bf16 v[34:37], v[190:193], v[206:209], v[34:37]
	v_mfma_f32_16x16x32_bf16 v[22:25], v[170:173], v[214:217], v[22:25]
	v_mfma_f32_16x16x32_bf16 v[18:21], v[190:193], v[214:217], v[18:21]
	v_mfma_f32_16x16x32_bf16 v[6:9], v[170:173], v[222:225], v[6:9]
	v_mfma_f32_16x16x32_bf16 v[2:5], v[190:193], v[222:225], v[2:5]
	v_mfma_f32_16x16x32_bf16 v[54:57], v[186:189], v[202:205], v[54:57]
	v_mfma_f32_16x16x32_bf16 v[50:53], v[194:197], v[202:205], v[50:53]
	v_mfma_f32_16x16x32_bf16 v[38:41], v[186:189], v[210:213], v[38:41]
	v_mfma_f32_16x16x32_bf16 v[34:37], v[194:197], v[210:213], v[34:37]
	v_mfma_f32_16x16x32_bf16 v[22:25], v[186:189], v[218:221], v[22:25]
	v_mfma_f32_16x16x32_bf16 v[18:21], v[194:197], v[218:221], v[18:21]
	v_mfma_f32_16x16x32_bf16 v[6:9], v[186:189], v[226:229], v[6:9]
	v_mfma_f32_16x16x32_bf16 v[2:5], v[194:197], v[226:229], v[2:5]
	s_barrier
	s_add_i32 s38, s38, 2
	s_add_u32 s54, s54, 0x100
	s_addc_u32 s55, s55, 0
	s_cmp_gt_u32 s38, 29
	s_cbranch_scc0 .LBB0_246
	s_and_b64 vcc, exec, s[16:17]
	s_cbranch_vccz .LBB0_249
	s_barrier

; #define PG8_STAGE(bufoff, gbase, RR, ld) do { _Pragma("unroll") for (int _i = 0; _i < 2; ++_i) \
;         __builtin_amdgcn_global_load_lds((const unsigned*)((const char*)(gbase) + (RR)[_i] * (ld) + C2[_i]), (LAS unsigned*)(lds + (bufoff) + ldsw + _i * 8192), 16, 0, 0); } while (0)
; #define PG8_LDA(dst, b, h) do { _Pragma("unroll") for (int m = 0; m < 4; ++m) _Pragma("unroll") for (int k = 0; k < 2; ++k) dst[m][k] = *(const LAS bf16x8*)(lds + PG8_SA(b, h) + aoff + m * 2048 + k * 1024); } while (0)
; #define PG8_LDB(dst, b, h) do { _Pragma("unroll") for (int n = 0; n < 2; ++n) _Pragma("unroll") for (int k = 0; k < 2; ++k) dst[n][k] = *(const LAS bf16x8*)(lds + PG8_SB(b, h) + boff + n * 2048 + k * 1024); } while (0)
; #define PG8_WAIT_V(n) asm volatile("s_waitcnt vmcnt(" #n ")" ::: "memory")
; #define PG8_WAIT_L(n) asm volatile("s_waitcnt lgkmcnt(" #n ")" ::: "memory")
; #define PG8_BAR __builtin_amdgcn_s_barrier()
; #define PG8_SCHED __builtin_amdgcn_sched_barrier(0)
; template <class Sched, class Epi>
; __device__ __forceinline__ void gemm_run(LAS unsigned char* lds, const Sched& S, const Epi& E) {
;     ...
;         const bool has_next = S.next(ui + 1, nxt);
;         const char* nA = has_next ? nxt.A : cA; const char* nB = has_next ? nxt.B : cB; const unsigned nlda = has_next ? nxt.lda : lda, nldb = has_next ? nxt.ldb : ldb;
;         const int nt = cur.nt;
;         for (int t = 0; t < nt; t += 2) {
;             const bool last = (t == nt - 2);
;             const char* a1 = cA + (size_t)(t + 1) * kstep;
;             const char* a2 = last ? nA : cA + (size_t)(t + 2) * kstep; const char* b2 = last ? nB : cB + (size_t)(t + 2) * kstep;
;             const unsigned la2 = last ? nlda : lda, lb2 = last ? nldb : ldb;
;             const char* a3 = a2 + kstep; const char* b3 = b2 + kstep;
;             PG8_LDB(B0, 0, 0); PG8_LDB(B1, 0, 1); PG8_SCHED; PG8_LDA(At, 0, 0); PG8_STAGE(PG8_SA(1, 1), a1 + (size_t)HALF * lda, RA, lda);
;             PG8_WAIT_V(8); PG8_WAIT_L(0); PG8_BAR; PG8_MMA(0, 0, At, B0); PG8_MMA(0, 1, At, B1); PG8_BAR; PG8_SCHED;
;             PG8_LDA(At, 0, 1); PG8_STAGE(PG8_SB(0, 0), b2, RB, lb2); PG8_STAGE(PG8_SB(0, 1), b2 + (size_t)HALF * lb2, RB, lb2); PG8_STAGE(PG8_SA(0, 0), a2, RA, la2);
;             PG8_WAIT_V(8); PG8_WAIT_L(0); PG8_BAR; PG8_MMA(1, 0, At, B0); PG8_MMA(1, 1, At, B1); PG8_BAR; PG8_SCHED;
.LBB0_439:
	s_and_b64 s[38:39], s[36:37], exec
	s_mov_b32 s63, s1
	s_cselect_b32 s55, s29, s59
	s_cselect_b32 s61, s28, s58
	s_cselect_b32 vcc_lo, s31, s65
	s_cselect_b32 vcc_hi, s30, s64
	s_lshl_b64 s[42:43], s[62:63], 7
	v_mad_u32_u24 v240, v177, s62, v160
	v_mad_u32_u24 v242, v178, s62, v160
	v_add_u32_e32 v240, s42, v240
	v_add_u32_e32 v242, s42, v242
	v_mul_lo_u32 v148, v177, s62
	v_lshl_add_u64 v[2:3], s[58:59], 0, v[160:161]
	v_lshl_add_u64 v[4:5], s[42:43], 0, v[148:149]
	v_mul_lo_u32 v148, v178, s62
	s_add_i32 s38, s5, -2
	v_lshl_add_u64 v[130:131], v[2:3], 0, v[4:5]
	v_lshl_add_u64 v[4:5], s[42:43], 0, v[148:149]
	s_add_u32 s39, s64, 0x100
	v_lshl_add_u64 v[132:133], v[2:3], 0, v[4:5]
	s_addc_u32 s40, s65, 0
	s_mov_b64 s[64:65], 0
	s_add_i32 s41, s0, 2
	s_add_u32 s42, s58, s64
	s_addc_u32 s43, s59, s65
	s_mov_b32 s98, s42
	s_mov_b32 s99, s43
	ds_read_b128 v[134:137], v179
	ds_read_b128 v[138:141], v179 offset:1024
	ds_read_b128 v[142:145], v179 offset:2048
	ds_read_b128 v[162:165], v179 offset:3072
	ds_read_b128 v[166:169], v180
	ds_read_b128 v[186:189], v180 offset:1024
	ds_read_b128 v[190:193], v180 offset:2048
	ds_read_b128 v[194:197], v180 offset:3072
	s_add_u32 s46, s42, 0x100
	s_addc_u32 s47, s43, 0
	s_add_u32 s48, s39, s64
	s_addc_u32 s49, s40, s65
	s_cmp_eq_u32 s38, s0
	s_cselect_b64 s[42:43], -1, 0
	s_and_b64 s[44:45], s[42:43], exec
	s_cselect_b32 s67, s55, s47
	s_cselect_b32 s66, s61, s46
	s_cselect_b32 s71, vcc_lo, s49
	s_cselect_b32 s70, vcc_hi, s48
	s_and_b64 s[42:43], s[36:37], s[42:43]
	s_and_b64 s[42:43], s[42:43], exec
	s_cselect_b32 s0, s3, s60
	s_cselect_b32 s68, s4, s62
	s_add_i32 m0, s82, 0xc000
	ds_read_b128 v[198:201], v181
	ds_read_b128 v[202:205], v181 offset:1024
	ds_read_b128 v[206:209], v181 offset:2048
	ds_read_b128 v[210:213], v181 offset:3072
	ds_read_b128 v[214:217], v181 offset:4096
	ds_read_b128 v[218:221], v181 offset:5120
	ds_read_b128 v[222:225], v181 offset:6144
	ds_read_b128 v[226:229], v181 offset:7168
	global_load_lds_dwordx4 v240, s[98:99]
	s_add_i32 m0, s82, 0xe000
	s_nop 0
	global_load_lds_dwordx4 v242, s[98:99]
	s_waitcnt vmcnt(8)
	s_waitcnt lgkmcnt(0)
	s_barrier
	s_waitcnt lgkmcnt(0)
	v_mfma_f32_16x16x32_bf16 v[126:129], v[134:137], v[198:201], 0
	v_mfma_f32_16x16x32_bf16 v[122:125], v[142:145], v[198:201], 0
	v_mfma_f32_16x16x32_bf16 v[110:113], v[134:137], v[206:209], 0
	v_mfma_f32_16x16x32_bf16 v[106:109], v[142:145], v[206:209], 0
	v_mfma_f32_16x16x32_bf16 v[94:97], v[134:137], v[214:217], 0
	v_mfma_f32_16x16x32_bf16 v[90:93], v[142:145], v[214:217], 0
	v_mfma_f32_16x16x32_bf16 v[78:81], v[134:137], v[222:225], 0
	v_mfma_f32_16x16x32_bf16 v[74:77], v[142:145], v[222:225], 0
	v_mfma_f32_16x16x32_bf16 v[126:129], v[138:141], v[202:205], v[126:129]
	v_mfma_f32_16x16x32_bf16 v[122:125], v[162:165], v[202:205], v[122:125]
	v_mfma_f32_16x16x32_bf16 v[110:113], v[138:141], v[210:213], v[110:113]
	v_mfma_f32_16x16x32_bf16 v[106:109], v[162:165], v[210:213], v[106:109]
	v_mfma_f32_16x16x32_bf16 v[94:97], v[138:141], v[218:221], v[94:97]
	v_mfma_f32_16x16x32_bf16 v[90:93], v[162:165], v[218:221], v[90:93]
	v_mfma_f32_16x16x32_bf16 v[78:81], v[138:141], v[226:229], v[78:81]
	v_mfma_f32_16x16x32_bf16 v[74:77], v[162:165], v[226:229], v[74:77]
	v_mfma_f32_16x16x32_bf16 v[118:121], v[166:169], v[198:201], 0
	v_mfma_f32_16x16x32_bf16 v[114:117], v[190:193], v[198:201], 0
	v_mfma_f32_16x16x32_bf16 v[102:105], v[166:169], v[206:209], 0
	v_mfma_f32_16x16x32_bf16 v[98:101], v[190:193], v[206:209], 0
	v_mfma_f32_16x16x32_bf16 v[86:89], v[166:169], v[214:217], 0
	v_mfma_f32_16x16x32_bf16 v[82:85], v[190:193], v[214:217], 0
	v_mfma_f32_16x16x32_bf16 v[70:73], v[166:169], v[222:225], 0
	v_mfma_f32_16x16x32_bf16 v[66:69], v[190:193], v[222:225], 0
	v_mfma_f32_16x16x32_bf16 v[118:121], v[186:189], v[202:205], v[118:121]
	v_mfma_f32_16x16x32_bf16 v[114:117], v[194:197], v[202:205], v[114:117]
	v_mfma_f32_16x16x32_bf16 v[102:105], v[186:189], v[210:213], v[102:105]
	v_mfma_f32_16x16x32_bf16 v[98:101], v[194:197], v[210:213], v[98:101]
	v_mfma_f32_16x16x32_bf16 v[86:89], v[186:189], v[218:221], v[86:89]
	v_mfma_f32_16x16x32_bf16 v[82:85], v[194:197], v[218:221], v[82:85]
	v_mfma_f32_16x16x32_bf16 v[70:73], v[186:189], v[226:229], v[70:73]
	v_mfma_f32_16x16x32_bf16 v[66:69], v[194:197], v[226:229], v[66:69]
	s_barrier
	v_mad_u32_u24 v230, v173, s0, v146
	s_add_i32 s42, s97, s81
	s_mov_b32 m0, s42
	ds_read_b128 v[198:201], v181 offset:16384
	ds_read_b128 v[202:205], v181 offset:17408
	ds_read_b128 v[206:209], v181 offset:18432
	ds_read_b128 v[210:213], v181 offset:19456
	ds_read_b128 v[214:217], v181 offset:20480
	ds_read_b128 v[218:221], v181 offset:21504
	ds_read_b128 v[222:225], v181 offset:22528
	ds_read_b128 v[226:229], v181 offset:23552
	global_load_lds_dwordx4 v230, s[70:71]
	s_add_i32 m0, s42, 0x2000
	s_lshl_b64 s[42:43], s[0:1], 7
	v_mad_u32_u24 v232, v175, s0, v146
	s_add_u32 s42, s70, s42
	s_addc_u32 s43, s71, s43
	s_mov_b64 s[100:101], s[42:43]
	s_add_i32 s0, s33, s81
	global_load_lds_dwordx4 v232, s[70:71]
	s_mov_b32 m0, s0
	v_mad_u32_u24 v234, v172, s68, v146
	global_load_lds_dwordx4 v230, s[42:43]
	s_add_i32 m0, s0, 0x2000
	v_mad_u32_u24 v236, v174, s68, v146
	global_load_lds_dwordx4 v232, s[42:43]
	s_mov_b32 m0, s82
	s_nop 0
	global_load_lds_dwordx4 v234, s[66:67]
	s_mov_b32 m0, s83
	s_nop 0
	global_load_lds_dwordx4 v236, s[66:67]
	s_waitcnt vmcnt(8)
	s_waitcnt lgkmcnt(0)
	s_barrier
; #define PG8_STAGE(bufoff, gbase, RR, ld) do { _Pragma("unroll") for (int _i = 0; _i < 2; ++_i) \
;         __builtin_amdgcn_global_load_lds((const unsigned*)((const char*)(gbase) + (RR)[_i] * (ld) + C2[_i]), (LAS unsigned*)(lds + (bufoff) + ldsw + _i * 8192), 16, 0, 0); } while (0)
; #define PG8_LDA(dst, b, h) do { _Pragma("unroll") for (int m = 0; m < 4; ++m) _Pragma("unroll") for (int k = 0; k < 2; ++k) dst[m][k] = *(const LAS bf16x8*)(lds + PG8_SA(b, h) + aoff + m * 2048 + k * 1024); } while (0)
; #define PG8_LDB(dst, b, h) do { _Pragma("unroll") for (int n = 0; n < 2; ++n) _Pragma("unroll") for (int k = 0; k < 2; ++k) dst[n][k] = *(const LAS bf16x8*)(lds + PG8_SB(b, h) + boff + n * 2048 + k * 1024); } while (0)
; #define PG8_MMA(ai, bj, At, Bt) do { __builtin_amdgcn_s_setprio(1); _Pragma("unroll") for (int m = 0; m < 4; ++m) _Pragma("unroll") for (int n = 0; n < 2; ++n) _Pragma("unroll") for (int k = 0; k < 2; ++k) \
;         acc[ai][bj][m][n] = __builtin_amdgcn_mfma_f32_16x16x32_bf16(Bt[n][k], At[m][k], acc[ai][bj][m][n], 0, 0, 0); __builtin_amdgcn_s_setprio(0); } while (0)
; #define PG8_WAIT_V(n) asm volatile("s_waitcnt vmcnt(" #n ")" ::: "memory")
; #define PG8_WAIT_L(n) asm volatile("s_waitcnt lgkmcnt(" #n ")" ::: "memory")
; #define PG8_BAR __builtin_amdgcn_s_barrier()
; #define PG8_SCHED __builtin_amdgcn_sched_barrier(0)
; template <class Sched, class Epi>
; __device__ __forceinline__ void gemm_run(LAS unsigned char* lds, const Sched& S, const Epi& E) {
;     ...
;             PG8_WAIT_V(8); PG8_WAIT_L(0); PG8_BAR; PG8_MMA(1, 0, At, B0); PG8_MMA(1, 1, At, B1); PG8_BAR; PG8_SCHED;
;             PG8_LDB(B0, 1, 0); PG8_LDB(B1, 1, 1); PG8_SCHED; PG8_LDA(At, 1, 0); PG8_STAGE(PG8_SA(0, 1), a2 + (size_t)HALF * la2, RA, la2);
;             PG8_WAIT_V(8); PG8_WAIT_L(0); PG8_BAR; PG8_MMA(0, 0, At, B0); PG8_MMA(0, 1, At, B1); PG8_BAR; PG8_SCHED;
	s_waitcnt lgkmcnt(0)
	v_mfma_f32_16x16x32_bf16 v[62:65], v[134:137], v[198:201], 0
	v_mfma_f32_16x16x32_bf16 v[58:61], v[142:145], v[198:201], 0
	v_mfma_f32_16x16x32_bf16 v[46:49], v[134:137], v[206:209], 0
	v_mfma_f32_16x16x32_bf16 v[42:45], v[142:145], v[206:209], 0
	v_mfma_f32_16x16x32_bf16 v[30:33], v[134:137], v[214:217], 0
	v_mfma_f32_16x16x32_bf16 v[26:29], v[142:145], v[214:217], 0
	v_mfma_f32_16x16x32_bf16 v[14:17], v[134:137], v[222:225], 0
	v_mfma_f32_16x16x32_bf16 v[10:13], v[142:145], v[222:225], 0
	v_mfma_f32_16x16x32_bf16 v[62:65], v[138:141], v[202:205], v[62:65]
	v_mfma_f32_16x16x32_bf16 v[58:61], v[162:165], v[202:205], v[58:61]
	v_mfma_f32_16x16x32_bf16 v[46:49], v[138:141], v[210:213], v[46:49]
	v_mfma_f32_16x16x32_bf16 v[42:45], v[162:165], v[210:213], v[42:45]
	v_mfma_f32_16x16x32_bf16 v[30:33], v[138:141], v[218:221], v[30:33]
	v_mfma_f32_16x16x32_bf16 v[26:29], v[162:165], v[218:221], v[26:29]
	v_mfma_f32_16x16x32_bf16 v[14:17], v[138:141], v[226:229], v[14:17]
	v_mfma_f32_16x16x32_bf16 v[10:13], v[162:165], v[226:229], v[10:13]
	v_mfma_f32_16x16x32_bf16 v[54:57], v[166:169], v[198:201], 0
	v_mfma_f32_16x16x32_bf16 v[50:53], v[190:193], v[198:201], 0
	v_mfma_f32_16x16x32_bf16 v[38:41], v[166:169], v[206:209], 0
	v_mfma_f32_16x16x32_bf16 v[34:37], v[190:193], v[206:209], 0
	v_mfma_f32_16x16x32_bf16 v[22:25], v[166:169], v[214:217], 0
	v_mfma_f32_16x16x32_bf16 v[18:21], v[190:193], v[214:217], 0
	v_mfma_f32_16x16x32_bf16 v[6:9], v[166:169], v[222:225], 0
	v_mfma_f32_16x16x32_bf16 v[2:5], v[190:193], v[222:225], 0
	v_mfma_f32_16x16x32_bf16 v[54:57], v[186:189], v[202:205], v[54:57]
	v_mfma_f32_16x16x32_bf16 v[50:53], v[194:197], v[202:205], v[50:53]
	v_mfma_f32_16x16x32_bf16 v[38:41], v[186:189], v[210:213], v[38:41]
	v_mfma_f32_16x16x32_bf16 v[34:37], v[194:197], v[210:213], v[34:37]
	v_mfma_f32_16x16x32_bf16 v[22:25], v[186:189], v[218:221], v[22:25]
	v_mfma_f32_16x16x32_bf16 v[18:21], v[194:197], v[218:221], v[18:21]
	v_mfma_f32_16x16x32_bf16 v[6:9], v[186:189], v[226:229], v[6:9]
	v_mfma_f32_16x16x32_bf16 v[2:5], v[194:197], v[226:229], v[2:5]
	s_barrier
	s_add_i32 s0, 0, 0x18000
	s_add_i32 s44, 0, 0x1c000
	ds_read_b128 v[134:137], v179 offset:32768
	ds_read_b128 v[138:141], v179 offset:33792
	ds_read_b128 v[142:145], v179 offset:34816
	ds_read_b128 v[162:165], v179 offset:35840
	ds_read_b128 v[166:169], v180 offset:32768
	ds_read_b128 v[186:189], v180 offset:33792
	ds_read_b128 v[190:193], v180 offset:34816
	ds_read_b128 v[194:197], v180 offset:35840
	s_mov_b32 s69, s1
	s_lshl_b64 s[42:43], s[68:69], 7
	s_add_u32 s42, s66, s42
	s_addc_u32 s43, s67, s43
	s_mov_b32 m0, s85
	ds_read_b128 v[198:201], v181 offset:32768
	ds_read_b128 v[202:205], v181 offset:33792
	ds_read_b128 v[206:209], v181 offset:34816
	ds_read_b128 v[210:213], v181 offset:35840
	ds_read_b128 v[214:217], v181 offset:36864
	ds_read_b128 v[218:221], v181 offset:37888
	ds_read_b128 v[222:225], v181 offset:38912
	ds_read_b128 v[226:229], v181 offset:39936
	global_load_lds_dwordx4 v234, s[42:43]
	s_mov_b32 m0, s90
	s_nop 0
	global_load_lds_dwordx4 v236, s[42:43]
	s_waitcnt vmcnt(8)
	s_waitcnt lgkmcnt(0)
	s_barrier
	s_waitcnt lgkmcnt(0)
	v_mfma_f32_16x16x32_bf16 v[126:129], v[134:137], v[198:201], v[126:129]
	v_mfma_f32_16x16x32_bf16 v[122:125], v[142:145], v[198:201], v[122:125]
	v_mfma_f32_16x16x32_bf16 v[110:113], v[134:137], v[206:209], v[110:113]
	v_mfma_f32_16x16x32_bf16 v[106:109], v[142:145], v[206:209], v[106:109]
	v_mfma_f32_16x16x32_bf16 v[94:97], v[134:137], v[214:217], v[94:97]
	v_mfma_f32_16x16x32_bf16 v[90:93], v[142:145], v[214:217], v[90:93]
	v_mfma_f32_16x16x32_bf16 v[78:81], v[134:137], v[222:225], v[78:81]
	v_mfma_f32_16x16x32_bf16 v[74:77], v[142:145], v[222:225], v[74:77]
	v_mfma_f32_16x16x32_bf16 v[126:129], v[138:141], v[202:205], v[126:129]
	v_mfma_f32_16x16x32_bf16 v[122:125], v[162:165], v[202:205], v[122:125]
	v_mfma_f32_16x16x32_bf16 v[110:113], v[138:141], v[210:213], v[110:113]
	v_mfma_f32_16x16x32_bf16 v[106:109], v[162:165], v[210:213], v[106:109]
	v_mfma_f32_16x16x32_bf16 v[94:97], v[138:141], v[218:221], v[94:97]
	v_mfma_f32_16x16x32_bf16 v[90:93], v[162:165], v[218:221], v[90:93]
	v_mfma_f32_16x16x32_bf16 v[78:81], v[138:141], v[226:229], v[78:81]
	v_mfma_f32_16x16x32_bf16 v[74:77], v[162:165], v[226:229], v[74:77]
	v_mfma_f32_16x16x32_bf16 v[118:121], v[166:169], v[198:201], v[118:121]
	v_mfma_f32_16x16x32_bf16 v[114:117], v[190:193], v[198:201], v[114:117]
	v_mfma_f32_16x16x32_bf16 v[102:105], v[166:169], v[206:209], v[102:105]
	v_mfma_f32_16x16x32_bf16 v[98:101], v[190:193], v[206:209], v[98:101]
	v_mfma_f32_16x16x32_bf16 v[86:89], v[166:169], v[214:217], v[86:89]
	v_mfma_f32_16x16x32_bf16 v[82:85], v[190:193], v[214:217], v[82:85]
	v_mfma_f32_16x16x32_bf16 v[70:73], v[166:169], v[222:225], v[70:73]
	v_mfma_f32_16x16x32_bf16 v[66:69], v[190:193], v[222:225], v[66:69]
	v_mfma_f32_16x16x32_bf16 v[118:121], v[186:189], v[202:205], v[118:121]
	v_mfma_f32_16x16x32_bf16 v[114:117], v[194:197], v[202:205], v[114:117]
	v_mfma_f32_16x16x32_bf16 v[102:105], v[186:189], v[210:213], v[102:105]
	v_mfma_f32_16x16x32_bf16 v[98:101], v[194:197], v[210:213], v[98:101]
	v_mfma_f32_16x16x32_bf16 v[86:89], v[186:189], v[218:221], v[86:89]
	v_mfma_f32_16x16x32_bf16 v[82:85], v[194:197], v[218:221], v[82:85]
	v_mfma_f32_16x16x32_bf16 v[70:73], v[186:189], v[226:229], v[70:73]
	v_mfma_f32_16x16x32_bf16 v[66:69], v[194:197], v[226:229], v[66:69]
	s_barrier
; #define PG8_STAGE(bufoff, gbase, RR, ld) do { _Pragma("unroll") for (int _i = 0; _i < 2; ++_i) \
;         __builtin_amdgcn_global_load_lds((const unsigned*)((const char*)(gbase) + (RR)[_i] * (ld) + C2[_i]), (LAS unsigned*)(lds + (bufoff) + ldsw + _i * 8192), 16, 0, 0); } while (0)
; #define PG8_LDA(dst, b, h) do { _Pragma("unroll") for (int m = 0; m < 4; ++m) _Pragma("unroll") for (int k = 0; k < 2; ++k) dst[m][k] = *(const LAS bf16x8*)(lds + PG8_SA(b, h) + aoff + m * 2048 + k * 1024); } while (0)
; #define PG8_LDB(dst, b, h) do { _Pragma("unroll") for (int n = 0; n < 2; ++n) _Pragma("unroll") for (int k = 0; k < 2; ++k) dst[n][k] = *(const LAS bf16x8*)(lds + PG8_SB(b, h) + boff + n * 2048 + k * 1024); } while (0)
; #define PG8_MMA(ai, bj, At, Bt) do { __builtin_amdgcn_s_setprio(1); _Pragma("unroll") for (int m = 0; m < 4; ++m) _Pragma("unroll") for (int n = 0; n < 2; ++n) _Pragma("unroll") for (int k = 0; k < 2; ++k) \
;         acc[ai][bj][m][n] = __builtin_amdgcn_mfma_f32_16x16x32_bf16(Bt[n][k], At[m][k], acc[ai][bj][m][n], 0, 0, 0); __builtin_amdgcn_s_setprio(0); } while (0)
; #define PG8_WAIT_V(n) asm volatile("s_waitcnt vmcnt(" #n ")" ::: "memory")
; #define PG8_WAIT_L(n) asm volatile("s_waitcnt lgkmcnt(" #n ")" ::: "memory")
; #define PG8_BAR __builtin_amdgcn_s_barrier()
; #define PG8_SCHED __builtin_amdgcn_sched_barrier(0)
; template <class Sched, class Epi>
; __device__ __forceinline__ void gemm_run(LAS unsigned char* lds, const Sched& S, const Epi& E) {
;     ...
;             PG8_LDB(B0, 0, 0); PG8_LDB(B1, 0, 1); PG8_SCHED; PG8_LDA(At, 0, 0); PG8_STAGE(PG8_SA(1, 1), a1 + (size_t)HALF * lda, RA, lda);
;     ...
;             PG8_LDA(At, 1, 1); PG8_STAGE(PG8_SB(1, 0), b3, RB, lb2); PG8_STAGE(PG8_SB(1, 1), b3 + (size_t)HALF * lb2, RB, lb2); PG8_STAGE(PG8_SA(1, 0), a3, RA, la2);
;             PG8_WAIT_V(8); PG8_WAIT_L(0); PG8_BAR; PG8_MMA(1, 0, At, B0); PG8_MMA(1, 1, At, B1); PG8_BAR; PG8_SCHED;
	s_add_i32 s0, s0, s81
	s_add_u32 s98, s70, 0x80
	s_addc_u32 s99, s71, 0
	s_mov_b32 m0, s0
	ds_read_b128 v[198:201], v181 offset:49152
	ds_read_b128 v[202:205], v181 offset:50176
	ds_read_b128 v[206:209], v181 offset:51200
	ds_read_b128 v[210:213], v181 offset:52224
	ds_read_b128 v[214:217], v181 offset:53248
	ds_read_b128 v[218:221], v181 offset:54272
	ds_read_b128 v[222:225], v181 offset:55296
	ds_read_b128 v[226:229], v181 offset:56320
	global_load_lds_dwordx4 v230, s[98:99]
	s_add_i32 m0, s0, 0x2000
	s_add_i32 s0, s44, s81
	global_load_lds_dwordx4 v232, s[98:99]
	s_add_u32 s100, s100, 0x80
	s_addc_u32 s101, s101, 0
	s_mov_b32 m0, s0
	s_nop 0
	global_load_lds_dwordx4 v230, s[100:101]
	s_add_i32 m0, s0, 0x2000
	s_nop 0
	global_load_lds_dwordx4 v232, s[100:101]
	s_add_u32 s42, s66, 0x80
	s_addc_u32 s43, s67, 0
	s_mov_b32 m0, s93
	s_nop 0
	global_load_lds_dwordx4 v234, s[42:43]
	s_mov_b32 m0, s94
	s_nop 0
	global_load_lds_dwordx4 v236, s[42:43]
	s_waitcnt vmcnt(8)
	s_waitcnt lgkmcnt(0)
	s_barrier
	s_waitcnt lgkmcnt(0)
	v_mfma_f32_16x16x32_bf16 v[62:65], v[134:137], v[198:201], v[62:65]
	v_mfma_f32_16x16x32_bf16 v[58:61], v[142:145], v[198:201], v[58:61]
	v_mfma_f32_16x16x32_bf16 v[46:49], v[134:137], v[206:209], v[46:49]
	v_mfma_f32_16x16x32_bf16 v[42:45], v[142:145], v[206:209], v[42:45]
	v_mfma_f32_16x16x32_bf16 v[30:33], v[134:137], v[214:217], v[30:33]
	v_mfma_f32_16x16x32_bf16 v[26:29], v[142:145], v[214:217], v[26:29]
	v_mfma_f32_16x16x32_bf16 v[14:17], v[134:137], v[222:225], v[14:17]
	v_mfma_f32_16x16x32_bf16 v[10:13], v[142:145], v[222:225], v[10:13]
	v_mfma_f32_16x16x32_bf16 v[62:65], v[138:141], v[202:205], v[62:65]
	v_mfma_f32_16x16x32_bf16 v[58:61], v[162:165], v[202:205], v[58:61]
	v_mfma_f32_16x16x32_bf16 v[46:49], v[138:141], v[210:213], v[46:49]
	v_mfma_f32_16x16x32_bf16 v[42:45], v[162:165], v[210:213], v[42:45]
	v_mfma_f32_16x16x32_bf16 v[30:33], v[138:141], v[218:221], v[30:33]
	v_mfma_f32_16x16x32_bf16 v[26:29], v[162:165], v[218:221], v[26:29]
	v_mfma_f32_16x16x32_bf16 v[14:17], v[138:141], v[226:229], v[14:17]
	v_mfma_f32_16x16x32_bf16 v[10:13], v[162:165], v[226:229], v[10:13]
	v_mfma_f32_16x16x32_bf16 v[54:57], v[166:169], v[198:201], v[54:57]
	v_mfma_f32_16x16x32_bf16 v[50:53], v[190:193], v[198:201], v[50:53]
	v_mfma_f32_16x16x32_bf16 v[38:41], v[166:169], v[206:209], v[38:41]
	v_mfma_f32_16x16x32_bf16 v[34:37], v[190:193], v[206:209], v[34:37]
	v_mfma_f32_16x16x32_bf16 v[22:25], v[166:169], v[214:217], v[22:25]
	v_mfma_f32_16x16x32_bf16 v[18:21], v[190:193], v[214:217], v[18:21]
	v_mfma_f32_16x16x32_bf16 v[6:9], v[166:169], v[222:225], v[6:9]
	v_mfma_f32_16x16x32_bf16 v[2:5], v[190:193], v[222:225], v[2:5]
	v_mfma_f32_16x16x32_bf16 v[54:57], v[186:189], v[202:205], v[54:57]
	v_mfma_f32_16x16x32_bf16 v[50:53], v[194:197], v[202:205], v[50:53]
	v_mfma_f32_16x16x32_bf16 v[38:41], v[186:189], v[210:213], v[38:41]
	v_mfma_f32_16x16x32_bf16 v[34:37], v[194:197], v[210:213], v[34:37]
	v_mfma_f32_16x16x32_bf16 v[22:25], v[186:189], v[218:221], v[22:25]
	v_mfma_f32_16x16x32_bf16 v[18:21], v[194:197], v[218:221], v[18:21]
	v_mfma_f32_16x16x32_bf16 v[6:9], v[186:189], v[226:229], v[6:9]
	v_mfma_f32_16x16x32_bf16 v[2:5], v[194:197], v[226:229], v[2:5]
	s_barrier
	s_add_u32 s64, s64, 0x100
	s_addc_u32 s65, s65, 0
	s_cmp_ge_i32 s41, s5
	s_mov_b32 s0, s41
	s_cbranch_scc0 .LBB0_440
	.p2align 6
.LBB0_440:
	s_add_i32 s41, s0, 2
	s_add_u32 s42, s58, s64
	s_addc_u32 s43, s59, s65
	s_mov_b32 s98, s42
	s_mov_b32 s99, s43
	ds_read_b128 v[134:137], v179
	ds_read_b128 v[138:141], v179 offset:1024
	ds_read_b128 v[142:145], v179 offset:2048
	ds_read_b128 v[162:165], v179 offset:3072
	ds_read_b128 v[166:169], v180
	ds_read_b128 v[186:189], v180 offset:1024
	ds_read_b128 v[190:193], v180 offset:2048
	ds_read_b128 v[194:197], v180 offset:3072
	s_add_u32 s46, s42, 0x100
	s_addc_u32 s47, s43, 0
	s_add_u32 s48, s39, s64
	s_addc_u32 s49, s40, s65
	s_cmp_eq_u32 s38, s0
	s_cselect_b64 s[42:43], -1, 0
	s_and_b64 s[44:45], s[42:43], exec
	s_cselect_b32 s67, s55, s47
	s_cselect_b32 s66, s61, s46
	s_cselect_b32 s71, vcc_lo, s49
	s_cselect_b32 s70, vcc_hi, s48
	s_and_b64 s[42:43], s[36:37], s[42:43]
	s_and_b64 s[42:43], s[42:43], exec
	s_cselect_b32 s0, s3, s60
	s_cselect_b32 s68, s4, s62
	s_add_i32 m0, s82, 0xc000
	ds_read_b128 v[198:201], v181
	ds_read_b128 v[202:205], v181 offset:1024
	ds_read_b128 v[206:209], v181 offset:2048
	ds_read_b128 v[210:213], v181 offset:3072
	ds_read_b128 v[214:217], v181 offset:4096
	ds_read_b128 v[218:221], v181 offset:5120
	ds_read_b128 v[222:225], v181 offset:6144
	ds_read_b128 v[226:229], v181 offset:7168
	global_load_lds_dwordx4 v240, s[98:99]
	s_add_i32 m0, s82, 0xe000
	s_nop 0
	global_load_lds_dwordx4 v242, s[98:99]
	s_waitcnt vmcnt(8)
	s_waitcnt lgkmcnt(0)
	s_barrier
; #define PG8_STAGE(bufoff, gbase, RR, ld) do { _Pragma("unroll") for (int _i = 0; _i < 2; ++_i) \
;         __builtin_amdgcn_global_load_lds((const unsigned*)((const char*)(gbase) + (RR)[_i] * (ld) + C2[_i]), (LAS unsigned*)(lds + (bufoff) + ldsw + _i * 8192), 16, 0, 0); } while (0)
; #define PG8_LDA(dst, b, h) do { _Pragma("unroll") for (int m = 0; m < 4; ++m) _Pragma("unroll") for (int k = 0; k < 2; ++k) dst[m][k] = *(const LAS bf16x8*)(lds + PG8_SA(b, h) + aoff + m * 2048 + k * 1024); } while (0)
; #define PG8_LDB(dst, b, h) do { _Pragma("unroll") for (int n = 0; n < 2; ++n) _Pragma("unroll") for (int k = 0; k < 2; ++k) dst[n][k] = *(const LAS bf16x8*)(lds + PG8_SB(b, h) + boff + n * 2048 + k * 1024); } while (0)
; #define PG8_MMA(ai, bj, At, Bt) do { __builtin_amdgcn_s_setprio(1); _Pragma("unroll") for (int m = 0; m < 4; ++m) _Pragma("unroll") for (int n = 0; n < 2; ++n) _Pragma("unroll") for (int k = 0; k < 2; ++k) \
;         acc[ai][bj][m][n] = __builtin_amdgcn_mfma_f32_16x16x32_bf16(Bt[n][k], At[m][k], acc[ai][bj][m][n], 0, 0, 0); __builtin_amdgcn_s_setprio(0); } while (0)
; #define PG8_WAIT_V(n) asm volatile("s_waitcnt vmcnt(" #n ")" ::: "memory")
; #define PG8_WAIT_L(n) asm volatile("s_waitcnt lgkmcnt(" #n ")" ::: "memory")
; #define PG8_BAR __builtin_amdgcn_s_barrier()
; #define PG8_SCHED __builtin_amdgcn_sched_barrier(0)
; template <class Sched, class Epi>
; __device__ __forceinline__ void gemm_run(LAS unsigned char* lds, const Sched& S, const Epi& E) {
;     ...
;             PG8_WAIT_V(8); PG8_WAIT_L(0); PG8_BAR; PG8_MMA(0, 0, At, B0); PG8_MMA(0, 1, At, B1); PG8_BAR; PG8_SCHED;
;             PG8_LDA(At, 0, 1); PG8_STAGE(PG8_SB(0, 0), b2, RB, lb2); PG8_STAGE(PG8_SB(0, 1), b2 + (size_t)HALF * lb2, RB, lb2); PG8_STAGE(PG8_SA(0, 0), a2, RA, la2);
;             PG8_WAIT_V(8); PG8_WAIT_L(0); PG8_BAR; PG8_MMA(1, 0, At, B0); PG8_MMA(1, 1, At, B1); PG8_BAR; PG8_SCHED;
;             PG8_LDB(B0, 1, 0); PG8_LDB(B1, 1, 1); PG8_SCHED; PG8_LDA(At, 1, 0); PG8_STAGE(PG8_SA(0, 1), a2 + (size_t)HALF * la2, RA, la2);
	s_waitcnt lgkmcnt(0)
	v_mfma_f32_16x16x32_bf16 v[126:129], v[134:137], v[198:201], v[126:129]
	v_mfma_f32_16x16x32_bf16 v[122:125], v[142:145], v[198:201], v[122:125]
	v_mfma_f32_16x16x32_bf16 v[110:113], v[134:137], v[206:209], v[110:113]
	v_mfma_f32_16x16x32_bf16 v[106:109], v[142:145], v[206:209], v[106:109]
	v_mfma_f32_16x16x32_bf16 v[94:97], v[134:137], v[214:217], v[94:97]
	v_mfma_f32_16x16x32_bf16 v[90:93], v[142:145], v[214:217], v[90:93]
	v_mfma_f32_16x16x32_bf16 v[78:81], v[134:137], v[222:225], v[78:81]
	v_mfma_f32_16x16x32_bf16 v[74:77], v[142:145], v[222:225], v[74:77]
	v_mfma_f32_16x16x32_bf16 v[126:129], v[138:141], v[202:205], v[126:129]
	v_mfma_f32_16x16x32_bf16 v[122:125], v[162:165], v[202:205], v[122:125]
	v_mfma_f32_16x16x32_bf16 v[110:113], v[138:141], v[210:213], v[110:113]
	v_mfma_f32_16x16x32_bf16 v[106:109], v[162:165], v[210:213], v[106:109]
	v_mfma_f32_16x16x32_bf16 v[94:97], v[138:141], v[218:221], v[94:97]
	v_mfma_f32_16x16x32_bf16 v[90:93], v[162:165], v[218:221], v[90:93]
	v_mfma_f32_16x16x32_bf16 v[78:81], v[138:141], v[226:229], v[78:81]
	v_mfma_f32_16x16x32_bf16 v[74:77], v[162:165], v[226:229], v[74:77]
	v_mfma_f32_16x16x32_bf16 v[118:121], v[166:169], v[198:201], v[118:121]
	v_mfma_f32_16x16x32_bf16 v[114:117], v[190:193], v[198:201], v[114:117]
	v_mfma_f32_16x16x32_bf16 v[102:105], v[166:169], v[206:209], v[102:105]
	v_mfma_f32_16x16x32_bf16 v[98:101], v[190:193], v[206:209], v[98:101]
	v_mfma_f32_16x16x32_bf16 v[86:89], v[166:169], v[214:217], v[86:89]
	v_mfma_f32_16x16x32_bf16 v[82:85], v[190:193], v[214:217], v[82:85]
	v_mfma_f32_16x16x32_bf16 v[70:73], v[166:169], v[222:225], v[70:73]
	v_mfma_f32_16x16x32_bf16 v[66:69], v[190:193], v[222:225], v[66:69]
	v_mfma_f32_16x16x32_bf16 v[118:121], v[186:189], v[202:205], v[118:121]
	v_mfma_f32_16x16x32_bf16 v[114:117], v[194:197], v[202:205], v[114:117]
	v_mfma_f32_16x16x32_bf16 v[102:105], v[186:189], v[210:213], v[102:105]
	v_mfma_f32_16x16x32_bf16 v[98:101], v[194:197], v[210:213], v[98:101]
	v_mfma_f32_16x16x32_bf16 v[86:89], v[186:189], v[218:221], v[86:89]
	v_mfma_f32_16x16x32_bf16 v[82:85], v[194:197], v[218:221], v[82:85]
	v_mfma_f32_16x16x32_bf16 v[70:73], v[186:189], v[226:229], v[70:73]
	v_mfma_f32_16x16x32_bf16 v[66:69], v[194:197], v[226:229], v[66:69]
	s_barrier
	v_mad_u32_u24 v230, v173, s0, v146
	s_add_i32 s42, s97, s81
	s_mov_b32 m0, s42
	ds_read_b128 v[198:201], v181 offset:16384
	ds_read_b128 v[202:205], v181 offset:17408
	ds_read_b128 v[206:209], v181 offset:18432
	ds_read_b128 v[210:213], v181 offset:19456
	ds_read_b128 v[214:217], v181 offset:20480
	ds_read_b128 v[218:221], v181 offset:21504
	ds_read_b128 v[222:225], v181 offset:22528
	ds_read_b128 v[226:229], v181 offset:23552
	global_load_lds_dwordx4 v230, s[70:71]
	s_add_i32 m0, s42, 0x2000
	s_lshl_b64 s[42:43], s[0:1], 7
	v_mad_u32_u24 v232, v175, s0, v146
	s_add_u32 s42, s70, s42
	s_addc_u32 s43, s71, s43
	s_mov_b64 s[100:101], s[42:43]
	s_add_i32 s0, s33, s81
	global_load_lds_dwordx4 v232, s[70:71]
	s_mov_b32 m0, s0
	v_mad_u32_u24 v234, v172, s68, v146
	global_load_lds_dwordx4 v230, s[42:43]
	s_add_i32 m0, s0, 0x2000
	v_mad_u32_u24 v236, v174, s68, v146
	global_load_lds_dwordx4 v232, s[42:43]
	s_mov_b32 m0, s82
	s_nop 0
	global_load_lds_dwordx4 v234, s[66:67]
	s_mov_b32 m0, s83
	s_nop 0
	global_load_lds_dwordx4 v236, s[66:67]
	s_waitcnt vmcnt(8)
	s_waitcnt lgkmcnt(0)
	s_barrier
	s_waitcnt lgkmcnt(0)
	v_mfma_f32_16x16x32_bf16 v[62:65], v[134:137], v[198:201], v[62:65]
	v_mfma_f32_16x16x32_bf16 v[58:61], v[142:145], v[198:201], v[58:61]
	v_mfma_f32_16x16x32_bf16 v[46:49], v[134:137], v[206:209], v[46:49]
	v_mfma_f32_16x16x32_bf16 v[42:45], v[142:145], v[206:209], v[42:45]
	v_mfma_f32_16x16x32_bf16 v[30:33], v[134:137], v[214:217], v[30:33]
	v_mfma_f32_16x16x32_bf16 v[26:29], v[142:145], v[214:217], v[26:29]
	v_mfma_f32_16x16x32_bf16 v[14:17], v[134:137], v[222:225], v[14:17]
	v_mfma_f32_16x16x32_bf16 v[10:13], v[142:145], v[222:225], v[10:13]
	v_mfma_f32_16x16x32_bf16 v[62:65], v[138:141], v[202:205], v[62:65]
	v_mfma_f32_16x16x32_bf16 v[58:61], v[162:165], v[202:205], v[58:61]
	v_mfma_f32_16x16x32_bf16 v[46:49], v[138:141], v[210:213], v[46:49]
	v_mfma_f32_16x16x32_bf16 v[42:45], v[162:165], v[210:213], v[42:45]
	v_mfma_f32_16x16x32_bf16 v[30:33], v[138:141], v[218:221], v[30:33]
	v_mfma_f32_16x16x32_bf16 v[26:29], v[162:165], v[218:221], v[26:29]
	v_mfma_f32_16x16x32_bf16 v[14:17], v[138:141], v[226:229], v[14:17]
	v_mfma_f32_16x16x32_bf16 v[10:13], v[162:165], v[226:229], v[10:13]
	v_mfma_f32_16x16x32_bf16 v[54:57], v[166:169], v[198:201], v[54:57]
	v_mfma_f32_16x16x32_bf16 v[50:53], v[190:193], v[198:201], v[50:53]
	v_mfma_f32_16x16x32_bf16 v[38:41], v[166:169], v[206:209], v[38:41]
	v_mfma_f32_16x16x32_bf16 v[34:37], v[190:193], v[206:209], v[34:37]
	v_mfma_f32_16x16x32_bf16 v[22:25], v[166:169], v[214:217], v[22:25]
	v_mfma_f32_16x16x32_bf16 v[18:21], v[190:193], v[214:217], v[18:21]
	v_mfma_f32_16x16x32_bf16 v[6:9], v[166:169], v[222:225], v[6:9]
	v_mfma_f32_16x16x32_bf16 v[2:5], v[190:193], v[222:225], v[2:5]
	v_mfma_f32_16x16x32_bf16 v[54:57], v[186:189], v[202:205], v[54:57]
	v_mfma_f32_16x16x32_bf16 v[50:53], v[194:197], v[202:205], v[50:53]
	v_mfma_f32_16x16x32_bf16 v[38:41], v[186:189], v[210:213], v[38:41]
	v_mfma_f32_16x16x32_bf16 v[34:37], v[194:197], v[210:213], v[34:37]
	v_mfma_f32_16x16x32_bf16 v[22:25], v[186:189], v[218:221], v[22:25]
	v_mfma_f32_16x16x32_bf16 v[18:21], v[194:197], v[218:221], v[18:21]
	v_mfma_f32_16x16x32_bf16 v[6:9], v[186:189], v[226:229], v[6:9]
	v_mfma_f32_16x16x32_bf16 v[2:5], v[194:197], v[226:229], v[2:5]
	s_barrier
; #define PG8_STAGE(bufoff, gbase, RR, ld) do { _Pragma("unroll") for (int _i = 0; _i < 2; ++_i) \
;         __builtin_amdgcn_global_load_lds((const unsigned*)((const char*)(gbase) + (RR)[_i] * (ld) + C2[_i]), (LAS unsigned*)(lds + (bufoff) + ldsw + _i * 8192), 16, 0, 0); } while (0)
; #define PG8_LDA(dst, b, h) do { _Pragma("unroll") for (int m = 0; m < 4; ++m) _Pragma("unroll") for (int k = 0; k < 2; ++k) dst[m][k] = *(const LAS bf16x8*)(lds + PG8_SA(b, h) + aoff + m * 2048 + k * 1024); } while (0)
; #define PG8_LDB(dst, b, h) do { _Pragma("unroll") for (int n = 0; n < 2; ++n) _Pragma("unroll") for (int k = 0; k < 2; ++k) dst[n][k] = *(const LAS bf16x8*)(lds + PG8_SB(b, h) + boff + n * 2048 + k * 1024); } while (0)
; #define PG8_MMA(ai, bj, At, Bt) do { __builtin_amdgcn_s_setprio(1); _Pragma("unroll") for (int m = 0; m < 4; ++m) _Pragma("unroll") for (int n = 0; n < 2; ++n) _Pragma("unroll") for (int k = 0; k < 2; ++k) \
;         acc[ai][bj][m][n] = __builtin_amdgcn_mfma_f32_16x16x32_bf16(Bt[n][k], At[m][k], acc[ai][bj][m][n], 0, 0, 0); __builtin_amdgcn_s_setprio(0); } while (0)
; #define PG8_WAIT_V(n) asm volatile("s_waitcnt vmcnt(" #n ")" ::: "memory")
; #define PG8_WAIT_L(n) asm volatile("s_waitcnt lgkmcnt(" #n ")" ::: "memory")
; #define PG8_BAR __builtin_amdgcn_s_barrier()
; #define PG8_SCHED __builtin_amdgcn_sched_barrier(0)
; template <class Sched, class Epi>
; __device__ __forceinline__ void gemm_run(LAS unsigned char* lds, const Sched& S, const Epi& E) {
;     ...
;             PG8_LDB(B0, 1, 0); PG8_LDB(B1, 1, 1); PG8_SCHED; PG8_LDA(At, 1, 0); PG8_STAGE(PG8_SA(0, 1), a2 + (size_t)HALF * la2, RA, la2);
;             PG8_WAIT_V(8); PG8_WAIT_L(0); PG8_BAR; PG8_MMA(0, 0, At, B0); PG8_MMA(0, 1, At, B1); PG8_BAR; PG8_SCHED;
;             PG8_LDA(At, 1, 1); PG8_STAGE(PG8_SB(1, 0), b3, RB, lb2); PG8_STAGE(PG8_SB(1, 1), b3 + (size_t)HALF * lb2, RB, lb2); PG8_STAGE(PG8_SA(1, 0), a3, RA, la2);
;             PG8_WAIT_V(8); PG8_WAIT_L(0); PG8_BAR; PG8_MMA(1, 0, At, B0); PG8_MMA(1, 1, At, B1); PG8_BAR; PG8_SCHED;
;         }
;         if (wr == 0) PG8_BAR;
	s_add_i32 s0, 0, 0x18000
	s_add_i32 s44, 0, 0x1c000
	ds_read_b128 v[134:137], v179 offset:32768
	ds_read_b128 v[138:141], v179 offset:33792
	ds_read_b128 v[142:145], v179 offset:34816
	ds_read_b128 v[162:165], v179 offset:35840
	ds_read_b128 v[166:169], v180 offset:32768
	ds_read_b128 v[186:189], v180 offset:33792
	ds_read_b128 v[190:193], v180 offset:34816
	ds_read_b128 v[194:197], v180 offset:35840
	s_mov_b32 s69, s1
	s_lshl_b64 s[42:43], s[68:69], 7
	s_add_u32 s42, s66, s42
	s_addc_u32 s43, s67, s43
	s_mov_b32 m0, s85
	ds_read_b128 v[198:201], v181 offset:32768
	ds_read_b128 v[202:205], v181 offset:33792
	ds_read_b128 v[206:209], v181 offset:34816
	ds_read_b128 v[210:213], v181 offset:35840
	ds_read_b128 v[214:217], v181 offset:36864
	ds_read_b128 v[218:221], v181 offset:37888
	ds_read_b128 v[222:225], v181 offset:38912
	ds_read_b128 v[226:229], v181 offset:39936
	global_load_lds_dwordx4 v234, s[42:43]
	s_mov_b32 m0, s90
	s_nop 0
	global_load_lds_dwordx4 v236, s[42:43]
	s_waitcnt vmcnt(8)
	s_waitcnt lgkmcnt(0)
	s_barrier
	s_waitcnt lgkmcnt(0)
	v_mfma_f32_16x16x32_bf16 v[126:129], v[134:137], v[198:201], v[126:129]
	v_mfma_f32_16x16x32_bf16 v[122:125], v[142:145], v[198:201], v[122:125]
	v_mfma_f32_16x16x32_bf16 v[110:113], v[134:137], v[206:209], v[110:113]
	v_mfma_f32_16x16x32_bf16 v[106:109], v[142:145], v[206:209], v[106:109]
	v_mfma_f32_16x16x32_bf16 v[94:97], v[134:137], v[214:217], v[94:97]
	v_mfma_f32_16x16x32_bf16 v[90:93], v[142:145], v[214:217], v[90:93]
	v_mfma_f32_16x16x32_bf16 v[78:81], v[134:137], v[222:225], v[78:81]
	v_mfma_f32_16x16x32_bf16 v[74:77], v[142:145], v[222:225], v[74:77]
	v_mfma_f32_16x16x32_bf16 v[126:129], v[138:141], v[202:205], v[126:129]
	v_mfma_f32_16x16x32_bf16 v[122:125], v[162:165], v[202:205], v[122:125]
	v_mfma_f32_16x16x32_bf16 v[110:113], v[138:141], v[210:213], v[110:113]
	v_mfma_f32_16x16x32_bf16 v[106:109], v[162:165], v[210:213], v[106:109]
	v_mfma_f32_16x16x32_bf16 v[94:97], v[138:141], v[218:221], v[94:97]
	v_mfma_f32_16x16x32_bf16 v[90:93], v[162:165], v[218:221], v[90:93]
	v_mfma_f32_16x16x32_bf16 v[78:81], v[138:141], v[226:229], v[78:81]
	v_mfma_f32_16x16x32_bf16 v[74:77], v[162:165], v[226:229], v[74:77]
	v_mfma_f32_16x16x32_bf16 v[118:121], v[166:169], v[198:201], v[118:121]
	v_mfma_f32_16x16x32_bf16 v[114:117], v[190:193], v[198:201], v[114:117]
	v_mfma_f32_16x16x32_bf16 v[102:105], v[166:169], v[206:209], v[102:105]
	v_mfma_f32_16x16x32_bf16 v[98:101], v[190:193], v[206:209], v[98:101]
	v_mfma_f32_16x16x32_bf16 v[86:89], v[166:169], v[214:217], v[86:89]
	v_mfma_f32_16x16x32_bf16 v[82:85], v[190:193], v[214:217], v[82:85]
	v_mfma_f32_16x16x32_bf16 v[70:73], v[166:169], v[222:225], v[70:73]
	v_mfma_f32_16x16x32_bf16 v[66:69], v[190:193], v[222:225], v[66:69]
	v_mfma_f32_16x16x32_bf16 v[118:121], v[186:189], v[202:205], v[118:121]
	v_mfma_f32_16x16x32_bf16 v[114:117], v[194:197], v[202:205], v[114:117]
	v_mfma_f32_16x16x32_bf16 v[102:105], v[186:189], v[210:213], v[102:105]
	v_mfma_f32_16x16x32_bf16 v[98:101], v[194:197], v[210:213], v[98:101]
	v_mfma_f32_16x16x32_bf16 v[86:89], v[186:189], v[218:221], v[86:89]
	v_mfma_f32_16x16x32_bf16 v[82:85], v[194:197], v[218:221], v[82:85]
	v_mfma_f32_16x16x32_bf16 v[70:73], v[186:189], v[226:229], v[70:73]
	v_mfma_f32_16x16x32_bf16 v[66:69], v[194:197], v[226:229], v[66:69]
	s_barrier
	s_add_i32 s0, s0, s81
	s_add_u32 s98, s70, 0x80
	s_addc_u32 s99, s71, 0
	s_mov_b32 m0, s0
	ds_read_b128 v[198:201], v181 offset:49152
	ds_read_b128 v[202:205], v181 offset:50176
	ds_read_b128 v[206:209], v181 offset:51200
	ds_read_b128 v[210:213], v181 offset:52224
	ds_read_b128 v[214:217], v181 offset:53248
	ds_read_b128 v[218:221], v181 offset:54272
	ds_read_b128 v[222:225], v181 offset:55296
	ds_read_b128 v[226:229], v181 offset:56320
	global_load_lds_dwordx4 v230, s[98:99]
	s_add_i32 m0, s0, 0x2000
	s_add_i32 s0, s44, s81
	global_load_lds_dwordx4 v232, s[98:99]
	s_add_u32 s100, s100, 0x80
	s_addc_u32 s101, s101, 0
	s_mov_b32 m0, s0
	s_nop 0
	global_load_lds_dwordx4 v230, s[100:101]
	s_add_i32 m0, s0, 0x2000
	s_nop 0
	global_load_lds_dwordx4 v232, s[100:101]
	s_add_u32 s42, s66, 0x80
	s_addc_u32 s43, s67, 0
	s_mov_b32 m0, s93
	s_nop 0
	global_load_lds_dwordx4 v234, s[42:43]
	s_mov_b32 m0, s94
	s_nop 0
	global_load_lds_dwordx4 v236, s[42:43]
	s_waitcnt vmcnt(8)
	s_waitcnt lgkmcnt(0)
	s_barrier
	s_waitcnt lgkmcnt(0)
	v_mfma_f32_16x16x32_bf16 v[62:65], v[134:137], v[198:201], v[62:65]
	v_mfma_f32_16x16x32_bf16 v[58:61], v[142:145], v[198:201], v[58:61]
	v_mfma_f32_16x16x32_bf16 v[46:49], v[134:137], v[206:209], v[46:49]
	v_mfma_f32_16x16x32_bf16 v[42:45], v[142:145], v[206:209], v[42:45]
	v_mfma_f32_16x16x32_bf16 v[30:33], v[134:137], v[214:217], v[30:33]
	v_mfma_f32_16x16x32_bf16 v[26:29], v[142:145], v[214:217], v[26:29]
	v_mfma_f32_16x16x32_bf16 v[14:17], v[134:137], v[222:225], v[14:17]
	v_mfma_f32_16x16x32_bf16 v[10:13], v[142:145], v[222:225], v[10:13]
	v_mfma_f32_16x16x32_bf16 v[62:65], v[138:141], v[202:205], v[62:65]
	v_mfma_f32_16x16x32_bf16 v[58:61], v[162:165], v[202:205], v[58:61]
	v_mfma_f32_16x16x32_bf16 v[46:49], v[138:141], v[210:213], v[46:49]
	v_mfma_f32_16x16x32_bf16 v[42:45], v[162:165], v[210:213], v[42:45]
	v_mfma_f32_16x16x32_bf16 v[30:33], v[138:141], v[218:221], v[30:33]
	v_mfma_f32_16x16x32_bf16 v[26:29], v[162:165], v[218:221], v[26:29]
	v_mfma_f32_16x16x32_bf16 v[14:17], v[138:141], v[226:229], v[14:17]
	v_mfma_f32_16x16x32_bf16 v[10:13], v[162:165], v[226:229], v[10:13]
	v_mfma_f32_16x16x32_bf16 v[54:57], v[166:169], v[198:201], v[54:57]
	v_mfma_f32_16x16x32_bf16 v[50:53], v[190:193], v[198:201], v[50:53]
	v_mfma_f32_16x16x32_bf16 v[38:41], v[166:169], v[206:209], v[38:41]
	v_mfma_f32_16x16x32_bf16 v[34:37], v[190:193], v[206:209], v[34:37]
	v_mfma_f32_16x16x32_bf16 v[22:25], v[166:169], v[214:217], v[22:25]
	v_mfma_f32_16x16x32_bf16 v[18:21], v[190:193], v[214:217], v[18:21]
	v_mfma_f32_16x16x32_bf16 v[6:9], v[166:169], v[222:225], v[6:9]
	v_mfma_f32_16x16x32_bf16 v[2:5], v[190:193], v[222:225], v[2:5]
	v_mfma_f32_16x16x32_bf16 v[54:57], v[186:189], v[202:205], v[54:57]
	v_mfma_f32_16x16x32_bf16 v[50:53], v[194:197], v[202:205], v[50:53]
	v_mfma_f32_16x16x32_bf16 v[38:41], v[186:189], v[210:213], v[38:41]
	v_mfma_f32_16x16x32_bf16 v[34:37], v[194:197], v[210:213], v[34:37]
	v_mfma_f32_16x16x32_bf16 v[22:25], v[186:189], v[218:221], v[22:25]
	v_mfma_f32_16x16x32_bf16 v[18:21], v[194:197], v[218:221], v[18:21]
	v_mfma_f32_16x16x32_bf16 v[6:9], v[186:189], v[226:229], v[6:9]
	v_mfma_f32_16x16x32_bf16 v[2:5], v[194:197], v[226:229], v[2:5]
	s_barrier
	s_add_u32 s64, s64, 0x100
	s_addc_u32 s65, s65, 0
	s_cmp_ge_i32 s41, s5
	s_mov_b32 s0, s41
	s_cbranch_scc0 .LBB0_440
	s_and_b64 vcc, exec, s[10:11]
	s_cbranch_vccz .LBB0_443
	s_barrier

; #define PG8_STAGE(bufoff, gbase, RR, ld) do { _Pragma("unroll") for (int _i = 0; _i < 2; ++_i) \
;         __builtin_amdgcn_global_load_lds((const unsigned*)((const char*)(gbase) + (RR)[_i] * (ld) + C2[_i]), (LAS unsigned*)(lds + (bufoff) + ldsw + _i * 8192), 16, 0, 0); } while (0)
; #define PG8_LDA(dst, b, h) do { _Pragma("unroll") for (int m = 0; m < 4; ++m) _Pragma("unroll") for (int k = 0; k < 2; ++k) dst[m][k] = *(const LAS bf16x8*)(lds + PG8_SA(b, h) + aoff + m * 2048 + k * 1024); } while (0)
; #define PG8_LDB(dst, b, h) do { _Pragma("unroll") for (int n = 0; n < 2; ++n) _Pragma("unroll") for (int k = 0; k < 2; ++k) dst[n][k] = *(const LAS bf16x8*)(lds + PG8_SB(b, h) + boff + n * 2048 + k * 1024); } while (0)
; #define PG8_WAIT_V(n) asm volatile("s_waitcnt vmcnt(" #n ")" ::: "memory")
; #define PG8_WAIT_L(n) asm volatile("s_waitcnt lgkmcnt(" #n ")" ::: "memory")
; #define PG8_BAR __builtin_amdgcn_s_barrier()
; #define PG8_SCHED __builtin_amdgcn_sched_barrier(0)
; template <class Sched, class Epi>
; __device__ __forceinline__ void gemm_run(LAS unsigned char* lds, const Sched& S, const Epi& E) {
;     ...
;         const bool has_next = S.next(ui + 1, nxt);
;         const char* nA = has_next ? nxt.A : cA; const char* nB = has_next ? nxt.B : cB; const unsigned nlda = has_next ? nxt.lda : lda, nldb = has_next ? nxt.ldb : ldb;
;         const int nt = cur.nt;
;         for (int t = 0; t < nt; t += 2) {
;             const bool last = (t == nt - 2);
;             const char* a1 = cA + (size_t)(t + 1) * kstep;
;             const char* a2 = last ? nA : cA + (size_t)(t + 2) * kstep; const char* b2 = last ? nB : cB + (size_t)(t + 2) * kstep;
;             const unsigned la2 = last ? nlda : lda, lb2 = last ? nldb : ldb;
;             const char* a3 = a2 + kstep; const char* b3 = b2 + kstep;
;             PG8_LDB(B0, 0, 0); PG8_LDB(B1, 0, 1); PG8_SCHED; PG8_LDA(At, 0, 0); PG8_STAGE(PG8_SA(1, 1), a1 + (size_t)HALF * lda, RA, lda);
;             PG8_WAIT_V(8); PG8_WAIT_L(0); PG8_BAR; PG8_MMA(0, 0, At, B0); PG8_MMA(0, 1, At, B1); PG8_BAR; PG8_SCHED;
;             PG8_LDA(At, 0, 1); PG8_STAGE(PG8_SB(0, 0), b2, RB, lb2); PG8_STAGE(PG8_SB(0, 1), b2 + (size_t)HALF * lb2, RB, lb2); PG8_STAGE(PG8_SA(0, 0), a2, RA, la2);
;             PG8_WAIT_V(8); PG8_WAIT_L(0); PG8_BAR; PG8_MMA(1, 0, At, B0); PG8_MMA(1, 1, At, B1); PG8_BAR; PG8_SCHED;
.LBB0_805:
	s_mov_b32 s57, s7
	s_lshl_b64 s[48:49], s[56:57], 7
	v_mad_u32_u24 v224, v191, s56, v150
	v_mad_u32_u24 v226, v192, s56, v150
	v_add_u32_e32 v224, s48, v224
	v_add_u32_e32 v226, s48, v226
	v_mul_lo_u32 v148, v191, s56
	v_lshl_add_u64 v[2:3], s[54:55], 0, v[150:151]
	v_lshl_add_u64 v[4:5], s[48:49], 0, v[148:149]
	v_mul_lo_u32 v148, v192, s56
	s_add_i32 s44, s81, -2
	v_lshl_add_u64 v[130:131], v[2:3], 0, v[4:5]
	v_lshl_add_u64 v[4:5], s[48:49], 0, v[148:149]
	s_add_u32 s45, s58, 0x100
	v_lshl_add_u64 v[132:133], v[2:3], 0, v[4:5]
	s_addc_u32 s46, s59, 0
	s_mov_b32 s6, 0
	s_mov_b64 s[58:59], 0
	ds_read_b128 v[134:137], v193
	ds_read_b128 v[138:141], v193 offset:1024
	ds_read_b128 v[142:145], v193 offset:2048
	ds_read_b128 v[152:155], v193 offset:3072
	ds_read_b128 v[156:159], v194
	ds_read_b128 v[160:163], v194 offset:1024
	ds_read_b128 v[164:167], v194 offset:2048
	ds_read_b128 v[168:171], v194 offset:3072
	s_add_i32 s47, s6, 2
	s_add_u32 s48, s54, s58
	s_addc_u32 s49, s55, s59
	s_mov_b32 s98, s48
	s_mov_b32 s99, s49
	s_add_u32 s48, s48, 0x100
	s_addc_u32 s49, s49, 0
	s_add_u32 s50, s45, s58
	s_addc_u32 s51, s46, s59
	s_cmp_eq_u32 s44, s6
	s_cselect_b32 s6, s39, s82
	s_cselect_b32 s61, s31, s49
	s_cselect_b32 s60, s30, s48
	s_cselect_b32 s62, s80, s56
	s_cselect_b32 s49, s41, s51
	s_cselect_b32 s48, s40, s50
	s_add_i32 m0, s43, 0xc000
	ds_read_b128 v[172:175], v195
	ds_read_b128 v[176:179], v195 offset:1024
	ds_read_b128 v[180:183], v195 offset:2048
	ds_read_b128 v[196:199], v195 offset:3072
	ds_read_b128 v[200:203], v195 offset:4096
	ds_read_b128 v[204:207], v195 offset:5120
	ds_read_b128 v[208:211], v195 offset:6144
	ds_read_b128 v[212:215], v195 offset:7168
	global_load_lds_dwordx4 v224, s[98:99]
	s_add_i32 m0, s43, 0xe000
	s_nop 0
	global_load_lds_dwordx4 v226, s[98:99]
	s_waitcnt vmcnt(8)
	s_waitcnt lgkmcnt(0)
	s_barrier
	s_waitcnt lgkmcnt(0)
	v_mfma_f32_16x16x32_bf16 v[126:129], v[134:137], v[172:175], 0
	v_mfma_f32_16x16x32_bf16 v[118:121], v[142:145], v[172:175], 0
	v_mfma_f32_16x16x32_bf16 v[110:113], v[134:137], v[180:183], 0
	v_mfma_f32_16x16x32_bf16 v[102:105], v[142:145], v[180:183], 0
	v_mfma_f32_16x16x32_bf16 v[94:97], v[134:137], v[200:203], 0
	v_mfma_f32_16x16x32_bf16 v[86:89], v[142:145], v[200:203], 0
	v_mfma_f32_16x16x32_bf16 v[78:81], v[134:137], v[208:211], 0
	v_mfma_f32_16x16x32_bf16 v[70:73], v[142:145], v[208:211], 0
	v_mfma_f32_16x16x32_bf16 v[126:129], v[138:141], v[176:179], v[126:129]
	v_mfma_f32_16x16x32_bf16 v[118:121], v[152:155], v[176:179], v[118:121]
	v_mfma_f32_16x16x32_bf16 v[110:113], v[138:141], v[196:199], v[110:113]
	v_mfma_f32_16x16x32_bf16 v[102:105], v[152:155], v[196:199], v[102:105]
	v_mfma_f32_16x16x32_bf16 v[94:97], v[138:141], v[204:207], v[94:97]
	v_mfma_f32_16x16x32_bf16 v[86:89], v[152:155], v[204:207], v[86:89]
	v_mfma_f32_16x16x32_bf16 v[78:81], v[138:141], v[212:215], v[78:81]
	v_mfma_f32_16x16x32_bf16 v[70:73], v[152:155], v[212:215], v[70:73]
	v_mfma_f32_16x16x32_bf16 v[122:125], v[156:159], v[172:175], 0
	v_mfma_f32_16x16x32_bf16 v[114:117], v[164:167], v[172:175], 0
	v_mfma_f32_16x16x32_bf16 v[106:109], v[156:159], v[180:183], 0
	v_mfma_f32_16x16x32_bf16 v[98:101], v[164:167], v[180:183], 0
	v_mfma_f32_16x16x32_bf16 v[90:93], v[156:159], v[200:203], 0
	v_mfma_f32_16x16x32_bf16 v[82:85], v[164:167], v[200:203], 0
	v_mfma_f32_16x16x32_bf16 v[74:77], v[156:159], v[208:211], 0
	v_mfma_f32_16x16x32_bf16 v[66:69], v[164:167], v[208:211], 0
	v_mfma_f32_16x16x32_bf16 v[122:125], v[160:163], v[176:179], v[122:125]
	v_mfma_f32_16x16x32_bf16 v[114:117], v[168:171], v[176:179], v[114:117]
	v_mfma_f32_16x16x32_bf16 v[106:109], v[160:163], v[196:199], v[106:109]
	v_mfma_f32_16x16x32_bf16 v[98:101], v[168:171], v[196:199], v[98:101]
	v_mfma_f32_16x16x32_bf16 v[90:93], v[160:163], v[204:207], v[90:93]
	v_mfma_f32_16x16x32_bf16 v[82:85], v[168:171], v[204:207], v[82:85]
	v_mfma_f32_16x16x32_bf16 v[74:77], v[160:163], v[212:215], v[74:77]
	v_mfma_f32_16x16x32_bf16 v[66:69], v[168:171], v[212:215], v[66:69]
	s_barrier
	v_mad_u32_u24 v216, v185, s6, v146
	s_add_i32 s50, s74, s3
	s_mov_b32 m0, s50
	ds_read_b128 v[172:175], v195 offset:16384
	ds_read_b128 v[176:179], v195 offset:17408
	ds_read_b128 v[180:183], v195 offset:18432
	ds_read_b128 v[196:199], v195 offset:19456
	ds_read_b128 v[200:203], v195 offset:20480
	ds_read_b128 v[204:207], v195 offset:21504
	ds_read_b128 v[208:211], v195 offset:22528
	ds_read_b128 v[212:215], v195 offset:23552
	global_load_lds_dwordx4 v216, s[48:49]
	v_mad_u32_u24 v218, v187, s6, v146
	s_add_i32 m0, s50, 0x2000
	s_lshl_b64 s[50:51], s[6:7], 7
	s_mov_b64 s[98:99], s[48:49]
	s_add_u32 s48, s48, s50
	s_addc_u32 s49, s49, s51
	s_mov_b64 s[100:101], s[48:49]
	s_add_i32 s6, s75, s3
	global_load_lds_dwordx4 v218, s[98:99]
	s_mov_b32 m0, s6
	v_mad_u32_u24 v220, v184, s62, v146
	global_load_lds_dwordx4 v216, s[48:49]
	s_add_i32 m0, s6, 0x2000
	v_mad_u32_u24 v222, v186, s62, v146
	global_load_lds_dwordx4 v218, s[48:49]
	s_mov_b32 m0, s43
	s_nop 0
	global_load_lds_dwordx4 v220, s[60:61]
	s_mov_b32 m0, s65
	s_nop 0
	global_load_lds_dwordx4 v222, s[60:61]
	s_waitcnt vmcnt(8)
	s_waitcnt lgkmcnt(0)
	s_barrier
; #define PG8_STAGE(bufoff, gbase, RR, ld) do { _Pragma("unroll") for (int _i = 0; _i < 2; ++_i) \
;         __builtin_amdgcn_global_load_lds((const unsigned*)((const char*)(gbase) + (RR)[_i] * (ld) + C2[_i]), (LAS unsigned*)(lds + (bufoff) + ldsw + _i * 8192), 16, 0, 0); } while (0)
; #define PG8_LDA(dst, b, h) do { _Pragma("unroll") for (int m = 0; m < 4; ++m) _Pragma("unroll") for (int k = 0; k < 2; ++k) dst[m][k] = *(const LAS bf16x8*)(lds + PG8_SA(b, h) + aoff + m * 2048 + k * 1024); } while (0)
; #define PG8_LDB(dst, b, h) do { _Pragma("unroll") for (int n = 0; n < 2; ++n) _Pragma("unroll") for (int k = 0; k < 2; ++k) dst[n][k] = *(const LAS bf16x8*)(lds + PG8_SB(b, h) + boff + n * 2048 + k * 1024); } while (0)
; #define PG8_MMA(ai, bj, At, Bt) do { __builtin_amdgcn_s_setprio(1); _Pragma("unroll") for (int m = 0; m < 4; ++m) _Pragma("unroll") for (int n = 0; n < 2; ++n) _Pragma("unroll") for (int k = 0; k < 2; ++k) \
;         acc[ai][bj][m][n] = __builtin_amdgcn_mfma_f32_16x16x32_bf16(Bt[n][k], At[m][k], acc[ai][bj][m][n], 0, 0, 0); __builtin_amdgcn_s_setprio(0); } while (0)
; #define PG8_WAIT_V(n) asm volatile("s_waitcnt vmcnt(" #n ")" ::: "memory")
; #define PG8_WAIT_L(n) asm volatile("s_waitcnt lgkmcnt(" #n ")" ::: "memory")
; #define PG8_BAR __builtin_amdgcn_s_barrier()
; #define PG8_SCHED __builtin_amdgcn_sched_barrier(0)
; template <class Sched, class Epi>
; __device__ __forceinline__ void gemm_run(LAS unsigned char* lds, const Sched& S, const Epi& E) {
;     ...
;             PG8_WAIT_V(8); PG8_WAIT_L(0); PG8_BAR; PG8_MMA(1, 0, At, B0); PG8_MMA(1, 1, At, B1); PG8_BAR; PG8_SCHED;
;             PG8_LDB(B0, 1, 0); PG8_LDB(B1, 1, 1); PG8_SCHED; PG8_LDA(At, 1, 0); PG8_STAGE(PG8_SA(0, 1), a2 + (size_t)HALF * la2, RA, la2);
;             PG8_WAIT_V(8); PG8_WAIT_L(0); PG8_BAR; PG8_MMA(0, 0, At, B0); PG8_MMA(0, 1, At, B1); PG8_BAR; PG8_SCHED;
	s_waitcnt lgkmcnt(0)
	v_mfma_f32_16x16x32_bf16 v[62:65], v[134:137], v[172:175], 0
	v_mfma_f32_16x16x32_bf16 v[54:57], v[142:145], v[172:175], 0
	v_mfma_f32_16x16x32_bf16 v[46:49], v[134:137], v[180:183], 0
	v_mfma_f32_16x16x32_bf16 v[38:41], v[142:145], v[180:183], 0
	v_mfma_f32_16x16x32_bf16 v[30:33], v[134:137], v[200:203], 0
	v_mfma_f32_16x16x32_bf16 v[22:25], v[142:145], v[200:203], 0
	v_mfma_f32_16x16x32_bf16 v[14:17], v[134:137], v[208:211], 0
	v_mfma_f32_16x16x32_bf16 v[6:9], v[142:145], v[208:211], 0
	v_mfma_f32_16x16x32_bf16 v[62:65], v[138:141], v[176:179], v[62:65]
	v_mfma_f32_16x16x32_bf16 v[54:57], v[152:155], v[176:179], v[54:57]
	v_mfma_f32_16x16x32_bf16 v[46:49], v[138:141], v[196:199], v[46:49]
	v_mfma_f32_16x16x32_bf16 v[38:41], v[152:155], v[196:199], v[38:41]
	v_mfma_f32_16x16x32_bf16 v[30:33], v[138:141], v[204:207], v[30:33]
	v_mfma_f32_16x16x32_bf16 v[22:25], v[152:155], v[204:207], v[22:25]
	v_mfma_f32_16x16x32_bf16 v[14:17], v[138:141], v[212:215], v[14:17]
	v_mfma_f32_16x16x32_bf16 v[6:9], v[152:155], v[212:215], v[6:9]
	v_mfma_f32_16x16x32_bf16 v[58:61], v[156:159], v[172:175], 0
	v_mfma_f32_16x16x32_bf16 v[50:53], v[164:167], v[172:175], 0
	v_mfma_f32_16x16x32_bf16 v[42:45], v[156:159], v[180:183], 0
	v_mfma_f32_16x16x32_bf16 v[34:37], v[164:167], v[180:183], 0
	v_mfma_f32_16x16x32_bf16 v[26:29], v[156:159], v[200:203], 0
	v_mfma_f32_16x16x32_bf16 v[18:21], v[164:167], v[200:203], 0
	v_mfma_f32_16x16x32_bf16 v[10:13], v[156:159], v[208:211], 0
	v_mfma_f32_16x16x32_bf16 v[2:5], v[164:167], v[208:211], 0
	v_mfma_f32_16x16x32_bf16 v[58:61], v[160:163], v[176:179], v[58:61]
	v_mfma_f32_16x16x32_bf16 v[50:53], v[168:171], v[176:179], v[50:53]
	v_mfma_f32_16x16x32_bf16 v[42:45], v[160:163], v[196:199], v[42:45]
	v_mfma_f32_16x16x32_bf16 v[34:37], v[168:171], v[196:199], v[34:37]
	v_mfma_f32_16x16x32_bf16 v[26:29], v[160:163], v[204:207], v[26:29]
	v_mfma_f32_16x16x32_bf16 v[18:21], v[168:171], v[204:207], v[18:21]
	v_mfma_f32_16x16x32_bf16 v[10:13], v[160:163], v[212:215], v[10:13]
	v_mfma_f32_16x16x32_bf16 v[2:5], v[168:171], v[212:215], v[2:5]
	s_barrier
	s_add_i32 s6, 0, 0x18000
	s_add_i32 s50, 0, 0x1c000
	ds_read_b128 v[134:137], v193 offset:32768
	ds_read_b128 v[138:141], v193 offset:33792
	ds_read_b128 v[142:145], v193 offset:34816
	ds_read_b128 v[152:155], v193 offset:35840
	ds_read_b128 v[156:159], v194 offset:32768
	ds_read_b128 v[160:163], v194 offset:33792
	ds_read_b128 v[164:167], v194 offset:34816
	ds_read_b128 v[168:171], v194 offset:35840
	s_mov_b32 s63, s7
	s_lshl_b64 s[48:49], s[62:63], 7
	s_add_u32 s48, s60, s48
	s_addc_u32 s49, s61, s49
	s_mov_b32 m0, s66
	ds_read_b128 v[172:175], v195 offset:32768
	ds_read_b128 v[176:179], v195 offset:33792
	ds_read_b128 v[180:183], v195 offset:34816
	ds_read_b128 v[196:199], v195 offset:35840
	ds_read_b128 v[200:203], v195 offset:36864
	ds_read_b128 v[204:207], v195 offset:37888
	ds_read_b128 v[208:211], v195 offset:38912
	ds_read_b128 v[212:215], v195 offset:39936
	global_load_lds_dwordx4 v220, s[48:49]
	s_mov_b32 m0, s67
	s_nop 0
	global_load_lds_dwordx4 v222, s[48:49]
	s_waitcnt vmcnt(8)
	s_waitcnt lgkmcnt(0)
	s_barrier
	s_waitcnt lgkmcnt(0)
	v_mfma_f32_16x16x32_bf16 v[126:129], v[134:137], v[172:175], v[126:129]
	v_mfma_f32_16x16x32_bf16 v[118:121], v[142:145], v[172:175], v[118:121]
	v_mfma_f32_16x16x32_bf16 v[110:113], v[134:137], v[180:183], v[110:113]
	v_mfma_f32_16x16x32_bf16 v[102:105], v[142:145], v[180:183], v[102:105]
	v_mfma_f32_16x16x32_bf16 v[94:97], v[134:137], v[200:203], v[94:97]
	v_mfma_f32_16x16x32_bf16 v[86:89], v[142:145], v[200:203], v[86:89]
	v_mfma_f32_16x16x32_bf16 v[78:81], v[134:137], v[208:211], v[78:81]
	v_mfma_f32_16x16x32_bf16 v[70:73], v[142:145], v[208:211], v[70:73]
	v_mfma_f32_16x16x32_bf16 v[126:129], v[138:141], v[176:179], v[126:129]
	v_mfma_f32_16x16x32_bf16 v[118:121], v[152:155], v[176:179], v[118:121]
	v_mfma_f32_16x16x32_bf16 v[110:113], v[138:141], v[196:199], v[110:113]
	v_mfma_f32_16x16x32_bf16 v[102:105], v[152:155], v[196:199], v[102:105]
	v_mfma_f32_16x16x32_bf16 v[94:97], v[138:141], v[204:207], v[94:97]
	v_mfma_f32_16x16x32_bf16 v[86:89], v[152:155], v[204:207], v[86:89]
	v_mfma_f32_16x16x32_bf16 v[78:81], v[138:141], v[212:215], v[78:81]
	v_mfma_f32_16x16x32_bf16 v[70:73], v[152:155], v[212:215], v[70:73]
	v_mfma_f32_16x16x32_bf16 v[122:125], v[156:159], v[172:175], v[122:125]
	v_mfma_f32_16x16x32_bf16 v[114:117], v[164:167], v[172:175], v[114:117]
	v_mfma_f32_16x16x32_bf16 v[106:109], v[156:159], v[180:183], v[106:109]
	v_mfma_f32_16x16x32_bf16 v[98:101], v[164:167], v[180:183], v[98:101]
	v_mfma_f32_16x16x32_bf16 v[90:93], v[156:159], v[200:203], v[90:93]
	v_mfma_f32_16x16x32_bf16 v[82:85], v[164:167], v[200:203], v[82:85]
	v_mfma_f32_16x16x32_bf16 v[74:77], v[156:159], v[208:211], v[74:77]
	v_mfma_f32_16x16x32_bf16 v[66:69], v[164:167], v[208:211], v[66:69]
	v_mfma_f32_16x16x32_bf16 v[122:125], v[160:163], v[176:179], v[122:125]
	v_mfma_f32_16x16x32_bf16 v[114:117], v[168:171], v[176:179], v[114:117]
	v_mfma_f32_16x16x32_bf16 v[106:109], v[160:163], v[196:199], v[106:109]
	v_mfma_f32_16x16x32_bf16 v[98:101], v[168:171], v[196:199], v[98:101]
	v_mfma_f32_16x16x32_bf16 v[90:93], v[160:163], v[204:207], v[90:93]
	v_mfma_f32_16x16x32_bf16 v[82:85], v[168:171], v[204:207], v[82:85]
	v_mfma_f32_16x16x32_bf16 v[74:77], v[160:163], v[212:215], v[74:77]
	v_mfma_f32_16x16x32_bf16 v[66:69], v[168:171], v[212:215], v[66:69]
	s_barrier
; #define PG8_STAGE(bufoff, gbase, RR, ld) do { _Pragma("unroll") for (int _i = 0; _i < 2; ++_i) \
;         __builtin_amdgcn_global_load_lds((const unsigned*)((const char*)(gbase) + (RR)[_i] * (ld) + C2[_i]), (LAS unsigned*)(lds + (bufoff) + ldsw + _i * 8192), 16, 0, 0); } while (0)
; #define PG8_LDA(dst, b, h) do { _Pragma("unroll") for (int m = 0; m < 4; ++m) _Pragma("unroll") for (int k = 0; k < 2; ++k) dst[m][k] = *(const LAS bf16x8*)(lds + PG8_SA(b, h) + aoff + m * 2048 + k * 1024); } while (0)
; #define PG8_LDB(dst, b, h) do { _Pragma("unroll") for (int n = 0; n < 2; ++n) _Pragma("unroll") for (int k = 0; k < 2; ++k) dst[n][k] = *(const LAS bf16x8*)(lds + PG8_SB(b, h) + boff + n * 2048 + k * 1024); } while (0)
; #define PG8_MMA(ai, bj, At, Bt) do { __builtin_amdgcn_s_setprio(1); _Pragma("unroll") for (int m = 0; m < 4; ++m) _Pragma("unroll") for (int n = 0; n < 2; ++n) _Pragma("unroll") for (int k = 0; k < 2; ++k) \
;         acc[ai][bj][m][n] = __builtin_amdgcn_mfma_f32_16x16x32_bf16(Bt[n][k], At[m][k], acc[ai][bj][m][n], 0, 0, 0); __builtin_amdgcn_s_setprio(0); } while (0)
; #define PG8_WAIT_V(n) asm volatile("s_waitcnt vmcnt(" #n ")" ::: "memory")
; #define PG8_WAIT_L(n) asm volatile("s_waitcnt lgkmcnt(" #n ")" ::: "memory")
; #define PG8_BAR __builtin_amdgcn_s_barrier()
; #define PG8_SCHED __builtin_amdgcn_sched_barrier(0)
; template <class Sched, class Epi>
; __device__ __forceinline__ void gemm_run(LAS unsigned char* lds, const Sched& S, const Epi& E) {
;     ...
;             PG8_LDB(B0, 0, 0); PG8_LDB(B1, 0, 1); PG8_SCHED; PG8_LDA(At, 0, 0); PG8_STAGE(PG8_SA(1, 1), a1 + (size_t)HALF * lda, RA, lda);
;     ...
;             PG8_LDA(At, 1, 1); PG8_STAGE(PG8_SB(1, 0), b3, RB, lb2); PG8_STAGE(PG8_SB(1, 1), b3 + (size_t)HALF * lb2, RB, lb2); PG8_STAGE(PG8_SA(1, 0), a3, RA, la2);
;             PG8_WAIT_V(8); PG8_WAIT_L(0); PG8_BAR; PG8_MMA(1, 0, At, B0); PG8_MMA(1, 1, At, B1); PG8_BAR; PG8_SCHED;
	s_add_i32 s6, s6, s3
	s_add_u32 s98, s98, 0x80
	s_addc_u32 s99, s99, 0
	s_mov_b32 m0, s6
	ds_read_b128 v[172:175], v195 offset:49152
	ds_read_b128 v[176:179], v195 offset:50176
	ds_read_b128 v[180:183], v195 offset:51200
	ds_read_b128 v[196:199], v195 offset:52224
	ds_read_b128 v[200:203], v195 offset:53248
	ds_read_b128 v[204:207], v195 offset:54272
	ds_read_b128 v[208:211], v195 offset:55296
	ds_read_b128 v[212:215], v195 offset:56320
	global_load_lds_dwordx4 v216, s[98:99]
	s_add_i32 m0, s6, 0x2000
	s_add_i32 s6, s50, s3
	global_load_lds_dwordx4 v218, s[98:99]
	s_add_u32 s100, s100, 0x80
	s_addc_u32 s101, s101, 0
	s_mov_b32 m0, s6
	s_nop 0
	global_load_lds_dwordx4 v216, s[100:101]
	s_add_i32 m0, s6, 0x2000
	s_nop 0
	global_load_lds_dwordx4 v218, s[100:101]
	s_add_u32 s48, s60, 0x80
	s_addc_u32 s49, s61, 0
	s_mov_b32 m0, s68
	s_nop 0
	global_load_lds_dwordx4 v220, s[48:49]
	s_mov_b32 m0, s69
	s_nop 0
	global_load_lds_dwordx4 v222, s[48:49]
	s_waitcnt vmcnt(8)
	s_waitcnt lgkmcnt(0)
	s_barrier
	s_waitcnt lgkmcnt(0)
	v_mfma_f32_16x16x32_bf16 v[62:65], v[134:137], v[172:175], v[62:65]
	v_mfma_f32_16x16x32_bf16 v[54:57], v[142:145], v[172:175], v[54:57]
	v_mfma_f32_16x16x32_bf16 v[46:49], v[134:137], v[180:183], v[46:49]
	v_mfma_f32_16x16x32_bf16 v[38:41], v[142:145], v[180:183], v[38:41]
	v_mfma_f32_16x16x32_bf16 v[30:33], v[134:137], v[200:203], v[30:33]
	v_mfma_f32_16x16x32_bf16 v[22:25], v[142:145], v[200:203], v[22:25]
	v_mfma_f32_16x16x32_bf16 v[14:17], v[134:137], v[208:211], v[14:17]
	v_mfma_f32_16x16x32_bf16 v[6:9], v[142:145], v[208:211], v[6:9]
	v_mfma_f32_16x16x32_bf16 v[62:65], v[138:141], v[176:179], v[62:65]
	v_mfma_f32_16x16x32_bf16 v[54:57], v[152:155], v[176:179], v[54:57]
	v_mfma_f32_16x16x32_bf16 v[46:49], v[138:141], v[196:199], v[46:49]
	v_mfma_f32_16x16x32_bf16 v[38:41], v[152:155], v[196:199], v[38:41]
	v_mfma_f32_16x16x32_bf16 v[30:33], v[138:141], v[204:207], v[30:33]
	v_mfma_f32_16x16x32_bf16 v[22:25], v[152:155], v[204:207], v[22:25]
	v_mfma_f32_16x16x32_bf16 v[14:17], v[138:141], v[212:215], v[14:17]
	v_mfma_f32_16x16x32_bf16 v[6:9], v[152:155], v[212:215], v[6:9]
	v_mfma_f32_16x16x32_bf16 v[58:61], v[156:159], v[172:175], v[58:61]
	v_mfma_f32_16x16x32_bf16 v[50:53], v[164:167], v[172:175], v[50:53]
	v_mfma_f32_16x16x32_bf16 v[42:45], v[156:159], v[180:183], v[42:45]
	v_mfma_f32_16x16x32_bf16 v[34:37], v[164:167], v[180:183], v[34:37]
	v_mfma_f32_16x16x32_bf16 v[26:29], v[156:159], v[200:203], v[26:29]
	v_mfma_f32_16x16x32_bf16 v[18:21], v[164:167], v[200:203], v[18:21]
	v_mfma_f32_16x16x32_bf16 v[10:13], v[156:159], v[208:211], v[10:13]
	v_mfma_f32_16x16x32_bf16 v[2:5], v[164:167], v[208:211], v[2:5]
	v_mfma_f32_16x16x32_bf16 v[58:61], v[160:163], v[176:179], v[58:61]
	v_mfma_f32_16x16x32_bf16 v[50:53], v[168:171], v[176:179], v[50:53]
	v_mfma_f32_16x16x32_bf16 v[42:45], v[160:163], v[196:199], v[42:45]
	v_mfma_f32_16x16x32_bf16 v[34:37], v[168:171], v[196:199], v[34:37]
	v_mfma_f32_16x16x32_bf16 v[26:29], v[160:163], v[204:207], v[26:29]
	v_mfma_f32_16x16x32_bf16 v[18:21], v[168:171], v[204:207], v[18:21]
	v_mfma_f32_16x16x32_bf16 v[10:13], v[160:163], v[212:215], v[10:13]
	v_mfma_f32_16x16x32_bf16 v[2:5], v[168:171], v[212:215], v[2:5]
	s_barrier
	s_add_u32 s58, s58, 0x100
	s_addc_u32 s59, s59, 0
	s_cmp_ge_i32 s47, s81
	s_mov_b32 s6, s47
	s_cbranch_scc0 .LBB0_806
	.p2align 6
.LBB0_806:
	ds_read_b128 v[134:137], v193
	ds_read_b128 v[138:141], v193 offset:1024
	ds_read_b128 v[142:145], v193 offset:2048
	ds_read_b128 v[152:155], v193 offset:3072
	ds_read_b128 v[156:159], v194
	ds_read_b128 v[160:163], v194 offset:1024
	ds_read_b128 v[164:167], v194 offset:2048
	ds_read_b128 v[168:171], v194 offset:3072
	s_add_i32 s47, s6, 2
	s_add_u32 s48, s54, s58
	s_addc_u32 s49, s55, s59
	s_mov_b32 s98, s48
	s_mov_b32 s99, s49
	s_add_u32 s48, s48, 0x100
	s_addc_u32 s49, s49, 0
	s_add_u32 s50, s45, s58
	s_addc_u32 s51, s46, s59
	s_cmp_eq_u32 s44, s6
	s_cselect_b32 s6, s39, s82
	s_cselect_b32 s61, s31, s49
	s_cselect_b32 s60, s30, s48
	s_cselect_b32 s62, s80, s56
	s_cselect_b32 s49, s41, s51
	s_cselect_b32 s48, s40, s50
	s_add_i32 m0, s43, 0xc000
	ds_read_b128 v[172:175], v195
	ds_read_b128 v[176:179], v195 offset:1024
	ds_read_b128 v[180:183], v195 offset:2048
	ds_read_b128 v[196:199], v195 offset:3072
	ds_read_b128 v[200:203], v195 offset:4096
	ds_read_b128 v[204:207], v195 offset:5120
	ds_read_b128 v[208:211], v195 offset:6144
	ds_read_b128 v[212:215], v195 offset:7168
	global_load_lds_dwordx4 v224, s[98:99]
	s_add_i32 m0, s43, 0xe000
	s_nop 0
	global_load_lds_dwordx4 v226, s[98:99]
	s_waitcnt vmcnt(8)
	s_waitcnt lgkmcnt(0)
	s_barrier
; #define PG8_STAGE(bufoff, gbase, RR, ld) do { _Pragma("unroll") for (int _i = 0; _i < 2; ++_i) \
;         __builtin_amdgcn_global_load_lds((const unsigned*)((const char*)(gbase) + (RR)[_i] * (ld) + C2[_i]), (LAS unsigned*)(lds + (bufoff) + ldsw + _i * 8192), 16, 0, 0); } while (0)
; #define PG8_LDA(dst, b, h) do { _Pragma("unroll") for (int m = 0; m < 4; ++m) _Pragma("unroll") for (int k = 0; k < 2; ++k) dst[m][k] = *(const LAS bf16x8*)(lds + PG8_SA(b, h) + aoff + m * 2048 + k * 1024); } while (0)
; #define PG8_LDB(dst, b, h) do { _Pragma("unroll") for (int n = 0; n < 2; ++n) _Pragma("unroll") for (int k = 0; k < 2; ++k) dst[n][k] = *(const LAS bf16x8*)(lds + PG8_SB(b, h) + boff + n * 2048 + k * 1024); } while (0)
; #define PG8_MMA(ai, bj, At, Bt) do { __builtin_amdgcn_s_setprio(1); _Pragma("unroll") for (int m = 0; m < 4; ++m) _Pragma("unroll") for (int n = 0; n < 2; ++n) _Pragma("unroll") for (int k = 0; k < 2; ++k) \
;         acc[ai][bj][m][n] = __builtin_amdgcn_mfma_f32_16x16x32_bf16(Bt[n][k], At[m][k], acc[ai][bj][m][n], 0, 0, 0); __builtin_amdgcn_s_setprio(0); } while (0)
; #define PG8_WAIT_V(n) asm volatile("s_waitcnt vmcnt(" #n ")" ::: "memory")
; #define PG8_WAIT_L(n) asm volatile("s_waitcnt lgkmcnt(" #n ")" ::: "memory")
; #define PG8_BAR __builtin_amdgcn_s_barrier()
; #define PG8_SCHED __builtin_amdgcn_sched_barrier(0)
; template <class Sched, class Epi>
; __device__ __forceinline__ void gemm_run(LAS unsigned char* lds, const Sched& S, const Epi& E) {
;     ...
;             PG8_WAIT_V(8); PG8_WAIT_L(0); PG8_BAR; PG8_MMA(0, 0, At, B0); PG8_MMA(0, 1, At, B1); PG8_BAR; PG8_SCHED;
;             PG8_LDA(At, 0, 1); PG8_STAGE(PG8_SB(0, 0), b2, RB, lb2); PG8_STAGE(PG8_SB(0, 1), b2 + (size_t)HALF * lb2, RB, lb2); PG8_STAGE(PG8_SA(0, 0), a2, RA, la2);
;             PG8_WAIT_V(8); PG8_WAIT_L(0); PG8_BAR; PG8_MMA(1, 0, At, B0); PG8_MMA(1, 1, At, B1); PG8_BAR; PG8_SCHED;
;             PG8_LDB(B0, 1, 0); PG8_LDB(B1, 1, 1); PG8_SCHED; PG8_LDA(At, 1, 0); PG8_STAGE(PG8_SA(0, 1), a2 + (size_t)HALF * la2, RA, la2);
	s_waitcnt lgkmcnt(0)
	v_mfma_f32_16x16x32_bf16 v[126:129], v[134:137], v[172:175], v[126:129]
	v_mfma_f32_16x16x32_bf16 v[118:121], v[142:145], v[172:175], v[118:121]
	v_mfma_f32_16x16x32_bf16 v[110:113], v[134:137], v[180:183], v[110:113]
	v_mfma_f32_16x16x32_bf16 v[102:105], v[142:145], v[180:183], v[102:105]
	v_mfma_f32_16x16x32_bf16 v[94:97], v[134:137], v[200:203], v[94:97]
	v_mfma_f32_16x16x32_bf16 v[86:89], v[142:145], v[200:203], v[86:89]
	v_mfma_f32_16x16x32_bf16 v[78:81], v[134:137], v[208:211], v[78:81]
	v_mfma_f32_16x16x32_bf16 v[70:73], v[142:145], v[208:211], v[70:73]
	v_mfma_f32_16x16x32_bf16 v[126:129], v[138:141], v[176:179], v[126:129]
	v_mfma_f32_16x16x32_bf16 v[118:121], v[152:155], v[176:179], v[118:121]
	v_mfma_f32_16x16x32_bf16 v[110:113], v[138:141], v[196:199], v[110:113]
	v_mfma_f32_16x16x32_bf16 v[102:105], v[152:155], v[196:199], v[102:105]
	v_mfma_f32_16x16x32_bf16 v[94:97], v[138:141], v[204:207], v[94:97]
	v_mfma_f32_16x16x32_bf16 v[86:89], v[152:155], v[204:207], v[86:89]
	v_mfma_f32_16x16x32_bf16 v[78:81], v[138:141], v[212:215], v[78:81]
	v_mfma_f32_16x16x32_bf16 v[70:73], v[152:155], v[212:215], v[70:73]
	v_mfma_f32_16x16x32_bf16 v[122:125], v[156:159], v[172:175], v[122:125]
	v_mfma_f32_16x16x32_bf16 v[114:117], v[164:167], v[172:175], v[114:117]
	v_mfma_f32_16x16x32_bf16 v[106:109], v[156:159], v[180:183], v[106:109]
	v_mfma_f32_16x16x32_bf16 v[98:101], v[164:167], v[180:183], v[98:101]
	v_mfma_f32_16x16x32_bf16 v[90:93], v[156:159], v[200:203], v[90:93]
	v_mfma_f32_16x16x32_bf16 v[82:85], v[164:167], v[200:203], v[82:85]
	v_mfma_f32_16x16x32_bf16 v[74:77], v[156:159], v[208:211], v[74:77]
	v_mfma_f32_16x16x32_bf16 v[66:69], v[164:167], v[208:211], v[66:69]
	v_mfma_f32_16x16x32_bf16 v[122:125], v[160:163], v[176:179], v[122:125]
	v_mfma_f32_16x16x32_bf16 v[114:117], v[168:171], v[176:179], v[114:117]
	v_mfma_f32_16x16x32_bf16 v[106:109], v[160:163], v[196:199], v[106:109]
	v_mfma_f32_16x16x32_bf16 v[98:101], v[168:171], v[196:199], v[98:101]
	v_mfma_f32_16x16x32_bf16 v[90:93], v[160:163], v[204:207], v[90:93]
	v_mfma_f32_16x16x32_bf16 v[82:85], v[168:171], v[204:207], v[82:85]
	v_mfma_f32_16x16x32_bf16 v[74:77], v[160:163], v[212:215], v[74:77]
	v_mfma_f32_16x16x32_bf16 v[66:69], v[168:171], v[212:215], v[66:69]
	s_barrier
	v_mad_u32_u24 v216, v185, s6, v146
	s_add_i32 s50, s74, s3
	s_mov_b32 m0, s50
	ds_read_b128 v[172:175], v195 offset:16384
	ds_read_b128 v[176:179], v195 offset:17408
	ds_read_b128 v[180:183], v195 offset:18432
	ds_read_b128 v[196:199], v195 offset:19456
	ds_read_b128 v[200:203], v195 offset:20480
	ds_read_b128 v[204:207], v195 offset:21504
	ds_read_b128 v[208:211], v195 offset:22528
	ds_read_b128 v[212:215], v195 offset:23552
	global_load_lds_dwordx4 v216, s[48:49]
	v_mad_u32_u24 v218, v187, s6, v146
	s_add_i32 m0, s50, 0x2000
	s_lshl_b64 s[50:51], s[6:7], 7
	s_mov_b64 s[98:99], s[48:49]
	s_add_u32 s48, s48, s50
	s_addc_u32 s49, s49, s51
	s_mov_b64 s[100:101], s[48:49]
	s_add_i32 s6, s75, s3
	global_load_lds_dwordx4 v218, s[98:99]
	s_mov_b32 m0, s6
	v_mad_u32_u24 v220, v184, s62, v146
	global_load_lds_dwordx4 v216, s[48:49]
	s_add_i32 m0, s6, 0x2000
	v_mad_u32_u24 v222, v186, s62, v146
	global_load_lds_dwordx4 v218, s[48:49]
	s_mov_b32 m0, s43
	s_nop 0
	global_load_lds_dwordx4 v220, s[60:61]
	s_mov_b32 m0, s65
	s_nop 0
	global_load_lds_dwordx4 v222, s[60:61]
	s_waitcnt vmcnt(8)
	s_waitcnt lgkmcnt(0)
	s_barrier
	s_waitcnt lgkmcnt(0)
	v_mfma_f32_16x16x32_bf16 v[62:65], v[134:137], v[172:175], v[62:65]
	v_mfma_f32_16x16x32_bf16 v[54:57], v[142:145], v[172:175], v[54:57]
	v_mfma_f32_16x16x32_bf16 v[46:49], v[134:137], v[180:183], v[46:49]
	v_mfma_f32_16x16x32_bf16 v[38:41], v[142:145], v[180:183], v[38:41]
	v_mfma_f32_16x16x32_bf16 v[30:33], v[134:137], v[200:203], v[30:33]
	v_mfma_f32_16x16x32_bf16 v[22:25], v[142:145], v[200:203], v[22:25]
	v_mfma_f32_16x16x32_bf16 v[14:17], v[134:137], v[208:211], v[14:17]
	v_mfma_f32_16x16x32_bf16 v[6:9], v[142:145], v[208:211], v[6:9]
	v_mfma_f32_16x16x32_bf16 v[62:65], v[138:141], v[176:179], v[62:65]
	v_mfma_f32_16x16x32_bf16 v[54:57], v[152:155], v[176:179], v[54:57]
	v_mfma_f32_16x16x32_bf16 v[46:49], v[138:141], v[196:199], v[46:49]
	v_mfma_f32_16x16x32_bf16 v[38:41], v[152:155], v[196:199], v[38:41]
	v_mfma_f32_16x16x32_bf16 v[30:33], v[138:141], v[204:207], v[30:33]
	v_mfma_f32_16x16x32_bf16 v[22:25], v[152:155], v[204:207], v[22:25]
	v_mfma_f32_16x16x32_bf16 v[14:17], v[138:141], v[212:215], v[14:17]
	v_mfma_f32_16x16x32_bf16 v[6:9], v[152:155], v[212:215], v[6:9]
	v_mfma_f32_16x16x32_bf16 v[58:61], v[156:159], v[172:175], v[58:61]
	v_mfma_f32_16x16x32_bf16 v[50:53], v[164:167], v[172:175], v[50:53]
	v_mfma_f32_16x16x32_bf16 v[42:45], v[156:159], v[180:183], v[42:45]
	v_mfma_f32_16x16x32_bf16 v[34:37], v[164:167], v[180:183], v[34:37]
	v_mfma_f32_16x16x32_bf16 v[26:29], v[156:159], v[200:203], v[26:29]
	v_mfma_f32_16x16x32_bf16 v[18:21], v[164:167], v[200:203], v[18:21]
	v_mfma_f32_16x16x32_bf16 v[10:13], v[156:159], v[208:211], v[10:13]
	v_mfma_f32_16x16x32_bf16 v[2:5], v[164:167], v[208:211], v[2:5]
	v_mfma_f32_16x16x32_bf16 v[58:61], v[160:163], v[176:179], v[58:61]
	v_mfma_f32_16x16x32_bf16 v[50:53], v[168:171], v[176:179], v[50:53]
	v_mfma_f32_16x16x32_bf16 v[42:45], v[160:163], v[196:199], v[42:45]
	v_mfma_f32_16x16x32_bf16 v[34:37], v[168:171], v[196:199], v[34:37]
	v_mfma_f32_16x16x32_bf16 v[26:29], v[160:163], v[204:207], v[26:29]
	v_mfma_f32_16x16x32_bf16 v[18:21], v[168:171], v[204:207], v[18:21]
	v_mfma_f32_16x16x32_bf16 v[10:13], v[160:163], v[212:215], v[10:13]
	v_mfma_f32_16x16x32_bf16 v[2:5], v[168:171], v[212:215], v[2:5]
	s_barrier
; #define PG8_STAGE(bufoff, gbase, RR, ld) do { _Pragma("unroll") for (int _i = 0; _i < 2; ++_i) \
;         __builtin_amdgcn_global_load_lds((const unsigned*)((const char*)(gbase) + (RR)[_i] * (ld) + C2[_i]), (LAS unsigned*)(lds + (bufoff) + ldsw + _i * 8192), 16, 0, 0); } while (0)
; #define PG8_LDA(dst, b, h) do { _Pragma("unroll") for (int m = 0; m < 4; ++m) _Pragma("unroll") for (int k = 0; k < 2; ++k) dst[m][k] = *(const LAS bf16x8*)(lds + PG8_SA(b, h) + aoff + m * 2048 + k * 1024); } while (0)
; #define PG8_LDB(dst, b, h) do { _Pragma("unroll") for (int n = 0; n < 2; ++n) _Pragma("unroll") for (int k = 0; k < 2; ++k) dst[n][k] = *(const LAS bf16x8*)(lds + PG8_SB(b, h) + boff + n * 2048 + k * 1024); } while (0)
; #define PG8_MMA(ai, bj, At, Bt) do { __builtin_amdgcn_s_setprio(1); _Pragma("unroll") for (int m = 0; m < 4; ++m) _Pragma("unroll") for (int n = 0; n < 2; ++n) _Pragma("unroll") for (int k = 0; k < 2; ++k) \
;         acc[ai][bj][m][n] = __builtin_amdgcn_mfma_f32_16x16x32_bf16(Bt[n][k], At[m][k], acc[ai][bj][m][n], 0, 0, 0); __builtin_amdgcn_s_setprio(0); } while (0)
; #define PG8_WAIT_V(n) asm volatile("s_waitcnt vmcnt(" #n ")" ::: "memory")
; #define PG8_WAIT_L(n) asm volatile("s_waitcnt lgkmcnt(" #n ")" ::: "memory")
; #define PG8_BAR __builtin_amdgcn_s_barrier()
; #define PG8_SCHED __builtin_amdgcn_sched_barrier(0)
; template <class Sched, class Epi>
; __device__ __forceinline__ void gemm_run(LAS unsigned char* lds, const Sched& S, const Epi& E) {
;     ...
;             PG8_LDB(B0, 1, 0); PG8_LDB(B1, 1, 1); PG8_SCHED; PG8_LDA(At, 1, 0); PG8_STAGE(PG8_SA(0, 1), a2 + (size_t)HALF * la2, RA, la2);
;             PG8_WAIT_V(8); PG8_WAIT_L(0); PG8_BAR; PG8_MMA(0, 0, At, B0); PG8_MMA(0, 1, At, B1); PG8_BAR; PG8_SCHED;
;             PG8_LDA(At, 1, 1); PG8_STAGE(PG8_SB(1, 0), b3, RB, lb2); PG8_STAGE(PG8_SB(1, 1), b3 + (size_t)HALF * lb2, RB, lb2); PG8_STAGE(PG8_SA(1, 0), a3, RA, la2);
;             PG8_WAIT_V(8); PG8_WAIT_L(0); PG8_BAR; PG8_MMA(1, 0, At, B0); PG8_MMA(1, 1, At, B1); PG8_BAR; PG8_SCHED;
;         }
;         if (wr == 0) PG8_BAR;
	s_add_i32 s6, 0, 0x18000
	s_add_i32 s50, 0, 0x1c000
	ds_read_b128 v[134:137], v193 offset:32768
	ds_read_b128 v[138:141], v193 offset:33792
	ds_read_b128 v[142:145], v193 offset:34816
	ds_read_b128 v[152:155], v193 offset:35840
	ds_read_b128 v[156:159], v194 offset:32768
	ds_read_b128 v[160:163], v194 offset:33792
	ds_read_b128 v[164:167], v194 offset:34816
	ds_read_b128 v[168:171], v194 offset:35840
	s_mov_b32 s63, s7
	s_lshl_b64 s[48:49], s[62:63], 7
	s_add_u32 s48, s60, s48
	s_addc_u32 s49, s61, s49
	s_mov_b32 m0, s66
	ds_read_b128 v[172:175], v195 offset:32768
	ds_read_b128 v[176:179], v195 offset:33792
	ds_read_b128 v[180:183], v195 offset:34816
	ds_read_b128 v[196:199], v195 offset:35840
	ds_read_b128 v[200:203], v195 offset:36864
	ds_read_b128 v[204:207], v195 offset:37888
	ds_read_b128 v[208:211], v195 offset:38912
	ds_read_b128 v[212:215], v195 offset:39936
	global_load_lds_dwordx4 v220, s[48:49]
	s_mov_b32 m0, s67
	s_nop 0
	global_load_lds_dwordx4 v222, s[48:49]
	s_waitcnt vmcnt(8)
	s_waitcnt lgkmcnt(0)
	s_barrier
	s_waitcnt lgkmcnt(0)
	v_mfma_f32_16x16x32_bf16 v[126:129], v[134:137], v[172:175], v[126:129]
	v_mfma_f32_16x16x32_bf16 v[118:121], v[142:145], v[172:175], v[118:121]
	v_mfma_f32_16x16x32_bf16 v[110:113], v[134:137], v[180:183], v[110:113]
	v_mfma_f32_16x16x32_bf16 v[102:105], v[142:145], v[180:183], v[102:105]
	v_mfma_f32_16x16x32_bf16 v[94:97], v[134:137], v[200:203], v[94:97]
	v_mfma_f32_16x16x32_bf16 v[86:89], v[142:145], v[200:203], v[86:89]
	v_mfma_f32_16x16x32_bf16 v[78:81], v[134:137], v[208:211], v[78:81]
	v_mfma_f32_16x16x32_bf16 v[70:73], v[142:145], v[208:211], v[70:73]
	v_mfma_f32_16x16x32_bf16 v[126:129], v[138:141], v[176:179], v[126:129]
	v_mfma_f32_16x16x32_bf16 v[118:121], v[152:155], v[176:179], v[118:121]
	v_mfma_f32_16x16x32_bf16 v[110:113], v[138:141], v[196:199], v[110:113]
	v_mfma_f32_16x16x32_bf16 v[102:105], v[152:155], v[196:199], v[102:105]
	v_mfma_f32_16x16x32_bf16 v[94:97], v[138:141], v[204:207], v[94:97]
	v_mfma_f32_16x16x32_bf16 v[86:89], v[152:155], v[204:207], v[86:89]
	v_mfma_f32_16x16x32_bf16 v[78:81], v[138:141], v[212:215], v[78:81]
	v_mfma_f32_16x16x32_bf16 v[70:73], v[152:155], v[212:215], v[70:73]
	v_mfma_f32_16x16x32_bf16 v[122:125], v[156:159], v[172:175], v[122:125]
	v_mfma_f32_16x16x32_bf16 v[114:117], v[164:167], v[172:175], v[114:117]
	v_mfma_f32_16x16x32_bf16 v[106:109], v[156:159], v[180:183], v[106:109]
	v_mfma_f32_16x16x32_bf16 v[98:101], v[164:167], v[180:183], v[98:101]
	v_mfma_f32_16x16x32_bf16 v[90:93], v[156:159], v[200:203], v[90:93]
	v_mfma_f32_16x16x32_bf16 v[82:85], v[164:167], v[200:203], v[82:85]
	v_mfma_f32_16x16x32_bf16 v[74:77], v[156:159], v[208:211], v[74:77]
	v_mfma_f32_16x16x32_bf16 v[66:69], v[164:167], v[208:211], v[66:69]
	v_mfma_f32_16x16x32_bf16 v[122:125], v[160:163], v[176:179], v[122:125]
	v_mfma_f32_16x16x32_bf16 v[114:117], v[168:171], v[176:179], v[114:117]
	v_mfma_f32_16x16x32_bf16 v[106:109], v[160:163], v[196:199], v[106:109]
	v_mfma_f32_16x16x32_bf16 v[98:101], v[168:171], v[196:199], v[98:101]
	v_mfma_f32_16x16x32_bf16 v[90:93], v[160:163], v[204:207], v[90:93]
	v_mfma_f32_16x16x32_bf16 v[82:85], v[168:171], v[204:207], v[82:85]
	v_mfma_f32_16x16x32_bf16 v[74:77], v[160:163], v[212:215], v[74:77]
	v_mfma_f32_16x16x32_bf16 v[66:69], v[168:171], v[212:215], v[66:69]
	s_barrier
	s_add_i32 s6, s6, s3
	s_add_u32 s98, s98, 0x80
	s_addc_u32 s99, s99, 0
	s_mov_b32 m0, s6
	ds_read_b128 v[172:175], v195 offset:49152
	ds_read_b128 v[176:179], v195 offset:50176
	ds_read_b128 v[180:183], v195 offset:51200
	ds_read_b128 v[196:199], v195 offset:52224
	ds_read_b128 v[200:203], v195 offset:53248
	ds_read_b128 v[204:207], v195 offset:54272
	ds_read_b128 v[208:211], v195 offset:55296
	ds_read_b128 v[212:215], v195 offset:56320
	global_load_lds_dwordx4 v216, s[98:99]
	s_add_i32 m0, s6, 0x2000
	s_add_i32 s6, s50, s3
	global_load_lds_dwordx4 v218, s[98:99]
	s_add_u32 s100, s100, 0x80
	s_addc_u32 s101, s101, 0
	s_mov_b32 m0, s6
	s_nop 0
	global_load_lds_dwordx4 v216, s[100:101]
	s_add_i32 m0, s6, 0x2000
	s_nop 0
	global_load_lds_dwordx4 v218, s[100:101]
	s_add_u32 s48, s60, 0x80
	s_addc_u32 s49, s61, 0
	s_mov_b32 m0, s68
	s_nop 0
	global_load_lds_dwordx4 v220, s[48:49]
	s_mov_b32 m0, s69
	s_nop 0
	global_load_lds_dwordx4 v222, s[48:49]
	s_waitcnt vmcnt(8)
	s_waitcnt lgkmcnt(0)
	s_barrier
	s_waitcnt lgkmcnt(0)
	v_mfma_f32_16x16x32_bf16 v[62:65], v[134:137], v[172:175], v[62:65]
	v_mfma_f32_16x16x32_bf16 v[54:57], v[142:145], v[172:175], v[54:57]
	v_mfma_f32_16x16x32_bf16 v[46:49], v[134:137], v[180:183], v[46:49]
	v_mfma_f32_16x16x32_bf16 v[38:41], v[142:145], v[180:183], v[38:41]
	v_mfma_f32_16x16x32_bf16 v[30:33], v[134:137], v[200:203], v[30:33]
	v_mfma_f32_16x16x32_bf16 v[22:25], v[142:145], v[200:203], v[22:25]
	v_mfma_f32_16x16x32_bf16 v[14:17], v[134:137], v[208:211], v[14:17]
	v_mfma_f32_16x16x32_bf16 v[6:9], v[142:145], v[208:211], v[6:9]
	v_mfma_f32_16x16x32_bf16 v[62:65], v[138:141], v[176:179], v[62:65]
	v_mfma_f32_16x16x32_bf16 v[54:57], v[152:155], v[176:179], v[54:57]
	v_mfma_f32_16x16x32_bf16 v[46:49], v[138:141], v[196:199], v[46:49]
	v_mfma_f32_16x16x32_bf16 v[38:41], v[152:155], v[196:199], v[38:41]
	v_mfma_f32_16x16x32_bf16 v[30:33], v[138:141], v[204:207], v[30:33]
	v_mfma_f32_16x16x32_bf16 v[22:25], v[152:155], v[204:207], v[22:25]
	v_mfma_f32_16x16x32_bf16 v[14:17], v[138:141], v[212:215], v[14:17]
	v_mfma_f32_16x16x32_bf16 v[6:9], v[152:155], v[212:215], v[6:9]
	v_mfma_f32_16x16x32_bf16 v[58:61], v[156:159], v[172:175], v[58:61]
	v_mfma_f32_16x16x32_bf16 v[50:53], v[164:167], v[172:175], v[50:53]
	v_mfma_f32_16x16x32_bf16 v[42:45], v[156:159], v[180:183], v[42:45]
	v_mfma_f32_16x16x32_bf16 v[34:37], v[164:167], v[180:183], v[34:37]
	v_mfma_f32_16x16x32_bf16 v[26:29], v[156:159], v[200:203], v[26:29]
	v_mfma_f32_16x16x32_bf16 v[18:21], v[164:167], v[200:203], v[18:21]
	v_mfma_f32_16x16x32_bf16 v[10:13], v[156:159], v[208:211], v[10:13]
	v_mfma_f32_16x16x32_bf16 v[2:5], v[164:167], v[208:211], v[2:5]
	v_mfma_f32_16x16x32_bf16 v[58:61], v[160:163], v[176:179], v[58:61]
	v_mfma_f32_16x16x32_bf16 v[50:53], v[168:171], v[176:179], v[50:53]
	v_mfma_f32_16x16x32_bf16 v[42:45], v[160:163], v[196:199], v[42:45]
	v_mfma_f32_16x16x32_bf16 v[34:37], v[168:171], v[196:199], v[34:37]
	v_mfma_f32_16x16x32_bf16 v[26:29], v[160:163], v[204:207], v[26:29]
	v_mfma_f32_16x16x32_bf16 v[18:21], v[168:171], v[204:207], v[18:21]
	v_mfma_f32_16x16x32_bf16 v[10:13], v[160:163], v[212:215], v[10:13]
	v_mfma_f32_16x16x32_bf16 v[2:5], v[168:171], v[212:215], v[2:5]
	s_barrier
	s_add_u32 s58, s58, 0x100
	s_addc_u32 s59, s59, 0
	s_cmp_ge_i32 s47, s81
	s_mov_b32 s6, s47
	s_cbranch_scc0 .LBB0_806
	s_and_b64 vcc, exec, s[10:11]
	s_cbranch_vccz .LBB0_809
	s_barrier

; #define PG8_STAGE(bufoff, gbase, RR, ld) do { _Pragma("unroll") for (int _i = 0; _i < 2; ++_i) \
;         __builtin_amdgcn_global_load_lds((const unsigned*)((const char*)(gbase) + (RR)[_i] * (ld) + C2[_i]), (LAS unsigned*)(lds + (bufoff) + ldsw + _i * 8192), 16, 0, 0); } while (0)
; #define PG8_LDA(dst, b, h) do { _Pragma("unroll") for (int m = 0; m < 4; ++m) _Pragma("unroll") for (int k = 0; k < 2; ++k) dst[m][k] = *(const LAS bf16x8*)(lds + PG8_SA(b, h) + aoff + m * 2048 + k * 1024); } while (0)
; #define PG8_LDB(dst, b, h) do { _Pragma("unroll") for (int n = 0; n < 2; ++n) _Pragma("unroll") for (int k = 0; k < 2; ++k) dst[n][k] = *(const LAS bf16x8*)(lds + PG8_SB(b, h) + boff + n * 2048 + k * 1024); } while (0)
; template <class Sched, class Epi>
; __device__ __forceinline__ void gemm_run(LAS unsigned char* lds, const Sched& S, const Epi& E) {
;     ...
;         for (int t = 0; t < nt; t += 2) {
;             const bool last = (t == nt - 2);
;             const char* a1 = cA + (size_t)(t + 1) * kstep;
;             const char* a2 = last ? nA : cA + (size_t)(t + 2) * kstep; const char* b2 = last ? nB : cB + (size_t)(t + 2) * kstep;
;             const unsigned la2 = last ? nlda : lda, lb2 = last ? nldb : ldb;
;             const char* a3 = a2 + kstep; const char* b3 = b2 + kstep;
;             PG8_LDB(B0, 0, 0); PG8_LDB(B1, 0, 1); PG8_SCHED; PG8_LDA(At, 0, 0); PG8_STAGE(PG8_SA(1, 1), a1 + (size_t)HALF * lda, RA, lda);
;             PG8_WAIT_V(8); PG8_WAIT_L(0); PG8_BAR; PG8_MMA(0, 0, At, B0); PG8_MMA(0, 1, At, B1); PG8_BAR; PG8_SCHED;
;             PG8_LDA(At, 0, 1); PG8_STAGE(PG8_SB(0, 0), b2, RB, lb2); PG8_STAGE(PG8_SB(0, 1), b2 + (size_t)HALF * lb2, RB, lb2); PG8_STAGE(PG8_SA(0, 0), a2, RA, la2);
;             PG8_WAIT_V(8); PG8_WAIT_L(0); PG8_BAR; PG8_MMA(1, 0, At, B0); PG8_MMA(1, 1, At, B1); PG8_BAR; PG8_SCHED;
;             PG8_LDB(B0, 1, 0); PG8_LDB(B1, 1, 1); PG8_SCHED; PG8_LDA(At, 1, 0); PG8_STAGE(PG8_SA(0, 1), a2 + (size_t)HALF * la2, RA, la2);
;             PG8_WAIT_V(8); PG8_WAIT_L(0); PG8_BAR; PG8_MMA(0, 0, At, B0); PG8_MMA(0, 1, At, B1); PG8_BAR; PG8_SCHED;
;             PG8_LDA(At, 1, 1); PG8_STAGE(PG8_SB(1, 0), b3, RB, lb2); PG8_STAGE(PG8_SB(1, 1), b3 + (size_t)HALF * lb2, RB, lb2); PG8_STAGE(PG8_SA(1, 0), a3, RA, la2);
;             PG8_WAIT_V(8); PG8_WAIT_L(0); PG8_BAR; PG8_MMA(1, 0, At, B0); PG8_MMA(1, 1, At, B1); PG8_BAR; PG8_SCHED;
.LBB0_893:
	s_add_u32 s19, s38, 0x100
	s_addc_u32 s31, s39, 0
	s_mov_b32 s44, -2
	s_mov_b64 s[38:39], 0
	s_waitcnt lgkmcnt(0)
	ds_read_b128 v[134:137], v191
	ds_read_b128 v[138:141], v191 offset:1024
	ds_read_b128 v[142:145], v191 offset:2048
	ds_read_b128 v[146:149], v191 offset:3072
	ds_read_b128 v[150:153], v192
	ds_read_b128 v[172:175], v192 offset:1024
	ds_read_b128 v[176:179], v192 offset:2048
	ds_read_b128 v[180:183], v192 offset:3072
	s_add_u32 s40, s36, s38
	s_addc_u32 s41, s37, s39
	s_mov_b32 s98, s40
	s_mov_b32 s99, s41
	s_add_u32 s40, s40, 0x100
	s_addc_u32 s41, s41, 0
	s_add_u32 s45, s19, s38
	s_addc_u32 s46, s31, s39
	s_cmpk_eq_i32 s38, 0xf00
	s_cselect_b32 s43, s21, s41
	s_cselect_b32 s42, s20, s40
	s_cselect_b32 s41, s29, s46
	s_cselect_b32 s40, s28, s45
	s_mov_b64 s[100:101], s[42:43]
	s_add_i32 m0, s33, 0xc000
	ds_read_b128 v[184:187], v193
	ds_read_b128 v[196:199], v193 offset:1024
	ds_read_b128 v[200:203], v193 offset:2048
	ds_read_b128 v[204:207], v193 offset:3072
	ds_read_b128 v[208:211], v193 offset:4096
	ds_read_b128 v[212:215], v193 offset:5120
	ds_read_b128 v[216:219], v193 offset:6144
	ds_read_b128 v[220:223], v193 offset:7168
	global_load_lds_dwordx4 v168, s[98:99]
	s_add_i32 m0, s33, 0xe000
	s_nop 0
	global_load_lds_dwordx4 v170, s[98:99]
	s_waitcnt vmcnt(8)
	s_waitcnt lgkmcnt(0)
	s_barrier
	s_waitcnt lgkmcnt(0)
	v_mfma_f32_16x16x32_bf16 v[126:129], v[134:137], v[184:187], 0
	v_mfma_f32_16x16x32_bf16 v[122:125], v[142:145], v[184:187], 0
	v_mfma_f32_16x16x32_bf16 v[110:113], v[134:137], v[200:203], 0
	v_mfma_f32_16x16x32_bf16 v[106:109], v[142:145], v[200:203], 0
	v_mfma_f32_16x16x32_bf16 v[94:97], v[134:137], v[208:211], 0
	v_mfma_f32_16x16x32_bf16 v[90:93], v[142:145], v[208:211], 0
	v_mfma_f32_16x16x32_bf16 v[78:81], v[134:137], v[216:219], 0
	v_mfma_f32_16x16x32_bf16 v[74:77], v[142:145], v[216:219], 0
	v_mfma_f32_16x16x32_bf16 v[126:129], v[138:141], v[196:199], v[126:129]
	v_mfma_f32_16x16x32_bf16 v[122:125], v[146:149], v[196:199], v[122:125]
	v_mfma_f32_16x16x32_bf16 v[110:113], v[138:141], v[204:207], v[110:113]
	v_mfma_f32_16x16x32_bf16 v[106:109], v[146:149], v[204:207], v[106:109]
	v_mfma_f32_16x16x32_bf16 v[94:97], v[138:141], v[212:215], v[94:97]
	v_mfma_f32_16x16x32_bf16 v[90:93], v[146:149], v[212:215], v[90:93]
	v_mfma_f32_16x16x32_bf16 v[78:81], v[138:141], v[220:223], v[78:81]
	v_mfma_f32_16x16x32_bf16 v[74:77], v[146:149], v[220:223], v[74:77]
	v_mfma_f32_16x16x32_bf16 v[118:121], v[150:153], v[184:187], 0
	v_mfma_f32_16x16x32_bf16 v[114:117], v[176:179], v[184:187], 0
	v_mfma_f32_16x16x32_bf16 v[102:105], v[150:153], v[200:203], 0
	v_mfma_f32_16x16x32_bf16 v[98:101], v[176:179], v[200:203], 0
	v_mfma_f32_16x16x32_bf16 v[86:89], v[150:153], v[208:211], 0
	v_mfma_f32_16x16x32_bf16 v[82:85], v[176:179], v[208:211], 0
	v_mfma_f32_16x16x32_bf16 v[70:73], v[150:153], v[216:219], 0
	v_mfma_f32_16x16x32_bf16 v[66:69], v[176:179], v[216:219], 0
	v_mfma_f32_16x16x32_bf16 v[118:121], v[172:175], v[196:199], v[118:121]
	v_mfma_f32_16x16x32_bf16 v[114:117], v[180:183], v[196:199], v[114:117]
	v_mfma_f32_16x16x32_bf16 v[102:105], v[172:175], v[204:207], v[102:105]
	v_mfma_f32_16x16x32_bf16 v[98:101], v[180:183], v[204:207], v[98:101]
	v_mfma_f32_16x16x32_bf16 v[86:89], v[172:175], v[212:215], v[86:89]
	v_mfma_f32_16x16x32_bf16 v[82:85], v[180:183], v[212:215], v[82:85]
	v_mfma_f32_16x16x32_bf16 v[70:73], v[172:175], v[220:223], v[70:73]
	v_mfma_f32_16x16x32_bf16 v[66:69], v[180:183], v[220:223], v[66:69]
	s_barrier
	s_add_i32 s45, s61, s3
	s_mov_b32 m0, s45
	ds_read_b128 v[184:187], v193 offset:16384
	ds_read_b128 v[196:199], v193 offset:17408
	ds_read_b128 v[200:203], v193 offset:18432
	ds_read_b128 v[204:207], v193 offset:19456
	ds_read_b128 v[208:211], v193 offset:20480
	ds_read_b128 v[212:215], v193 offset:21504
	ds_read_b128 v[216:219], v193 offset:22528
	ds_read_b128 v[220:223], v193 offset:23552
	global_load_lds_dwordx4 v156, s[40:41]
	s_add_i32 m0, s45, 0x2000
	s_add_u32 s46, s40, 0x80000
	s_addc_u32 s47, s41, 0
	s_add_i32 s45, s62, s3
	global_load_lds_dwordx4 v160, s[40:41]
	s_mov_b32 m0, s45
	s_nop 0
	global_load_lds_dwordx4 v156, s[46:47]
	s_add_i32 m0, s45, 0x2000
	s_nop 0
	global_load_lds_dwordx4 v160, s[46:47]
	s_mov_b32 m0, s33
	s_nop 0
	global_load_lds_dwordx4 v162, s[42:43]
	s_mov_b32 m0, s35
	s_nop 0
	global_load_lds_dwordx4 v164, s[42:43]
	s_waitcnt vmcnt(8)
	s_waitcnt lgkmcnt(0)
	s_barrier
	s_waitcnt lgkmcnt(0)
	v_mfma_f32_16x16x32_bf16 v[62:65], v[134:137], v[184:187], 0
	v_mfma_f32_16x16x32_bf16 v[58:61], v[142:145], v[184:187], 0
	v_mfma_f32_16x16x32_bf16 v[46:49], v[134:137], v[200:203], 0
	v_mfma_f32_16x16x32_bf16 v[42:45], v[142:145], v[200:203], 0
	v_mfma_f32_16x16x32_bf16 v[30:33], v[134:137], v[208:211], 0
	v_mfma_f32_16x16x32_bf16 v[26:29], v[142:145], v[208:211], 0
	v_mfma_f32_16x16x32_bf16 v[14:17], v[134:137], v[216:219], 0
	v_mfma_f32_16x16x32_bf16 v[10:13], v[142:145], v[216:219], 0
	v_mfma_f32_16x16x32_bf16 v[62:65], v[138:141], v[196:199], v[62:65]
	v_mfma_f32_16x16x32_bf16 v[58:61], v[146:149], v[196:199], v[58:61]
	v_mfma_f32_16x16x32_bf16 v[46:49], v[138:141], v[204:207], v[46:49]
	v_mfma_f32_16x16x32_bf16 v[42:45], v[146:149], v[204:207], v[42:45]
	v_mfma_f32_16x16x32_bf16 v[30:33], v[138:141], v[212:215], v[30:33]
	v_mfma_f32_16x16x32_bf16 v[26:29], v[146:149], v[212:215], v[26:29]
	v_mfma_f32_16x16x32_bf16 v[14:17], v[138:141], v[220:223], v[14:17]
	v_mfma_f32_16x16x32_bf16 v[10:13], v[146:149], v[220:223], v[10:13]
	v_mfma_f32_16x16x32_bf16 v[54:57], v[150:153], v[184:187], 0
	v_mfma_f32_16x16x32_bf16 v[50:53], v[176:179], v[184:187], 0
	v_mfma_f32_16x16x32_bf16 v[38:41], v[150:153], v[200:203], 0
	v_mfma_f32_16x16x32_bf16 v[34:37], v[176:179], v[200:203], 0
	v_mfma_f32_16x16x32_bf16 v[22:25], v[150:153], v[208:211], 0
	v_mfma_f32_16x16x32_bf16 v[18:21], v[176:179], v[208:211], 0
	v_mfma_f32_16x16x32_bf16 v[6:9], v[150:153], v[216:219], 0
	v_mfma_f32_16x16x32_bf16 v[2:5], v[176:179], v[216:219], 0
	v_mfma_f32_16x16x32_bf16 v[54:57], v[172:175], v[196:199], v[54:57]
	v_mfma_f32_16x16x32_bf16 v[50:53], v[180:183], v[196:199], v[50:53]
	v_mfma_f32_16x16x32_bf16 v[38:41], v[172:175], v[204:207], v[38:41]
	v_mfma_f32_16x16x32_bf16 v[34:37], v[180:183], v[204:207], v[34:37]
	v_mfma_f32_16x16x32_bf16 v[22:25], v[172:175], v[212:215], v[22:25]
	v_mfma_f32_16x16x32_bf16 v[18:21], v[180:183], v[212:215], v[18:21]
	v_mfma_f32_16x16x32_bf16 v[6:9], v[172:175], v[220:223], v[6:9]
	v_mfma_f32_16x16x32_bf16 v[2:5], v[180:183], v[220:223], v[2:5]
	s_barrier
; #define PG8_STAGE(bufoff, gbase, RR, ld) do { _Pragma("unroll") for (int _i = 0; _i < 2; ++_i) \
;         __builtin_amdgcn_global_load_lds((const unsigned*)((const char*)(gbase) + (RR)[_i] * (ld) + C2[_i]), (LAS unsigned*)(lds + (bufoff) + ldsw + _i * 8192), 16, 0, 0); } while (0)
; #define PG8_LDA(dst, b, h) do { _Pragma("unroll") for (int m = 0; m < 4; ++m) _Pragma("unroll") for (int k = 0; k < 2; ++k) dst[m][k] = *(const LAS bf16x8*)(lds + PG8_SA(b, h) + aoff + m * 2048 + k * 1024); } while (0)
; #define PG8_LDB(dst, b, h) do { _Pragma("unroll") for (int n = 0; n < 2; ++n) _Pragma("unroll") for (int k = 0; k < 2; ++k) dst[n][k] = *(const LAS bf16x8*)(lds + PG8_SB(b, h) + boff + n * 2048 + k * 1024); } while (0)
; #define PG8_MMA(ai, bj, At, Bt) do { __builtin_amdgcn_s_setprio(1); _Pragma("unroll") for (int m = 0; m < 4; ++m) _Pragma("unroll") for (int n = 0; n < 2; ++n) _Pragma("unroll") for (int k = 0; k < 2; ++k) \
;         acc[ai][bj][m][n] = __builtin_amdgcn_mfma_f32_16x16x32_bf16(Bt[n][k], At[m][k], acc[ai][bj][m][n], 0, 0, 0); __builtin_amdgcn_s_setprio(0); } while (0)
; #define PG8_BAR __builtin_amdgcn_s_barrier()
; template <class Sched, class Epi>
; __device__ __forceinline__ void gemm_run(LAS unsigned char* lds, const Sched& S, const Epi& E) {
;     ...
;             PG8_LDB(B0, 0, 0); PG8_LDB(B1, 0, 1); PG8_SCHED; PG8_LDA(At, 0, 0); PG8_STAGE(PG8_SA(1, 1), a1 + (size_t)HALF * lda, RA, lda);
;             PG8_WAIT_V(8); PG8_WAIT_L(0); PG8_BAR; PG8_MMA(0, 0, At, B0); PG8_MMA(0, 1, At, B1); PG8_BAR; PG8_SCHED;
;             PG8_LDA(At, 0, 1); PG8_STAGE(PG8_SB(0, 0), b2, RB, lb2); PG8_STAGE(PG8_SB(0, 1), b2 + (size_t)HALF * lb2, RB, lb2); PG8_STAGE(PG8_SA(0, 0), a2, RA, la2);
;             PG8_WAIT_V(8); PG8_WAIT_L(0); PG8_BAR; PG8_MMA(1, 0, At, B0); PG8_MMA(1, 1, At, B1); PG8_BAR; PG8_SCHED;
;             PG8_LDB(B0, 1, 0); PG8_LDB(B1, 1, 1); PG8_SCHED; PG8_LDA(At, 1, 0); PG8_STAGE(PG8_SA(0, 1), a2 + (size_t)HALF * la2, RA, la2);
;             PG8_WAIT_V(8); PG8_WAIT_L(0); PG8_BAR; PG8_MMA(0, 0, At, B0); PG8_MMA(0, 1, At, B1); PG8_BAR; PG8_SCHED;
;             PG8_LDA(At, 1, 1); PG8_STAGE(PG8_SB(1, 0), b3, RB, lb2); PG8_STAGE(PG8_SB(1, 1), b3 + (size_t)HALF * lb2, RB, lb2); PG8_STAGE(PG8_SA(1, 0), a3, RA, la2);
;             PG8_WAIT_V(8); PG8_WAIT_L(0); PG8_BAR; PG8_MMA(1, 0, At, B0); PG8_MMA(1, 1, At, B1); PG8_BAR; PG8_SCHED;
;         }
	s_add_i32 s45, 0, 0x18000
	s_add_i32 s46, 0, 0x1c000
	ds_read_b128 v[134:137], v191 offset:32768
	ds_read_b128 v[138:141], v191 offset:33792
	ds_read_b128 v[142:145], v191 offset:34816
	ds_read_b128 v[146:149], v191 offset:35840
	ds_read_b128 v[150:153], v192 offset:32768
	ds_read_b128 v[172:175], v192 offset:33792
	ds_read_b128 v[176:179], v192 offset:34816
	ds_read_b128 v[180:183], v192 offset:35840
	s_add_u32 s42, s42, 0x80000
	s_addc_u32 s43, s43, 0
	s_mov_b32 m0, s52
	ds_read_b128 v[184:187], v193 offset:32768
	ds_read_b128 v[196:199], v193 offset:33792
	ds_read_b128 v[200:203], v193 offset:34816
	ds_read_b128 v[204:207], v193 offset:35840
	ds_read_b128 v[208:211], v193 offset:36864
	ds_read_b128 v[212:215], v193 offset:37888
	ds_read_b128 v[216:219], v193 offset:38912
	ds_read_b128 v[220:223], v193 offset:39936
	global_load_lds_dwordx4 v162, s[42:43]
	s_mov_b32 m0, s53
	s_nop 0
	global_load_lds_dwordx4 v164, s[42:43]
	s_waitcnt vmcnt(8)
	s_waitcnt lgkmcnt(0)
	s_barrier
	s_waitcnt lgkmcnt(0)
	v_mfma_f32_16x16x32_bf16 v[126:129], v[134:137], v[184:187], v[126:129]
	v_mfma_f32_16x16x32_bf16 v[122:125], v[142:145], v[184:187], v[122:125]
	v_mfma_f32_16x16x32_bf16 v[110:113], v[134:137], v[200:203], v[110:113]
	v_mfma_f32_16x16x32_bf16 v[106:109], v[142:145], v[200:203], v[106:109]
	v_mfma_f32_16x16x32_bf16 v[94:97], v[134:137], v[208:211], v[94:97]
	v_mfma_f32_16x16x32_bf16 v[90:93], v[142:145], v[208:211], v[90:93]
	v_mfma_f32_16x16x32_bf16 v[78:81], v[134:137], v[216:219], v[78:81]
	v_mfma_f32_16x16x32_bf16 v[74:77], v[142:145], v[216:219], v[74:77]
	v_mfma_f32_16x16x32_bf16 v[126:129], v[138:141], v[196:199], v[126:129]
	v_mfma_f32_16x16x32_bf16 v[122:125], v[146:149], v[196:199], v[122:125]
	v_mfma_f32_16x16x32_bf16 v[110:113], v[138:141], v[204:207], v[110:113]
	v_mfma_f32_16x16x32_bf16 v[106:109], v[146:149], v[204:207], v[106:109]
	v_mfma_f32_16x16x32_bf16 v[94:97], v[138:141], v[212:215], v[94:97]
	v_mfma_f32_16x16x32_bf16 v[90:93], v[146:149], v[212:215], v[90:93]
	v_mfma_f32_16x16x32_bf16 v[78:81], v[138:141], v[220:223], v[78:81]
	v_mfma_f32_16x16x32_bf16 v[74:77], v[146:149], v[220:223], v[74:77]
	v_mfma_f32_16x16x32_bf16 v[118:121], v[150:153], v[184:187], v[118:121]
	v_mfma_f32_16x16x32_bf16 v[114:117], v[176:179], v[184:187], v[114:117]
	v_mfma_f32_16x16x32_bf16 v[102:105], v[150:153], v[200:203], v[102:105]
	v_mfma_f32_16x16x32_bf16 v[98:101], v[176:179], v[200:203], v[98:101]
	v_mfma_f32_16x16x32_bf16 v[86:89], v[150:153], v[208:211], v[86:89]
	v_mfma_f32_16x16x32_bf16 v[82:85], v[176:179], v[208:211], v[82:85]
	v_mfma_f32_16x16x32_bf16 v[70:73], v[150:153], v[216:219], v[70:73]
	v_mfma_f32_16x16x32_bf16 v[66:69], v[176:179], v[216:219], v[66:69]
	v_mfma_f32_16x16x32_bf16 v[118:121], v[172:175], v[196:199], v[118:121]
	v_mfma_f32_16x16x32_bf16 v[114:117], v[180:183], v[196:199], v[114:117]
	v_mfma_f32_16x16x32_bf16 v[102:105], v[172:175], v[204:207], v[102:105]
	v_mfma_f32_16x16x32_bf16 v[98:101], v[180:183], v[204:207], v[98:101]
	v_mfma_f32_16x16x32_bf16 v[86:89], v[172:175], v[212:215], v[86:89]
	v_mfma_f32_16x16x32_bf16 v[82:85], v[180:183], v[212:215], v[82:85]
	v_mfma_f32_16x16x32_bf16 v[70:73], v[172:175], v[220:223], v[70:73]
	v_mfma_f32_16x16x32_bf16 v[66:69], v[180:183], v[220:223], v[66:69]
	s_barrier
	s_add_i32 s42, s45, s3
	s_mov_b32 m0, s42
	ds_read_b128 v[184:187], v193 offset:49152
	ds_read_b128 v[196:199], v193 offset:50176
	ds_read_b128 v[200:203], v193 offset:51200
	ds_read_b128 v[204:207], v193 offset:52224
	ds_read_b128 v[208:211], v193 offset:53248
	ds_read_b128 v[212:215], v193 offset:54272
	ds_read_b128 v[216:219], v193 offset:55296
	ds_read_b128 v[220:223], v193 offset:56320
	s_add_u32 s98, s40, 0x80
	s_addc_u32 s99, s41, 0
	global_load_lds_dwordx4 v156, s[98:99]
	s_add_i32 m0, s42, 0x2000
	s_nop 0
	global_load_lds_dwordx4 v160, s[98:99]
	s_add_u32 s40, s40, 0x80080
	s_addc_u32 s41, s41, 0
	s_add_i32 s42, s46, s3
	s_mov_b32 m0, s42
	s_nop 0
	global_load_lds_dwordx4 v156, s[40:41]
	s_add_i32 m0, s42, 0x2000
	s_nop 0
	global_load_lds_dwordx4 v160, s[40:41]
	s_mov_b32 m0, s55
	s_nop 0
	s_add_u32 s100, s100, 0x80
	s_addc_u32 s101, s101, 0
	global_load_lds_dwordx4 v162, s[100:101]
	s_mov_b32 m0, s56
	s_nop 0
	global_load_lds_dwordx4 v164, s[100:101]
	s_waitcnt vmcnt(8)
	s_waitcnt lgkmcnt(0)
	s_barrier
	s_waitcnt lgkmcnt(0)
	v_mfma_f32_16x16x32_bf16 v[62:65], v[134:137], v[184:187], v[62:65]
	v_mfma_f32_16x16x32_bf16 v[58:61], v[142:145], v[184:187], v[58:61]
	v_mfma_f32_16x16x32_bf16 v[46:49], v[134:137], v[200:203], v[46:49]
	v_mfma_f32_16x16x32_bf16 v[42:45], v[142:145], v[200:203], v[42:45]
	v_mfma_f32_16x16x32_bf16 v[30:33], v[134:137], v[208:211], v[30:33]
	v_mfma_f32_16x16x32_bf16 v[26:29], v[142:145], v[208:211], v[26:29]
	v_mfma_f32_16x16x32_bf16 v[14:17], v[134:137], v[216:219], v[14:17]
	v_mfma_f32_16x16x32_bf16 v[10:13], v[142:145], v[216:219], v[10:13]
	v_mfma_f32_16x16x32_bf16 v[62:65], v[138:141], v[196:199], v[62:65]
	v_mfma_f32_16x16x32_bf16 v[58:61], v[146:149], v[196:199], v[58:61]
	v_mfma_f32_16x16x32_bf16 v[46:49], v[138:141], v[204:207], v[46:49]
	v_mfma_f32_16x16x32_bf16 v[42:45], v[146:149], v[204:207], v[42:45]
	v_mfma_f32_16x16x32_bf16 v[30:33], v[138:141], v[212:215], v[30:33]
	v_mfma_f32_16x16x32_bf16 v[26:29], v[146:149], v[212:215], v[26:29]
	v_mfma_f32_16x16x32_bf16 v[14:17], v[138:141], v[220:223], v[14:17]
	v_mfma_f32_16x16x32_bf16 v[10:13], v[146:149], v[220:223], v[10:13]
	v_mfma_f32_16x16x32_bf16 v[54:57], v[150:153], v[184:187], v[54:57]
	v_mfma_f32_16x16x32_bf16 v[50:53], v[176:179], v[184:187], v[50:53]
	v_mfma_f32_16x16x32_bf16 v[38:41], v[150:153], v[200:203], v[38:41]
	v_mfma_f32_16x16x32_bf16 v[34:37], v[176:179], v[200:203], v[34:37]
	v_mfma_f32_16x16x32_bf16 v[22:25], v[150:153], v[208:211], v[22:25]
	v_mfma_f32_16x16x32_bf16 v[18:21], v[176:179], v[208:211], v[18:21]
	v_mfma_f32_16x16x32_bf16 v[6:9], v[150:153], v[216:219], v[6:9]
	v_mfma_f32_16x16x32_bf16 v[2:5], v[176:179], v[216:219], v[2:5]
	v_mfma_f32_16x16x32_bf16 v[54:57], v[172:175], v[196:199], v[54:57]
	v_mfma_f32_16x16x32_bf16 v[50:53], v[180:183], v[196:199], v[50:53]
	v_mfma_f32_16x16x32_bf16 v[38:41], v[172:175], v[204:207], v[38:41]
	v_mfma_f32_16x16x32_bf16 v[34:37], v[180:183], v[204:207], v[34:37]
	v_mfma_f32_16x16x32_bf16 v[22:25], v[172:175], v[212:215], v[22:25]
	v_mfma_f32_16x16x32_bf16 v[18:21], v[180:183], v[212:215], v[18:21]
	v_mfma_f32_16x16x32_bf16 v[6:9], v[172:175], v[220:223], v[6:9]
	v_mfma_f32_16x16x32_bf16 v[2:5], v[180:183], v[220:223], v[2:5]
	s_barrier
	s_add_i32 s44, s44, 2
	s_add_u32 s38, s38, 0x100
	s_addc_u32 s39, s39, 0
	s_cmp_gt_u32 s44, 29
	s_cbranch_scc0 .LBB0_894
	.p2align 6
; #define PG8_STAGE(bufoff, gbase, RR, ld) do { _Pragma("unroll") for (int _i = 0; _i < 2; ++_i) \
;         __builtin_amdgcn_global_load_lds((const unsigned*)((const char*)(gbase) + (RR)[_i] * (ld) + C2[_i]), (LAS unsigned*)(lds + (bufoff) + ldsw + _i * 8192), 16, 0, 0); } while (0)
; #define PG8_LDA(dst, b, h) do { _Pragma("unroll") for (int m = 0; m < 4; ++m) _Pragma("unroll") for (int k = 0; k < 2; ++k) dst[m][k] = *(const LAS bf16x8*)(lds + PG8_SA(b, h) + aoff + m * 2048 + k * 1024); } while (0)
; #define PG8_LDB(dst, b, h) do { _Pragma("unroll") for (int n = 0; n < 2; ++n) _Pragma("unroll") for (int k = 0; k < 2; ++k) dst[n][k] = *(const LAS bf16x8*)(lds + PG8_SB(b, h) + boff + n * 2048 + k * 1024); } while (0)
; #define PG8_MMA(ai, bj, At, Bt) do { __builtin_amdgcn_s_setprio(1); _Pragma("unroll") for (int m = 0; m < 4; ++m) _Pragma("unroll") for (int n = 0; n < 2; ++n) _Pragma("unroll") for (int k = 0; k < 2; ++k) \
;         acc[ai][bj][m][n] = __builtin_amdgcn_mfma_f32_16x16x32_bf16(Bt[n][k], At[m][k], acc[ai][bj][m][n], 0, 0, 0); __builtin_amdgcn_s_setprio(0); } while (0)
; #define PG8_WAIT_V(n) asm volatile("s_waitcnt vmcnt(" #n ")" ::: "memory")
; #define PG8_WAIT_L(n) asm volatile("s_waitcnt lgkmcnt(" #n ")" ::: "memory")
; #define PG8_BAR __builtin_amdgcn_s_barrier()
; #define PG8_SCHED __builtin_amdgcn_sched_barrier(0)
; template <class Sched, class Epi>
; __device__ __forceinline__ void gemm_run(LAS unsigned char* lds, const Sched& S, const Epi& E) {
;     ...
;             PG8_LDB(B0, 0, 0); PG8_LDB(B1, 0, 1); PG8_SCHED; PG8_LDA(At, 0, 0); PG8_STAGE(PG8_SA(1, 1), a1 + (size_t)HALF * lda, RA, lda);
;             PG8_WAIT_V(8); PG8_WAIT_L(0); PG8_BAR; PG8_MMA(0, 0, At, B0); PG8_MMA(0, 1, At, B1); PG8_BAR; PG8_SCHED;
;             PG8_LDA(At, 0, 1); PG8_STAGE(PG8_SB(0, 0), b2, RB, lb2); PG8_STAGE(PG8_SB(0, 1), b2 + (size_t)HALF * lb2, RB, lb2); PG8_STAGE(PG8_SA(0, 0), a2, RA, la2);
;             PG8_WAIT_V(8); PG8_WAIT_L(0); PG8_BAR; PG8_MMA(1, 0, At, B0); PG8_MMA(1, 1, At, B1); PG8_BAR; PG8_SCHED;
;             PG8_LDB(B0, 1, 0); PG8_LDB(B1, 1, 1); PG8_SCHED; PG8_LDA(At, 1, 0); PG8_STAGE(PG8_SA(0, 1), a2 + (size_t)HALF * la2, RA, la2);
;             PG8_WAIT_V(8); PG8_WAIT_L(0); PG8_BAR; PG8_MMA(0, 0, At, B0); PG8_MMA(0, 1, At, B1); PG8_BAR; PG8_SCHED;
.LBB0_894:
	ds_read_b128 v[134:137], v191
	ds_read_b128 v[138:141], v191 offset:1024
	ds_read_b128 v[142:145], v191 offset:2048
	ds_read_b128 v[146:149], v191 offset:3072
	ds_read_b128 v[150:153], v192
	ds_read_b128 v[172:175], v192 offset:1024
	ds_read_b128 v[176:179], v192 offset:2048
	ds_read_b128 v[180:183], v192 offset:3072
	s_add_u32 s40, s36, s38
	s_addc_u32 s41, s37, s39
	s_mov_b32 s98, s40
	s_mov_b32 s99, s41
	s_add_u32 s40, s40, 0x100
	s_addc_u32 s41, s41, 0
	s_add_u32 s45, s19, s38
	s_addc_u32 s46, s31, s39
	s_cmpk_eq_i32 s38, 0xf00
	s_cselect_b32 s43, s21, s41
	s_cselect_b32 s42, s20, s40
	s_cselect_b32 s41, s29, s46
	s_cselect_b32 s40, s28, s45
	s_mov_b64 s[100:101], s[42:43]
	s_add_i32 m0, s33, 0xc000
	ds_read_b128 v[184:187], v193
	ds_read_b128 v[196:199], v193 offset:1024
	ds_read_b128 v[200:203], v193 offset:2048
	ds_read_b128 v[204:207], v193 offset:3072
	ds_read_b128 v[208:211], v193 offset:4096
	ds_read_b128 v[212:215], v193 offset:5120
	ds_read_b128 v[216:219], v193 offset:6144
	ds_read_b128 v[220:223], v193 offset:7168
	global_load_lds_dwordx4 v168, s[98:99]
	s_add_i32 m0, s33, 0xe000
	s_nop 0
	global_load_lds_dwordx4 v170, s[98:99]
	s_waitcnt vmcnt(8)
	s_waitcnt lgkmcnt(0)
	s_barrier
	s_waitcnt lgkmcnt(0)
	v_mfma_f32_16x16x32_bf16 v[126:129], v[134:137], v[184:187], v[126:129]
	v_mfma_f32_16x16x32_bf16 v[122:125], v[142:145], v[184:187], v[122:125]
	v_mfma_f32_16x16x32_bf16 v[110:113], v[134:137], v[200:203], v[110:113]
	v_mfma_f32_16x16x32_bf16 v[106:109], v[142:145], v[200:203], v[106:109]
	v_mfma_f32_16x16x32_bf16 v[94:97], v[134:137], v[208:211], v[94:97]
	v_mfma_f32_16x16x32_bf16 v[90:93], v[142:145], v[208:211], v[90:93]
	v_mfma_f32_16x16x32_bf16 v[78:81], v[134:137], v[216:219], v[78:81]
	v_mfma_f32_16x16x32_bf16 v[74:77], v[142:145], v[216:219], v[74:77]
	v_mfma_f32_16x16x32_bf16 v[126:129], v[138:141], v[196:199], v[126:129]
	v_mfma_f32_16x16x32_bf16 v[122:125], v[146:149], v[196:199], v[122:125]
	v_mfma_f32_16x16x32_bf16 v[110:113], v[138:141], v[204:207], v[110:113]
	v_mfma_f32_16x16x32_bf16 v[106:109], v[146:149], v[204:207], v[106:109]
	v_mfma_f32_16x16x32_bf16 v[94:97], v[138:141], v[212:215], v[94:97]
	v_mfma_f32_16x16x32_bf16 v[90:93], v[146:149], v[212:215], v[90:93]
	v_mfma_f32_16x16x32_bf16 v[78:81], v[138:141], v[220:223], v[78:81]
	v_mfma_f32_16x16x32_bf16 v[74:77], v[146:149], v[220:223], v[74:77]
	v_mfma_f32_16x16x32_bf16 v[118:121], v[150:153], v[184:187], v[118:121]
	v_mfma_f32_16x16x32_bf16 v[114:117], v[176:179], v[184:187], v[114:117]
	v_mfma_f32_16x16x32_bf16 v[102:105], v[150:153], v[200:203], v[102:105]
	v_mfma_f32_16x16x32_bf16 v[98:101], v[176:179], v[200:203], v[98:101]
	v_mfma_f32_16x16x32_bf16 v[86:89], v[150:153], v[208:211], v[86:89]
	v_mfma_f32_16x16x32_bf16 v[82:85], v[176:179], v[208:211], v[82:85]
	v_mfma_f32_16x16x32_bf16 v[70:73], v[150:153], v[216:219], v[70:73]
	v_mfma_f32_16x16x32_bf16 v[66:69], v[176:179], v[216:219], v[66:69]
	v_mfma_f32_16x16x32_bf16 v[118:121], v[172:175], v[196:199], v[118:121]
	v_mfma_f32_16x16x32_bf16 v[114:117], v[180:183], v[196:199], v[114:117]
	v_mfma_f32_16x16x32_bf16 v[102:105], v[172:175], v[204:207], v[102:105]
	v_mfma_f32_16x16x32_bf16 v[98:101], v[180:183], v[204:207], v[98:101]
	v_mfma_f32_16x16x32_bf16 v[86:89], v[172:175], v[212:215], v[86:89]
	v_mfma_f32_16x16x32_bf16 v[82:85], v[180:183], v[212:215], v[82:85]
	v_mfma_f32_16x16x32_bf16 v[70:73], v[172:175], v[220:223], v[70:73]
	v_mfma_f32_16x16x32_bf16 v[66:69], v[180:183], v[220:223], v[66:69]
	s_barrier
	s_add_i32 s45, s61, s3
	s_mov_b32 m0, s45
	ds_read_b128 v[184:187], v193 offset:16384
	ds_read_b128 v[196:199], v193 offset:17408
	ds_read_b128 v[200:203], v193 offset:18432
	ds_read_b128 v[204:207], v193 offset:19456
	ds_read_b128 v[208:211], v193 offset:20480
	ds_read_b128 v[212:215], v193 offset:21504
	ds_read_b128 v[216:219], v193 offset:22528
	ds_read_b128 v[220:223], v193 offset:23552
	global_load_lds_dwordx4 v156, s[40:41]
	s_add_i32 m0, s45, 0x2000
	s_add_u32 s46, s40, 0x80000
	s_addc_u32 s47, s41, 0
	s_add_i32 s45, s62, s3
	global_load_lds_dwordx4 v160, s[40:41]
	s_mov_b32 m0, s45
	s_nop 0
	global_load_lds_dwordx4 v156, s[46:47]
	s_add_i32 m0, s45, 0x2000
	s_nop 0
	global_load_lds_dwordx4 v160, s[46:47]
	s_mov_b32 m0, s33
	s_nop 0
	global_load_lds_dwordx4 v162, s[42:43]
	s_mov_b32 m0, s35
	s_nop 0
	global_load_lds_dwordx4 v164, s[42:43]
	s_waitcnt vmcnt(8)
	s_waitcnt lgkmcnt(0)
	s_barrier
	s_waitcnt lgkmcnt(0)
	v_mfma_f32_16x16x32_bf16 v[62:65], v[134:137], v[184:187], v[62:65]
	v_mfma_f32_16x16x32_bf16 v[58:61], v[142:145], v[184:187], v[58:61]
	v_mfma_f32_16x16x32_bf16 v[46:49], v[134:137], v[200:203], v[46:49]
	v_mfma_f32_16x16x32_bf16 v[42:45], v[142:145], v[200:203], v[42:45]
	v_mfma_f32_16x16x32_bf16 v[30:33], v[134:137], v[208:211], v[30:33]
	v_mfma_f32_16x16x32_bf16 v[26:29], v[142:145], v[208:211], v[26:29]
	v_mfma_f32_16x16x32_bf16 v[14:17], v[134:137], v[216:219], v[14:17]
	v_mfma_f32_16x16x32_bf16 v[10:13], v[142:145], v[216:219], v[10:13]
	v_mfma_f32_16x16x32_bf16 v[62:65], v[138:141], v[196:199], v[62:65]
	v_mfma_f32_16x16x32_bf16 v[58:61], v[146:149], v[196:199], v[58:61]
	v_mfma_f32_16x16x32_bf16 v[46:49], v[138:141], v[204:207], v[46:49]
	v_mfma_f32_16x16x32_bf16 v[42:45], v[146:149], v[204:207], v[42:45]
	v_mfma_f32_16x16x32_bf16 v[30:33], v[138:141], v[212:215], v[30:33]
	v_mfma_f32_16x16x32_bf16 v[26:29], v[146:149], v[212:215], v[26:29]
	v_mfma_f32_16x16x32_bf16 v[14:17], v[138:141], v[220:223], v[14:17]
	v_mfma_f32_16x16x32_bf16 v[10:13], v[146:149], v[220:223], v[10:13]
	v_mfma_f32_16x16x32_bf16 v[54:57], v[150:153], v[184:187], v[54:57]
	v_mfma_f32_16x16x32_bf16 v[50:53], v[176:179], v[184:187], v[50:53]
	v_mfma_f32_16x16x32_bf16 v[38:41], v[150:153], v[200:203], v[38:41]
	v_mfma_f32_16x16x32_bf16 v[34:37], v[176:179], v[200:203], v[34:37]
	v_mfma_f32_16x16x32_bf16 v[22:25], v[150:153], v[208:211], v[22:25]
	v_mfma_f32_16x16x32_bf16 v[18:21], v[176:179], v[208:211], v[18:21]
	v_mfma_f32_16x16x32_bf16 v[6:9], v[150:153], v[216:219], v[6:9]
	v_mfma_f32_16x16x32_bf16 v[2:5], v[176:179], v[216:219], v[2:5]
	v_mfma_f32_16x16x32_bf16 v[54:57], v[172:175], v[196:199], v[54:57]
	v_mfma_f32_16x16x32_bf16 v[50:53], v[180:183], v[196:199], v[50:53]
	v_mfma_f32_16x16x32_bf16 v[38:41], v[172:175], v[204:207], v[38:41]
	v_mfma_f32_16x16x32_bf16 v[34:37], v[180:183], v[204:207], v[34:37]
	v_mfma_f32_16x16x32_bf16 v[22:25], v[172:175], v[212:215], v[22:25]
	v_mfma_f32_16x16x32_bf16 v[18:21], v[180:183], v[212:215], v[18:21]
	v_mfma_f32_16x16x32_bf16 v[6:9], v[172:175], v[220:223], v[6:9]
	v_mfma_f32_16x16x32_bf16 v[2:5], v[180:183], v[220:223], v[2:5]
	s_barrier
; #define PG8_STAGE(bufoff, gbase, RR, ld) do { _Pragma("unroll") for (int _i = 0; _i < 2; ++_i) \
;         __builtin_amdgcn_global_load_lds((const unsigned*)((const char*)(gbase) + (RR)[_i] * (ld) + C2[_i]), (LAS unsigned*)(lds + (bufoff) + ldsw + _i * 8192), 16, 0, 0); } while (0)
; #define PG8_LDA(dst, b, h) do { _Pragma("unroll") for (int m = 0; m < 4; ++m) _Pragma("unroll") for (int k = 0; k < 2; ++k) dst[m][k] = *(const LAS bf16x8*)(lds + PG8_SA(b, h) + aoff + m * 2048 + k * 1024); } while (0)
; #define PG8_LDB(dst, b, h) do { _Pragma("unroll") for (int n = 0; n < 2; ++n) _Pragma("unroll") for (int k = 0; k < 2; ++k) dst[n][k] = *(const LAS bf16x8*)(lds + PG8_SB(b, h) + boff + n * 2048 + k * 1024); } while (0)
; #define PG8_MMA(ai, bj, At, Bt) do { __builtin_amdgcn_s_setprio(1); _Pragma("unroll") for (int m = 0; m < 4; ++m) _Pragma("unroll") for (int n = 0; n < 2; ++n) _Pragma("unroll") for (int k = 0; k < 2; ++k) \
;         acc[ai][bj][m][n] = __builtin_amdgcn_mfma_f32_16x16x32_bf16(Bt[n][k], At[m][k], acc[ai][bj][m][n], 0, 0, 0); __builtin_amdgcn_s_setprio(0); } while (0)
; #define PG8_WAIT_V(n) asm volatile("s_waitcnt vmcnt(" #n ")" ::: "memory")
; #define PG8_WAIT_L(n) asm volatile("s_waitcnt lgkmcnt(" #n ")" ::: "memory")
; #define PG8_BAR __builtin_amdgcn_s_barrier()
; #define PG8_SCHED __builtin_amdgcn_sched_barrier(0)
; template <class Sched, class Epi>
; __device__ __forceinline__ void gemm_run(LAS unsigned char* lds, const Sched& S, const Epi& E) {
;     ...
;             PG8_LDB(B0, 1, 0); PG8_LDB(B1, 1, 1); PG8_SCHED; PG8_LDA(At, 1, 0); PG8_STAGE(PG8_SA(0, 1), a2 + (size_t)HALF * la2, RA, la2);
;             PG8_WAIT_V(8); PG8_WAIT_L(0); PG8_BAR; PG8_MMA(0, 0, At, B0); PG8_MMA(0, 1, At, B1); PG8_BAR; PG8_SCHED;
;             PG8_LDA(At, 1, 1); PG8_STAGE(PG8_SB(1, 0), b3, RB, lb2); PG8_STAGE(PG8_SB(1, 1), b3 + (size_t)HALF * lb2, RB, lb2); PG8_STAGE(PG8_SA(1, 0), a3, RA, la2);
;             PG8_WAIT_V(8); PG8_WAIT_L(0); PG8_BAR; PG8_MMA(1, 0, At, B0); PG8_MMA(1, 1, At, B1); PG8_BAR; PG8_SCHED;
;         }
;         if (wr == 0) PG8_BAR;
	s_add_i32 s45, 0, 0x18000
	s_add_i32 s46, 0, 0x1c000
	ds_read_b128 v[134:137], v191 offset:32768
	ds_read_b128 v[138:141], v191 offset:33792
	ds_read_b128 v[142:145], v191 offset:34816
	ds_read_b128 v[146:149], v191 offset:35840
	ds_read_b128 v[150:153], v192 offset:32768
	ds_read_b128 v[172:175], v192 offset:33792
	ds_read_b128 v[176:179], v192 offset:34816
	ds_read_b128 v[180:183], v192 offset:35840
	s_add_u32 s42, s42, 0x80000
	s_addc_u32 s43, s43, 0
	s_mov_b32 m0, s52
	ds_read_b128 v[184:187], v193 offset:32768
	ds_read_b128 v[196:199], v193 offset:33792
	ds_read_b128 v[200:203], v193 offset:34816
	ds_read_b128 v[204:207], v193 offset:35840
	ds_read_b128 v[208:211], v193 offset:36864
	ds_read_b128 v[212:215], v193 offset:37888
	ds_read_b128 v[216:219], v193 offset:38912
	ds_read_b128 v[220:223], v193 offset:39936
	global_load_lds_dwordx4 v162, s[42:43]
	s_mov_b32 m0, s53
	s_nop 0
	global_load_lds_dwordx4 v164, s[42:43]
	s_waitcnt vmcnt(8)
	s_waitcnt lgkmcnt(0)
	s_barrier
	s_waitcnt lgkmcnt(0)
	v_mfma_f32_16x16x32_bf16 v[126:129], v[134:137], v[184:187], v[126:129]
	v_mfma_f32_16x16x32_bf16 v[122:125], v[142:145], v[184:187], v[122:125]
	v_mfma_f32_16x16x32_bf16 v[110:113], v[134:137], v[200:203], v[110:113]
	v_mfma_f32_16x16x32_bf16 v[106:109], v[142:145], v[200:203], v[106:109]
	v_mfma_f32_16x16x32_bf16 v[94:97], v[134:137], v[208:211], v[94:97]
	v_mfma_f32_16x16x32_bf16 v[90:93], v[142:145], v[208:211], v[90:93]
	v_mfma_f32_16x16x32_bf16 v[78:81], v[134:137], v[216:219], v[78:81]
	v_mfma_f32_16x16x32_bf16 v[74:77], v[142:145], v[216:219], v[74:77]
	v_mfma_f32_16x16x32_bf16 v[126:129], v[138:141], v[196:199], v[126:129]
	v_mfma_f32_16x16x32_bf16 v[122:125], v[146:149], v[196:199], v[122:125]
	v_mfma_f32_16x16x32_bf16 v[110:113], v[138:141], v[204:207], v[110:113]
	v_mfma_f32_16x16x32_bf16 v[106:109], v[146:149], v[204:207], v[106:109]
	v_mfma_f32_16x16x32_bf16 v[94:97], v[138:141], v[212:215], v[94:97]
	v_mfma_f32_16x16x32_bf16 v[90:93], v[146:149], v[212:215], v[90:93]
	v_mfma_f32_16x16x32_bf16 v[78:81], v[138:141], v[220:223], v[78:81]
	v_mfma_f32_16x16x32_bf16 v[74:77], v[146:149], v[220:223], v[74:77]
	v_mfma_f32_16x16x32_bf16 v[118:121], v[150:153], v[184:187], v[118:121]
	v_mfma_f32_16x16x32_bf16 v[114:117], v[176:179], v[184:187], v[114:117]
	v_mfma_f32_16x16x32_bf16 v[102:105], v[150:153], v[200:203], v[102:105]
	v_mfma_f32_16x16x32_bf16 v[98:101], v[176:179], v[200:203], v[98:101]
	v_mfma_f32_16x16x32_bf16 v[86:89], v[150:153], v[208:211], v[86:89]
	v_mfma_f32_16x16x32_bf16 v[82:85], v[176:179], v[208:211], v[82:85]
	v_mfma_f32_16x16x32_bf16 v[70:73], v[150:153], v[216:219], v[70:73]
	v_mfma_f32_16x16x32_bf16 v[66:69], v[176:179], v[216:219], v[66:69]
	v_mfma_f32_16x16x32_bf16 v[118:121], v[172:175], v[196:199], v[118:121]
	v_mfma_f32_16x16x32_bf16 v[114:117], v[180:183], v[196:199], v[114:117]
	v_mfma_f32_16x16x32_bf16 v[102:105], v[172:175], v[204:207], v[102:105]
	v_mfma_f32_16x16x32_bf16 v[98:101], v[180:183], v[204:207], v[98:101]
	v_mfma_f32_16x16x32_bf16 v[86:89], v[172:175], v[212:215], v[86:89]
	v_mfma_f32_16x16x32_bf16 v[82:85], v[180:183], v[212:215], v[82:85]
	v_mfma_f32_16x16x32_bf16 v[70:73], v[172:175], v[220:223], v[70:73]
	v_mfma_f32_16x16x32_bf16 v[66:69], v[180:183], v[220:223], v[66:69]
	s_barrier
	s_add_i32 s42, s45, s3
	s_mov_b32 m0, s42
	ds_read_b128 v[184:187], v193 offset:49152
	ds_read_b128 v[196:199], v193 offset:50176
	ds_read_b128 v[200:203], v193 offset:51200
	ds_read_b128 v[204:207], v193 offset:52224
	ds_read_b128 v[208:211], v193 offset:53248
	ds_read_b128 v[212:215], v193 offset:54272
	ds_read_b128 v[216:219], v193 offset:55296
	ds_read_b128 v[220:223], v193 offset:56320
	s_add_u32 s98, s40, 0x80
	s_addc_u32 s99, s41, 0
	global_load_lds_dwordx4 v156, s[98:99]
	s_add_i32 m0, s42, 0x2000
	s_nop 0
	global_load_lds_dwordx4 v160, s[98:99]
	s_add_u32 s40, s40, 0x80080
	s_addc_u32 s41, s41, 0
	s_add_i32 s42, s46, s3
	s_mov_b32 m0, s42
	s_nop 0
	global_load_lds_dwordx4 v156, s[40:41]
	s_add_i32 m0, s42, 0x2000
	s_nop 0
	global_load_lds_dwordx4 v160, s[40:41]
	s_mov_b32 m0, s55
	s_nop 0
	s_add_u32 s100, s100, 0x80
	s_addc_u32 s101, s101, 0
	global_load_lds_dwordx4 v162, s[100:101]
	s_mov_b32 m0, s56
	s_nop 0
	global_load_lds_dwordx4 v164, s[100:101]
	s_waitcnt vmcnt(8)
	s_waitcnt lgkmcnt(0)
	s_barrier
	s_waitcnt lgkmcnt(0)
	v_mfma_f32_16x16x32_bf16 v[62:65], v[134:137], v[184:187], v[62:65]
	v_mfma_f32_16x16x32_bf16 v[58:61], v[142:145], v[184:187], v[58:61]
	v_mfma_f32_16x16x32_bf16 v[46:49], v[134:137], v[200:203], v[46:49]
	v_mfma_f32_16x16x32_bf16 v[42:45], v[142:145], v[200:203], v[42:45]
	v_mfma_f32_16x16x32_bf16 v[30:33], v[134:137], v[208:211], v[30:33]
	v_mfma_f32_16x16x32_bf16 v[26:29], v[142:145], v[208:211], v[26:29]
	v_mfma_f32_16x16x32_bf16 v[14:17], v[134:137], v[216:219], v[14:17]
	v_mfma_f32_16x16x32_bf16 v[10:13], v[142:145], v[216:219], v[10:13]
	v_mfma_f32_16x16x32_bf16 v[62:65], v[138:141], v[196:199], v[62:65]
	v_mfma_f32_16x16x32_bf16 v[58:61], v[146:149], v[196:199], v[58:61]
	v_mfma_f32_16x16x32_bf16 v[46:49], v[138:141], v[204:207], v[46:49]
	v_mfma_f32_16x16x32_bf16 v[42:45], v[146:149], v[204:207], v[42:45]
	v_mfma_f32_16x16x32_bf16 v[30:33], v[138:141], v[212:215], v[30:33]
	v_mfma_f32_16x16x32_bf16 v[26:29], v[146:149], v[212:215], v[26:29]
	v_mfma_f32_16x16x32_bf16 v[14:17], v[138:141], v[220:223], v[14:17]
	v_mfma_f32_16x16x32_bf16 v[10:13], v[146:149], v[220:223], v[10:13]
	v_mfma_f32_16x16x32_bf16 v[54:57], v[150:153], v[184:187], v[54:57]
	v_mfma_f32_16x16x32_bf16 v[50:53], v[176:179], v[184:187], v[50:53]
	v_mfma_f32_16x16x32_bf16 v[38:41], v[150:153], v[200:203], v[38:41]
	v_mfma_f32_16x16x32_bf16 v[34:37], v[176:179], v[200:203], v[34:37]
	v_mfma_f32_16x16x32_bf16 v[22:25], v[150:153], v[208:211], v[22:25]
	v_mfma_f32_16x16x32_bf16 v[18:21], v[176:179], v[208:211], v[18:21]
	v_mfma_f32_16x16x32_bf16 v[6:9], v[150:153], v[216:219], v[6:9]
	v_mfma_f32_16x16x32_bf16 v[2:5], v[176:179], v[216:219], v[2:5]
	v_mfma_f32_16x16x32_bf16 v[54:57], v[172:175], v[196:199], v[54:57]
	v_mfma_f32_16x16x32_bf16 v[50:53], v[180:183], v[196:199], v[50:53]
	v_mfma_f32_16x16x32_bf16 v[38:41], v[172:175], v[204:207], v[38:41]
	v_mfma_f32_16x16x32_bf16 v[34:37], v[180:183], v[204:207], v[34:37]
	v_mfma_f32_16x16x32_bf16 v[22:25], v[172:175], v[212:215], v[22:25]
	v_mfma_f32_16x16x32_bf16 v[18:21], v[180:183], v[212:215], v[18:21]
	v_mfma_f32_16x16x32_bf16 v[6:9], v[172:175], v[220:223], v[6:9]
	v_mfma_f32_16x16x32_bf16 v[2:5], v[180:183], v[220:223], v[2:5]
	s_barrier
	s_add_i32 s44, s44, 2
	s_add_u32 s38, s38, 0x100
	s_addc_u32 s39, s39, 0
	s_cmp_gt_u32 s44, 29
	s_cbranch_scc0 .LBB0_894
	s_and_b64 vcc, exec, s[12:13]
	s_cbranch_vccz .LBB0_897
	s_barrier

; #define PG8_STAGE(bufoff, gbase, RR, ld) do { _Pragma("unroll") for (int _i = 0; _i < 2; ++_i) \
;         __builtin_amdgcn_global_load_lds((const unsigned*)((const char*)(gbase) + (RR)[_i] * (ld) + C2[_i]), (LAS unsigned*)(lds + (bufoff) + ldsw + _i * 8192), 16, 0, 0); } while (0)
; #define PG8_LDA(dst, b, h) do { _Pragma("unroll") for (int m = 0; m < 4; ++m) _Pragma("unroll") for (int k = 0; k < 2; ++k) dst[m][k] = *(const LAS bf16x8*)(lds + PG8_SA(b, h) + aoff + m * 2048 + k * 1024); } while (0)
; #define PG8_LDB(dst, b, h) do { _Pragma("unroll") for (int n = 0; n < 2; ++n) _Pragma("unroll") for (int k = 0; k < 2; ++k) dst[n][k] = *(const LAS bf16x8*)(lds + PG8_SB(b, h) + boff + n * 2048 + k * 1024); } while (0)
; template <class Sched, class Epi>
; __device__ __forceinline__ void gemm_run(LAS unsigned char* lds, const Sched& S, const Epi& E) {
;     ...
;         for (int t = 0; t < nt; t += 2) {
;             const bool last = (t == nt - 2);
;             const char* a1 = cA + (size_t)(t + 1) * kstep;
;             const char* a2 = last ? nA : cA + (size_t)(t + 2) * kstep; const char* b2 = last ? nB : cB + (size_t)(t + 2) * kstep;
;             const unsigned la2 = last ? nlda : lda, lb2 = last ? nldb : ldb;
;             const char* a3 = a2 + kstep; const char* b3 = b2 + kstep;
;             PG8_LDB(B0, 0, 0); PG8_LDB(B1, 0, 1); PG8_SCHED; PG8_LDA(At, 0, 0); PG8_STAGE(PG8_SA(1, 1), a1 + (size_t)HALF * lda, RA, lda);
;             PG8_WAIT_V(8); PG8_WAIT_L(0); PG8_BAR; PG8_MMA(0, 0, At, B0); PG8_MMA(0, 1, At, B1); PG8_BAR; PG8_SCHED;
;             PG8_LDA(At, 0, 1); PG8_STAGE(PG8_SB(0, 0), b2, RB, lb2); PG8_STAGE(PG8_SB(0, 1), b2 + (size_t)HALF * lb2, RB, lb2); PG8_STAGE(PG8_SA(0, 0), a2, RA, la2);
;             PG8_WAIT_V(8); PG8_WAIT_L(0); PG8_BAR; PG8_MMA(1, 0, At, B0); PG8_MMA(1, 1, At, B1); PG8_BAR; PG8_SCHED;
;             PG8_LDB(B0, 1, 0); PG8_LDB(B1, 1, 1); PG8_SCHED; PG8_LDA(At, 1, 0); PG8_STAGE(PG8_SA(0, 1), a2 + (size_t)HALF * la2, RA, la2);
;             PG8_WAIT_V(8); PG8_WAIT_L(0); PG8_BAR; PG8_MMA(0, 0, At, B0); PG8_MMA(0, 1, At, B1); PG8_BAR; PG8_SCHED;
;             PG8_LDA(At, 1, 1); PG8_STAGE(PG8_SB(1, 0), b3, RB, lb2); PG8_STAGE(PG8_SB(1, 1), b3 + (size_t)HALF * lb2, RB, lb2); PG8_STAGE(PG8_SA(1, 0), a3, RA, la2);
;             PG8_WAIT_V(8); PG8_WAIT_L(0); PG8_BAR; PG8_MMA(1, 0, At, B0); PG8_MMA(1, 1, At, B1); PG8_BAR; PG8_SCHED;
.LBB0_998:
	s_add_u32 s15, s30, 0x100
	s_addc_u32 s54, s31, 0
	s_mov_b32 s55, -2
	s_mov_b64 s[30:31], 0
	ds_read_b128 v[156:159], v152
	ds_read_b128 v[160:163], v152 offset:1024
	ds_read_b128 v[164:167], v152 offset:2048
	ds_read_b128 v[168:171], v152 offset:3072
	ds_read_b128 v[172:175], v153
	ds_read_b128 v[176:179], v153 offset:1024
	ds_read_b128 v[180:183], v153 offset:2048
	ds_read_b128 v[184:187], v153 offset:3072
	s_add_u32 s36, s28, s30
	s_addc_u32 s37, s29, s31
	s_mov_b32 s98, s36
	s_mov_b32 s99, s37
	s_add_u32 s36, s36, 0x100
	s_addc_u32 s37, s37, 0
	s_add_u32 s56, s15, s30
	s_addc_u32 s57, s54, s31
	s_cmpk_eq_i32 s30, 0xf00
	s_cselect_b32 s39, s17, s37
	s_cselect_b32 s38, s16, s36
	s_cselect_b32 s37, s21, s57
	s_cselect_b32 s36, s20, s56
	s_mov_b64 s[100:101], s[38:39]
	s_add_i32 m0, s42, 0xc000
	ds_read_b128 v[188:191], v154
	ds_read_b128 v[192:195], v154 offset:1024
	ds_read_b128 v[196:199], v154 offset:2048
	ds_read_b128 v[200:203], v154 offset:3072
	ds_read_b128 v[204:207], v154 offset:4096
	ds_read_b128 v[208:211], v154 offset:5120
	ds_read_b128 v[212:215], v154 offset:6144
	ds_read_b128 v[216:219], v154 offset:7168
	global_load_lds_dwordx4 v142, s[98:99]
	s_add_i32 m0, s42, 0xe000
	s_nop 0
	global_load_lds_dwordx4 v144, s[98:99]
	s_waitcnt vmcnt(8)
	s_waitcnt lgkmcnt(0)
	s_barrier
	s_waitcnt lgkmcnt(0)
	v_mfma_f32_16x16x32_bf16 v[126:129], v[156:159], v[188:191], 0
	v_mfma_f32_16x16x32_bf16 v[122:125], v[164:167], v[188:191], 0
	v_mfma_f32_16x16x32_bf16 v[110:113], v[156:159], v[196:199], 0
	v_mfma_f32_16x16x32_bf16 v[106:109], v[164:167], v[196:199], 0
	v_mfma_f32_16x16x32_bf16 v[94:97], v[156:159], v[204:207], 0
	v_mfma_f32_16x16x32_bf16 v[90:93], v[164:167], v[204:207], 0
	v_mfma_f32_16x16x32_bf16 v[78:81], v[156:159], v[212:215], 0
	v_mfma_f32_16x16x32_bf16 v[74:77], v[164:167], v[212:215], 0
	v_mfma_f32_16x16x32_bf16 v[126:129], v[160:163], v[192:195], v[126:129]
	v_mfma_f32_16x16x32_bf16 v[122:125], v[168:171], v[192:195], v[122:125]
	v_mfma_f32_16x16x32_bf16 v[110:113], v[160:163], v[200:203], v[110:113]
	v_mfma_f32_16x16x32_bf16 v[106:109], v[168:171], v[200:203], v[106:109]
	v_mfma_f32_16x16x32_bf16 v[94:97], v[160:163], v[208:211], v[94:97]
	v_mfma_f32_16x16x32_bf16 v[90:93], v[168:171], v[208:211], v[90:93]
	v_mfma_f32_16x16x32_bf16 v[78:81], v[160:163], v[216:219], v[78:81]
	v_mfma_f32_16x16x32_bf16 v[74:77], v[168:171], v[216:219], v[74:77]
	v_mfma_f32_16x16x32_bf16 v[118:121], v[172:175], v[188:191], 0
	v_mfma_f32_16x16x32_bf16 v[114:117], v[180:183], v[188:191], 0
	v_mfma_f32_16x16x32_bf16 v[102:105], v[172:175], v[196:199], 0
	v_mfma_f32_16x16x32_bf16 v[98:101], v[180:183], v[196:199], 0
	v_mfma_f32_16x16x32_bf16 v[86:89], v[172:175], v[204:207], 0
	v_mfma_f32_16x16x32_bf16 v[82:85], v[180:183], v[204:207], 0
	v_mfma_f32_16x16x32_bf16 v[70:73], v[172:175], v[212:215], 0
	v_mfma_f32_16x16x32_bf16 v[66:69], v[180:183], v[212:215], 0
	v_mfma_f32_16x16x32_bf16 v[118:121], v[176:179], v[192:195], v[118:121]
	v_mfma_f32_16x16x32_bf16 v[114:117], v[184:187], v[192:195], v[114:117]
	v_mfma_f32_16x16x32_bf16 v[102:105], v[176:179], v[200:203], v[102:105]
	v_mfma_f32_16x16x32_bf16 v[98:101], v[184:187], v[200:203], v[98:101]
	v_mfma_f32_16x16x32_bf16 v[86:89], v[176:179], v[208:211], v[86:89]
	v_mfma_f32_16x16x32_bf16 v[82:85], v[184:187], v[208:211], v[82:85]
	v_mfma_f32_16x16x32_bf16 v[70:73], v[176:179], v[216:219], v[70:73]
	v_mfma_f32_16x16x32_bf16 v[66:69], v[184:187], v[216:219], v[66:69]
	s_barrier
	s_add_i32 s56, s49, s3
	s_mov_b32 m0, s56
	ds_read_b128 v[188:191], v154 offset:16384
	ds_read_b128 v[192:195], v154 offset:17408
	ds_read_b128 v[196:199], v154 offset:18432
	ds_read_b128 v[200:203], v154 offset:19456
	ds_read_b128 v[204:207], v154 offset:20480
	ds_read_b128 v[208:211], v154 offset:21504
	ds_read_b128 v[212:215], v154 offset:22528
	ds_read_b128 v[216:219], v154 offset:23552
	global_load_lds_dwordx4 v132, s[36:37]
	s_add_i32 m0, s56, 0x2000
	s_add_u32 s56, s36, 0x80000
	s_addc_u32 s57, s37, 0
	s_add_i32 s58, s50, s3
	global_load_lds_dwordx4 v136, s[36:37]
	s_mov_b32 m0, s58
	s_nop 0
	global_load_lds_dwordx4 v132, s[56:57]
	s_add_i32 m0, s58, 0x2000
	s_nop 0
	global_load_lds_dwordx4 v136, s[56:57]
	s_mov_b32 m0, s42
	s_nop 0
	global_load_lds_dwordx4 v138, s[38:39]
	s_mov_b32 m0, s43
	s_nop 0
	global_load_lds_dwordx4 v140, s[38:39]
	s_waitcnt vmcnt(8)
	s_waitcnt lgkmcnt(0)
	s_barrier
	s_waitcnt lgkmcnt(0)
	v_mfma_f32_16x16x32_bf16 v[62:65], v[156:159], v[188:191], 0
	v_mfma_f32_16x16x32_bf16 v[58:61], v[164:167], v[188:191], 0
	v_mfma_f32_16x16x32_bf16 v[46:49], v[156:159], v[196:199], 0
	v_mfma_f32_16x16x32_bf16 v[42:45], v[164:167], v[196:199], 0
	v_mfma_f32_16x16x32_bf16 v[30:33], v[156:159], v[204:207], 0
	v_mfma_f32_16x16x32_bf16 v[26:29], v[164:167], v[204:207], 0
	v_mfma_f32_16x16x32_bf16 v[14:17], v[156:159], v[212:215], 0
	v_mfma_f32_16x16x32_bf16 v[10:13], v[164:167], v[212:215], 0
	v_mfma_f32_16x16x32_bf16 v[62:65], v[160:163], v[192:195], v[62:65]
	v_mfma_f32_16x16x32_bf16 v[58:61], v[168:171], v[192:195], v[58:61]
	v_mfma_f32_16x16x32_bf16 v[46:49], v[160:163], v[200:203], v[46:49]
	v_mfma_f32_16x16x32_bf16 v[42:45], v[168:171], v[200:203], v[42:45]
	v_mfma_f32_16x16x32_bf16 v[30:33], v[160:163], v[208:211], v[30:33]
	v_mfma_f32_16x16x32_bf16 v[26:29], v[168:171], v[208:211], v[26:29]
	v_mfma_f32_16x16x32_bf16 v[14:17], v[160:163], v[216:219], v[14:17]
	v_mfma_f32_16x16x32_bf16 v[10:13], v[168:171], v[216:219], v[10:13]
	v_mfma_f32_16x16x32_bf16 v[54:57], v[172:175], v[188:191], 0
	v_mfma_f32_16x16x32_bf16 v[50:53], v[180:183], v[188:191], 0
	v_mfma_f32_16x16x32_bf16 v[38:41], v[172:175], v[196:199], 0
	v_mfma_f32_16x16x32_bf16 v[34:37], v[180:183], v[196:199], 0
	v_mfma_f32_16x16x32_bf16 v[22:25], v[172:175], v[204:207], 0
	v_mfma_f32_16x16x32_bf16 v[18:21], v[180:183], v[204:207], 0
	v_mfma_f32_16x16x32_bf16 v[6:9], v[172:175], v[212:215], 0
	v_mfma_f32_16x16x32_bf16 v[2:5], v[180:183], v[212:215], 0
	v_mfma_f32_16x16x32_bf16 v[54:57], v[176:179], v[192:195], v[54:57]
	v_mfma_f32_16x16x32_bf16 v[50:53], v[184:187], v[192:195], v[50:53]
	v_mfma_f32_16x16x32_bf16 v[38:41], v[176:179], v[200:203], v[38:41]
	v_mfma_f32_16x16x32_bf16 v[34:37], v[184:187], v[200:203], v[34:37]
	v_mfma_f32_16x16x32_bf16 v[22:25], v[176:179], v[208:211], v[22:25]
	v_mfma_f32_16x16x32_bf16 v[18:21], v[184:187], v[208:211], v[18:21]
	v_mfma_f32_16x16x32_bf16 v[6:9], v[176:179], v[216:219], v[6:9]
	v_mfma_f32_16x16x32_bf16 v[2:5], v[184:187], v[216:219], v[2:5]
	s_barrier
; #define PG8_STAGE(bufoff, gbase, RR, ld) do { _Pragma("unroll") for (int _i = 0; _i < 2; ++_i) \
;         __builtin_amdgcn_global_load_lds((const unsigned*)((const char*)(gbase) + (RR)[_i] * (ld) + C2[_i]), (LAS unsigned*)(lds + (bufoff) + ldsw + _i * 8192), 16, 0, 0); } while (0)
; #define PG8_LDA(dst, b, h) do { _Pragma("unroll") for (int m = 0; m < 4; ++m) _Pragma("unroll") for (int k = 0; k < 2; ++k) dst[m][k] = *(const LAS bf16x8*)(lds + PG8_SA(b, h) + aoff + m * 2048 + k * 1024); } while (0)
; #define PG8_LDB(dst, b, h) do { _Pragma("unroll") for (int n = 0; n < 2; ++n) _Pragma("unroll") for (int k = 0; k < 2; ++k) dst[n][k] = *(const LAS bf16x8*)(lds + PG8_SB(b, h) + boff + n * 2048 + k * 1024); } while (0)
; #define PG8_MMA(ai, bj, At, Bt) do { __builtin_amdgcn_s_setprio(1); _Pragma("unroll") for (int m = 0; m < 4; ++m) _Pragma("unroll") for (int n = 0; n < 2; ++n) _Pragma("unroll") for (int k = 0; k < 2; ++k) \
;         acc[ai][bj][m][n] = __builtin_amdgcn_mfma_f32_16x16x32_bf16(Bt[n][k], At[m][k], acc[ai][bj][m][n], 0, 0, 0); __builtin_amdgcn_s_setprio(0); } while (0)
; #define PG8_BAR __builtin_amdgcn_s_barrier()
; template <class Sched, class Epi>
; __device__ __forceinline__ void gemm_run(LAS unsigned char* lds, const Sched& S, const Epi& E) {
;     ...
;             PG8_LDB(B0, 0, 0); PG8_LDB(B1, 0, 1); PG8_SCHED; PG8_LDA(At, 0, 0); PG8_STAGE(PG8_SA(1, 1), a1 + (size_t)HALF * lda, RA, lda);
;             PG8_WAIT_V(8); PG8_WAIT_L(0); PG8_BAR; PG8_MMA(0, 0, At, B0); PG8_MMA(0, 1, At, B1); PG8_BAR; PG8_SCHED;
;             PG8_LDA(At, 0, 1); PG8_STAGE(PG8_SB(0, 0), b2, RB, lb2); PG8_STAGE(PG8_SB(0, 1), b2 + (size_t)HALF * lb2, RB, lb2); PG8_STAGE(PG8_SA(0, 0), a2, RA, la2);
;             PG8_WAIT_V(8); PG8_WAIT_L(0); PG8_BAR; PG8_MMA(1, 0, At, B0); PG8_MMA(1, 1, At, B1); PG8_BAR; PG8_SCHED;
;             PG8_LDB(B0, 1, 0); PG8_LDB(B1, 1, 1); PG8_SCHED; PG8_LDA(At, 1, 0); PG8_STAGE(PG8_SA(0, 1), a2 + (size_t)HALF * la2, RA, la2);
;             PG8_WAIT_V(8); PG8_WAIT_L(0); PG8_BAR; PG8_MMA(0, 0, At, B0); PG8_MMA(0, 1, At, B1); PG8_BAR; PG8_SCHED;
;             PG8_LDA(At, 1, 1); PG8_STAGE(PG8_SB(1, 0), b3, RB, lb2); PG8_STAGE(PG8_SB(1, 1), b3 + (size_t)HALF * lb2, RB, lb2); PG8_STAGE(PG8_SA(1, 0), a3, RA, la2);
;             PG8_WAIT_V(8); PG8_WAIT_L(0); PG8_BAR; PG8_MMA(1, 0, At, B0); PG8_MMA(1, 1, At, B1); PG8_BAR; PG8_SCHED;
;         }
	s_add_i32 s56, 0, 0x18000
	s_add_i32 s57, 0, 0x1c000
	ds_read_b128 v[156:159], v152 offset:32768
	ds_read_b128 v[160:163], v152 offset:33792
	ds_read_b128 v[164:167], v152 offset:34816
	ds_read_b128 v[168:171], v152 offset:35840
	ds_read_b128 v[172:175], v153 offset:32768
	ds_read_b128 v[176:179], v153 offset:33792
	ds_read_b128 v[180:183], v153 offset:34816
	ds_read_b128 v[184:187], v153 offset:35840
	s_add_u32 s38, s38, 0x80000
	s_addc_u32 s39, s39, 0
	s_mov_b32 m0, s44
	ds_read_b128 v[188:191], v154 offset:32768
	ds_read_b128 v[192:195], v154 offset:33792
	ds_read_b128 v[196:199], v154 offset:34816
	ds_read_b128 v[200:203], v154 offset:35840
	ds_read_b128 v[204:207], v154 offset:36864
	ds_read_b128 v[208:211], v154 offset:37888
	ds_read_b128 v[212:215], v154 offset:38912
	ds_read_b128 v[216:219], v154 offset:39936
	global_load_lds_dwordx4 v138, s[38:39]
	s_mov_b32 m0, s45
	s_nop 0
	global_load_lds_dwordx4 v140, s[38:39]
	s_waitcnt vmcnt(8)
	s_waitcnt lgkmcnt(0)
	s_barrier
	s_waitcnt lgkmcnt(0)
	v_mfma_f32_16x16x32_bf16 v[126:129], v[156:159], v[188:191], v[126:129]
	v_mfma_f32_16x16x32_bf16 v[122:125], v[164:167], v[188:191], v[122:125]
	v_mfma_f32_16x16x32_bf16 v[110:113], v[156:159], v[196:199], v[110:113]
	v_mfma_f32_16x16x32_bf16 v[106:109], v[164:167], v[196:199], v[106:109]
	v_mfma_f32_16x16x32_bf16 v[94:97], v[156:159], v[204:207], v[94:97]
	v_mfma_f32_16x16x32_bf16 v[90:93], v[164:167], v[204:207], v[90:93]
	v_mfma_f32_16x16x32_bf16 v[78:81], v[156:159], v[212:215], v[78:81]
	v_mfma_f32_16x16x32_bf16 v[74:77], v[164:167], v[212:215], v[74:77]
	v_mfma_f32_16x16x32_bf16 v[126:129], v[160:163], v[192:195], v[126:129]
	v_mfma_f32_16x16x32_bf16 v[122:125], v[168:171], v[192:195], v[122:125]
	v_mfma_f32_16x16x32_bf16 v[110:113], v[160:163], v[200:203], v[110:113]
	v_mfma_f32_16x16x32_bf16 v[106:109], v[168:171], v[200:203], v[106:109]
	v_mfma_f32_16x16x32_bf16 v[94:97], v[160:163], v[208:211], v[94:97]
	v_mfma_f32_16x16x32_bf16 v[90:93], v[168:171], v[208:211], v[90:93]
	v_mfma_f32_16x16x32_bf16 v[78:81], v[160:163], v[216:219], v[78:81]
	v_mfma_f32_16x16x32_bf16 v[74:77], v[168:171], v[216:219], v[74:77]
	v_mfma_f32_16x16x32_bf16 v[118:121], v[172:175], v[188:191], v[118:121]
	v_mfma_f32_16x16x32_bf16 v[114:117], v[180:183], v[188:191], v[114:117]
	v_mfma_f32_16x16x32_bf16 v[102:105], v[172:175], v[196:199], v[102:105]
	v_mfma_f32_16x16x32_bf16 v[98:101], v[180:183], v[196:199], v[98:101]
	v_mfma_f32_16x16x32_bf16 v[86:89], v[172:175], v[204:207], v[86:89]
	v_mfma_f32_16x16x32_bf16 v[82:85], v[180:183], v[204:207], v[82:85]
	v_mfma_f32_16x16x32_bf16 v[70:73], v[172:175], v[212:215], v[70:73]
	v_mfma_f32_16x16x32_bf16 v[66:69], v[180:183], v[212:215], v[66:69]
	v_mfma_f32_16x16x32_bf16 v[118:121], v[176:179], v[192:195], v[118:121]
	v_mfma_f32_16x16x32_bf16 v[114:117], v[184:187], v[192:195], v[114:117]
	v_mfma_f32_16x16x32_bf16 v[102:105], v[176:179], v[200:203], v[102:105]
	v_mfma_f32_16x16x32_bf16 v[98:101], v[184:187], v[200:203], v[98:101]
	v_mfma_f32_16x16x32_bf16 v[86:89], v[176:179], v[208:211], v[86:89]
	v_mfma_f32_16x16x32_bf16 v[82:85], v[184:187], v[208:211], v[82:85]
	v_mfma_f32_16x16x32_bf16 v[70:73], v[176:179], v[216:219], v[70:73]
	v_mfma_f32_16x16x32_bf16 v[66:69], v[184:187], v[216:219], v[66:69]
	s_barrier
	s_add_i32 s38, s56, s3
	s_mov_b32 m0, s38
	ds_read_b128 v[188:191], v154 offset:49152
	ds_read_b128 v[192:195], v154 offset:50176
	ds_read_b128 v[196:199], v154 offset:51200
	ds_read_b128 v[200:203], v154 offset:52224
	ds_read_b128 v[204:207], v154 offset:53248
	ds_read_b128 v[208:211], v154 offset:54272
	ds_read_b128 v[212:215], v154 offset:55296
	ds_read_b128 v[216:219], v154 offset:56320
	s_add_u32 s98, s36, 0x80
	s_addc_u32 s99, s37, 0
	global_load_lds_dwordx4 v132, s[98:99]
	s_add_i32 m0, s38, 0x2000
	s_nop 0
	global_load_lds_dwordx4 v136, s[98:99]
	s_add_u32 s36, s36, 0x80080
	s_addc_u32 s37, s37, 0
	s_add_i32 s38, s57, s3
	s_mov_b32 m0, s38
	s_nop 0
	global_load_lds_dwordx4 v132, s[36:37]
	s_add_i32 m0, s38, 0x2000
	s_nop 0
	global_load_lds_dwordx4 v136, s[36:37]
	s_mov_b32 m0, s47
	s_nop 0
	s_add_u32 s100, s100, 0x80
	s_addc_u32 s101, s101, 0
	global_load_lds_dwordx4 v138, s[100:101]
	s_mov_b32 m0, s48
	s_nop 0
	global_load_lds_dwordx4 v140, s[100:101]
	s_waitcnt vmcnt(8)
	s_waitcnt lgkmcnt(0)
	s_barrier
	s_waitcnt lgkmcnt(0)
	v_mfma_f32_16x16x32_bf16 v[62:65], v[156:159], v[188:191], v[62:65]
	v_mfma_f32_16x16x32_bf16 v[58:61], v[164:167], v[188:191], v[58:61]
	v_mfma_f32_16x16x32_bf16 v[46:49], v[156:159], v[196:199], v[46:49]
	v_mfma_f32_16x16x32_bf16 v[42:45], v[164:167], v[196:199], v[42:45]
	v_mfma_f32_16x16x32_bf16 v[30:33], v[156:159], v[204:207], v[30:33]
	v_mfma_f32_16x16x32_bf16 v[26:29], v[164:167], v[204:207], v[26:29]
	v_mfma_f32_16x16x32_bf16 v[14:17], v[156:159], v[212:215], v[14:17]
	v_mfma_f32_16x16x32_bf16 v[10:13], v[164:167], v[212:215], v[10:13]
	v_mfma_f32_16x16x32_bf16 v[62:65], v[160:163], v[192:195], v[62:65]
	v_mfma_f32_16x16x32_bf16 v[58:61], v[168:171], v[192:195], v[58:61]
	v_mfma_f32_16x16x32_bf16 v[46:49], v[160:163], v[200:203], v[46:49]
	v_mfma_f32_16x16x32_bf16 v[42:45], v[168:171], v[200:203], v[42:45]
	v_mfma_f32_16x16x32_bf16 v[30:33], v[160:163], v[208:211], v[30:33]
	v_mfma_f32_16x16x32_bf16 v[26:29], v[168:171], v[208:211], v[26:29]
	v_mfma_f32_16x16x32_bf16 v[14:17], v[160:163], v[216:219], v[14:17]
	v_mfma_f32_16x16x32_bf16 v[10:13], v[168:171], v[216:219], v[10:13]
	v_mfma_f32_16x16x32_bf16 v[54:57], v[172:175], v[188:191], v[54:57]
	v_mfma_f32_16x16x32_bf16 v[50:53], v[180:183], v[188:191], v[50:53]
	v_mfma_f32_16x16x32_bf16 v[38:41], v[172:175], v[196:199], v[38:41]
	v_mfma_f32_16x16x32_bf16 v[34:37], v[180:183], v[196:199], v[34:37]
	v_mfma_f32_16x16x32_bf16 v[22:25], v[172:175], v[204:207], v[22:25]
	v_mfma_f32_16x16x32_bf16 v[18:21], v[180:183], v[204:207], v[18:21]
	v_mfma_f32_16x16x32_bf16 v[6:9], v[172:175], v[212:215], v[6:9]
	v_mfma_f32_16x16x32_bf16 v[2:5], v[180:183], v[212:215], v[2:5]
	v_mfma_f32_16x16x32_bf16 v[54:57], v[176:179], v[192:195], v[54:57]
	v_mfma_f32_16x16x32_bf16 v[50:53], v[184:187], v[192:195], v[50:53]
	v_mfma_f32_16x16x32_bf16 v[38:41], v[176:179], v[200:203], v[38:41]
	v_mfma_f32_16x16x32_bf16 v[34:37], v[184:187], v[200:203], v[34:37]
	v_mfma_f32_16x16x32_bf16 v[22:25], v[176:179], v[208:211], v[22:25]
	v_mfma_f32_16x16x32_bf16 v[18:21], v[184:187], v[208:211], v[18:21]
	v_mfma_f32_16x16x32_bf16 v[6:9], v[176:179], v[216:219], v[6:9]
	v_mfma_f32_16x16x32_bf16 v[2:5], v[184:187], v[216:219], v[2:5]
	s_barrier
	s_add_i32 s55, s55, 2
	s_add_u32 s30, s30, 0x100
	s_addc_u32 s31, s31, 0
	s_cmp_gt_u32 s55, 29
	s_cbranch_scc0 .LBB0_999
	.p2align 6
; #define PG8_STAGE(bufoff, gbase, RR, ld) do { _Pragma("unroll") for (int _i = 0; _i < 2; ++_i) \
;         __builtin_amdgcn_global_load_lds((const unsigned*)((const char*)(gbase) + (RR)[_i] * (ld) + C2[_i]), (LAS unsigned*)(lds + (bufoff) + ldsw + _i * 8192), 16, 0, 0); } while (0)
; #define PG8_LDA(dst, b, h) do { _Pragma("unroll") for (int m = 0; m < 4; ++m) _Pragma("unroll") for (int k = 0; k < 2; ++k) dst[m][k] = *(const LAS bf16x8*)(lds + PG8_SA(b, h) + aoff + m * 2048 + k * 1024); } while (0)
; #define PG8_LDB(dst, b, h) do { _Pragma("unroll") for (int n = 0; n < 2; ++n) _Pragma("unroll") for (int k = 0; k < 2; ++k) dst[n][k] = *(const LAS bf16x8*)(lds + PG8_SB(b, h) + boff + n * 2048 + k * 1024); } while (0)
; #define PG8_MMA(ai, bj, At, Bt) do { __builtin_amdgcn_s_setprio(1); _Pragma("unroll") for (int m = 0; m < 4; ++m) _Pragma("unroll") for (int n = 0; n < 2; ++n) _Pragma("unroll") for (int k = 0; k < 2; ++k) \
;         acc[ai][bj][m][n] = __builtin_amdgcn_mfma_f32_16x16x32_bf16(Bt[n][k], At[m][k], acc[ai][bj][m][n], 0, 0, 0); __builtin_amdgcn_s_setprio(0); } while (0)
; #define PG8_WAIT_V(n) asm volatile("s_waitcnt vmcnt(" #n ")" ::: "memory")
; #define PG8_WAIT_L(n) asm volatile("s_waitcnt lgkmcnt(" #n ")" ::: "memory")
; #define PG8_BAR __builtin_amdgcn_s_barrier()
; #define PG8_SCHED __builtin_amdgcn_sched_barrier(0)
; template <class Sched, class Epi>
; __device__ __forceinline__ void gemm_run(LAS unsigned char* lds, const Sched& S, const Epi& E) {
;     ...
;             PG8_LDB(B0, 0, 0); PG8_LDB(B1, 0, 1); PG8_SCHED; PG8_LDA(At, 0, 0); PG8_STAGE(PG8_SA(1, 1), a1 + (size_t)HALF * lda, RA, lda);
;             PG8_WAIT_V(8); PG8_WAIT_L(0); PG8_BAR; PG8_MMA(0, 0, At, B0); PG8_MMA(0, 1, At, B1); PG8_BAR; PG8_SCHED;
;             PG8_LDA(At, 0, 1); PG8_STAGE(PG8_SB(0, 0), b2, RB, lb2); PG8_STAGE(PG8_SB(0, 1), b2 + (size_t)HALF * lb2, RB, lb2); PG8_STAGE(PG8_SA(0, 0), a2, RA, la2);
;             PG8_WAIT_V(8); PG8_WAIT_L(0); PG8_BAR; PG8_MMA(1, 0, At, B0); PG8_MMA(1, 1, At, B1); PG8_BAR; PG8_SCHED;
;             PG8_LDB(B0, 1, 0); PG8_LDB(B1, 1, 1); PG8_SCHED; PG8_LDA(At, 1, 0); PG8_STAGE(PG8_SA(0, 1), a2 + (size_t)HALF * la2, RA, la2);
;             PG8_WAIT_V(8); PG8_WAIT_L(0); PG8_BAR; PG8_MMA(0, 0, At, B0); PG8_MMA(0, 1, At, B1); PG8_BAR; PG8_SCHED;
.LBB0_999:
	ds_read_b128 v[156:159], v152
	ds_read_b128 v[160:163], v152 offset:1024
	ds_read_b128 v[164:167], v152 offset:2048
	ds_read_b128 v[168:171], v152 offset:3072
	ds_read_b128 v[172:175], v153
	ds_read_b128 v[176:179], v153 offset:1024
	ds_read_b128 v[180:183], v153 offset:2048
	ds_read_b128 v[184:187], v153 offset:3072
	s_add_u32 s36, s28, s30
	s_addc_u32 s37, s29, s31
	s_mov_b32 s98, s36
	s_mov_b32 s99, s37
	s_add_u32 s36, s36, 0x100
	s_addc_u32 s37, s37, 0
	s_add_u32 s56, s15, s30
	s_addc_u32 s57, s54, s31
	s_cmpk_eq_i32 s30, 0xf00
	s_cselect_b32 s39, s17, s37
	s_cselect_b32 s38, s16, s36
	s_cselect_b32 s37, s21, s57
	s_cselect_b32 s36, s20, s56
	s_mov_b64 s[100:101], s[38:39]
	s_add_i32 m0, s42, 0xc000
	ds_read_b128 v[188:191], v154
	ds_read_b128 v[192:195], v154 offset:1024
	ds_read_b128 v[196:199], v154 offset:2048
	ds_read_b128 v[200:203], v154 offset:3072
	ds_read_b128 v[204:207], v154 offset:4096
	ds_read_b128 v[208:211], v154 offset:5120
	ds_read_b128 v[212:215], v154 offset:6144
	ds_read_b128 v[216:219], v154 offset:7168
	global_load_lds_dwordx4 v142, s[98:99]
	s_add_i32 m0, s42, 0xe000
	s_nop 0
	global_load_lds_dwordx4 v144, s[98:99]
	s_waitcnt vmcnt(8)
	s_waitcnt lgkmcnt(0)
	s_barrier
	s_waitcnt lgkmcnt(0)
	v_mfma_f32_16x16x32_bf16 v[126:129], v[156:159], v[188:191], v[126:129]
	v_mfma_f32_16x16x32_bf16 v[122:125], v[164:167], v[188:191], v[122:125]
	v_mfma_f32_16x16x32_bf16 v[110:113], v[156:159], v[196:199], v[110:113]
	v_mfma_f32_16x16x32_bf16 v[106:109], v[164:167], v[196:199], v[106:109]
	v_mfma_f32_16x16x32_bf16 v[94:97], v[156:159], v[204:207], v[94:97]
	v_mfma_f32_16x16x32_bf16 v[90:93], v[164:167], v[204:207], v[90:93]
	v_mfma_f32_16x16x32_bf16 v[78:81], v[156:159], v[212:215], v[78:81]
	v_mfma_f32_16x16x32_bf16 v[74:77], v[164:167], v[212:215], v[74:77]
	v_mfma_f32_16x16x32_bf16 v[126:129], v[160:163], v[192:195], v[126:129]
	v_mfma_f32_16x16x32_bf16 v[122:125], v[168:171], v[192:195], v[122:125]
	v_mfma_f32_16x16x32_bf16 v[110:113], v[160:163], v[200:203], v[110:113]
	v_mfma_f32_16x16x32_bf16 v[106:109], v[168:171], v[200:203], v[106:109]
	v_mfma_f32_16x16x32_bf16 v[94:97], v[160:163], v[208:211], v[94:97]
	v_mfma_f32_16x16x32_bf16 v[90:93], v[168:171], v[208:211], v[90:93]
	v_mfma_f32_16x16x32_bf16 v[78:81], v[160:163], v[216:219], v[78:81]
	v_mfma_f32_16x16x32_bf16 v[74:77], v[168:171], v[216:219], v[74:77]
	v_mfma_f32_16x16x32_bf16 v[118:121], v[172:175], v[188:191], v[118:121]
	v_mfma_f32_16x16x32_bf16 v[114:117], v[180:183], v[188:191], v[114:117]
	v_mfma_f32_16x16x32_bf16 v[102:105], v[172:175], v[196:199], v[102:105]
	v_mfma_f32_16x16x32_bf16 v[98:101], v[180:183], v[196:199], v[98:101]
	v_mfma_f32_16x16x32_bf16 v[86:89], v[172:175], v[204:207], v[86:89]
	v_mfma_f32_16x16x32_bf16 v[82:85], v[180:183], v[204:207], v[82:85]
	v_mfma_f32_16x16x32_bf16 v[70:73], v[172:175], v[212:215], v[70:73]
	v_mfma_f32_16x16x32_bf16 v[66:69], v[180:183], v[212:215], v[66:69]
	v_mfma_f32_16x16x32_bf16 v[118:121], v[176:179], v[192:195], v[118:121]
	v_mfma_f32_16x16x32_bf16 v[114:117], v[184:187], v[192:195], v[114:117]
	v_mfma_f32_16x16x32_bf16 v[102:105], v[176:179], v[200:203], v[102:105]
	v_mfma_f32_16x16x32_bf16 v[98:101], v[184:187], v[200:203], v[98:101]
	v_mfma_f32_16x16x32_bf16 v[86:89], v[176:179], v[208:211], v[86:89]
	v_mfma_f32_16x16x32_bf16 v[82:85], v[184:187], v[208:211], v[82:85]
	v_mfma_f32_16x16x32_bf16 v[70:73], v[176:179], v[216:219], v[70:73]
	v_mfma_f32_16x16x32_bf16 v[66:69], v[184:187], v[216:219], v[66:69]
	s_barrier
	s_add_i32 s56, s49, s3
	s_mov_b32 m0, s56
	ds_read_b128 v[188:191], v154 offset:16384
	ds_read_b128 v[192:195], v154 offset:17408
	ds_read_b128 v[196:199], v154 offset:18432
	ds_read_b128 v[200:203], v154 offset:19456
	ds_read_b128 v[204:207], v154 offset:20480
	ds_read_b128 v[208:211], v154 offset:21504
	ds_read_b128 v[212:215], v154 offset:22528
	ds_read_b128 v[216:219], v154 offset:23552
	global_load_lds_dwordx4 v132, s[36:37]
	s_add_i32 m0, s56, 0x2000
	s_add_u32 s56, s36, 0x80000
	s_addc_u32 s57, s37, 0
	s_add_i32 s58, s50, s3
	global_load_lds_dwordx4 v136, s[36:37]
	s_mov_b32 m0, s58
	s_nop 0
	global_load_lds_dwordx4 v132, s[56:57]
	s_add_i32 m0, s58, 0x2000
	s_nop 0
	global_load_lds_dwordx4 v136, s[56:57]
	s_mov_b32 m0, s42
	s_nop 0
	global_load_lds_dwordx4 v138, s[38:39]
	s_mov_b32 m0, s43
	s_nop 0
	global_load_lds_dwordx4 v140, s[38:39]
	s_waitcnt vmcnt(8)
	s_waitcnt lgkmcnt(0)
	s_barrier
	s_waitcnt lgkmcnt(0)
	v_mfma_f32_16x16x32_bf16 v[62:65], v[156:159], v[188:191], v[62:65]
	v_mfma_f32_16x16x32_bf16 v[58:61], v[164:167], v[188:191], v[58:61]
	v_mfma_f32_16x16x32_bf16 v[46:49], v[156:159], v[196:199], v[46:49]
	v_mfma_f32_16x16x32_bf16 v[42:45], v[164:167], v[196:199], v[42:45]
	v_mfma_f32_16x16x32_bf16 v[30:33], v[156:159], v[204:207], v[30:33]
	v_mfma_f32_16x16x32_bf16 v[26:29], v[164:167], v[204:207], v[26:29]
	v_mfma_f32_16x16x32_bf16 v[14:17], v[156:159], v[212:215], v[14:17]
	v_mfma_f32_16x16x32_bf16 v[10:13], v[164:167], v[212:215], v[10:13]
	v_mfma_f32_16x16x32_bf16 v[62:65], v[160:163], v[192:195], v[62:65]
	v_mfma_f32_16x16x32_bf16 v[58:61], v[168:171], v[192:195], v[58:61]
	v_mfma_f32_16x16x32_bf16 v[46:49], v[160:163], v[200:203], v[46:49]
	v_mfma_f32_16x16x32_bf16 v[42:45], v[168:171], v[200:203], v[42:45]
	v_mfma_f32_16x16x32_bf16 v[30:33], v[160:163], v[208:211], v[30:33]
	v_mfma_f32_16x16x32_bf16 v[26:29], v[168:171], v[208:211], v[26:29]
	v_mfma_f32_16x16x32_bf16 v[14:17], v[160:163], v[216:219], v[14:17]
	v_mfma_f32_16x16x32_bf16 v[10:13], v[168:171], v[216:219], v[10:13]
	v_mfma_f32_16x16x32_bf16 v[54:57], v[172:175], v[188:191], v[54:57]
	v_mfma_f32_16x16x32_bf16 v[50:53], v[180:183], v[188:191], v[50:53]
	v_mfma_f32_16x16x32_bf16 v[38:41], v[172:175], v[196:199], v[38:41]
	v_mfma_f32_16x16x32_bf16 v[34:37], v[180:183], v[196:199], v[34:37]
	v_mfma_f32_16x16x32_bf16 v[22:25], v[172:175], v[204:207], v[22:25]
	v_mfma_f32_16x16x32_bf16 v[18:21], v[180:183], v[204:207], v[18:21]
	v_mfma_f32_16x16x32_bf16 v[6:9], v[172:175], v[212:215], v[6:9]
	v_mfma_f32_16x16x32_bf16 v[2:5], v[180:183], v[212:215], v[2:5]
	v_mfma_f32_16x16x32_bf16 v[54:57], v[176:179], v[192:195], v[54:57]
	v_mfma_f32_16x16x32_bf16 v[50:53], v[184:187], v[192:195], v[50:53]
	v_mfma_f32_16x16x32_bf16 v[38:41], v[176:179], v[200:203], v[38:41]
	v_mfma_f32_16x16x32_bf16 v[34:37], v[184:187], v[200:203], v[34:37]
	v_mfma_f32_16x16x32_bf16 v[22:25], v[176:179], v[208:211], v[22:25]
	v_mfma_f32_16x16x32_bf16 v[18:21], v[184:187], v[208:211], v[18:21]
	v_mfma_f32_16x16x32_bf16 v[6:9], v[176:179], v[216:219], v[6:9]
	v_mfma_f32_16x16x32_bf16 v[2:5], v[184:187], v[216:219], v[2:5]
	s_barrier
; #define PG8_STAGE(bufoff, gbase, RR, ld) do { _Pragma("unroll") for (int _i = 0; _i < 2; ++_i) \
;         __builtin_amdgcn_global_load_lds((const unsigned*)((const char*)(gbase) + (RR)[_i] * (ld) + C2[_i]), (LAS unsigned*)(lds + (bufoff) + ldsw + _i * 8192), 16, 0, 0); } while (0)
; #define PG8_LDA(dst, b, h) do { _Pragma("unroll") for (int m = 0; m < 4; ++m) _Pragma("unroll") for (int k = 0; k < 2; ++k) dst[m][k] = *(const LAS bf16x8*)(lds + PG8_SA(b, h) + aoff + m * 2048 + k * 1024); } while (0)
; #define PG8_LDB(dst, b, h) do { _Pragma("unroll") for (int n = 0; n < 2; ++n) _Pragma("unroll") for (int k = 0; k < 2; ++k) dst[n][k] = *(const LAS bf16x8*)(lds + PG8_SB(b, h) + boff + n * 2048 + k * 1024); } while (0)
; #define PG8_MMA(ai, bj, At, Bt) do { __builtin_amdgcn_s_setprio(1); _Pragma("unroll") for (int m = 0; m < 4; ++m) _Pragma("unroll") for (int n = 0; n < 2; ++n) _Pragma("unroll") for (int k = 0; k < 2; ++k) \
;         acc[ai][bj][m][n] = __builtin_amdgcn_mfma_f32_16x16x32_bf16(Bt[n][k], At[m][k], acc[ai][bj][m][n], 0, 0, 0); __builtin_amdgcn_s_setprio(0); } while (0)
; #define PG8_WAIT_V(n) asm volatile("s_waitcnt vmcnt(" #n ")" ::: "memory")
; #define PG8_WAIT_L(n) asm volatile("s_waitcnt lgkmcnt(" #n ")" ::: "memory")
; #define PG8_BAR __builtin_amdgcn_s_barrier()
; #define PG8_SCHED __builtin_amdgcn_sched_barrier(0)
; template <class Sched, class Epi>
; __device__ __forceinline__ void gemm_run(LAS unsigned char* lds, const Sched& S, const Epi& E) {
;     ...
;             PG8_LDB(B0, 1, 0); PG8_LDB(B1, 1, 1); PG8_SCHED; PG8_LDA(At, 1, 0); PG8_STAGE(PG8_SA(0, 1), a2 + (size_t)HALF * la2, RA, la2);
;             PG8_WAIT_V(8); PG8_WAIT_L(0); PG8_BAR; PG8_MMA(0, 0, At, B0); PG8_MMA(0, 1, At, B1); PG8_BAR; PG8_SCHED;
;             PG8_LDA(At, 1, 1); PG8_STAGE(PG8_SB(1, 0), b3, RB, lb2); PG8_STAGE(PG8_SB(1, 1), b3 + (size_t)HALF * lb2, RB, lb2); PG8_STAGE(PG8_SA(1, 0), a3, RA, la2);
;             PG8_WAIT_V(8); PG8_WAIT_L(0); PG8_BAR; PG8_MMA(1, 0, At, B0); PG8_MMA(1, 1, At, B1); PG8_BAR; PG8_SCHED;
;         }
;         if (wr == 0) PG8_BAR;
	s_add_i32 s56, 0, 0x18000
	s_add_i32 s57, 0, 0x1c000
	ds_read_b128 v[156:159], v152 offset:32768
	ds_read_b128 v[160:163], v152 offset:33792
	ds_read_b128 v[164:167], v152 offset:34816
	ds_read_b128 v[168:171], v152 offset:35840
	ds_read_b128 v[172:175], v153 offset:32768
	ds_read_b128 v[176:179], v153 offset:33792
	ds_read_b128 v[180:183], v153 offset:34816
	ds_read_b128 v[184:187], v153 offset:35840
	s_add_u32 s38, s38, 0x80000
	s_addc_u32 s39, s39, 0
	s_mov_b32 m0, s44
	ds_read_b128 v[188:191], v154 offset:32768
	ds_read_b128 v[192:195], v154 offset:33792
	ds_read_b128 v[196:199], v154 offset:34816
	ds_read_b128 v[200:203], v154 offset:35840
	ds_read_b128 v[204:207], v154 offset:36864
	ds_read_b128 v[208:211], v154 offset:37888
	ds_read_b128 v[212:215], v154 offset:38912
	ds_read_b128 v[216:219], v154 offset:39936
	global_load_lds_dwordx4 v138, s[38:39]
	s_mov_b32 m0, s45
	s_nop 0
	global_load_lds_dwordx4 v140, s[38:39]
	s_waitcnt vmcnt(8)
	s_waitcnt lgkmcnt(0)
	s_barrier
	s_waitcnt lgkmcnt(0)
	v_mfma_f32_16x16x32_bf16 v[126:129], v[156:159], v[188:191], v[126:129]
	v_mfma_f32_16x16x32_bf16 v[122:125], v[164:167], v[188:191], v[122:125]
	v_mfma_f32_16x16x32_bf16 v[110:113], v[156:159], v[196:199], v[110:113]
	v_mfma_f32_16x16x32_bf16 v[106:109], v[164:167], v[196:199], v[106:109]
	v_mfma_f32_16x16x32_bf16 v[94:97], v[156:159], v[204:207], v[94:97]
	v_mfma_f32_16x16x32_bf16 v[90:93], v[164:167], v[204:207], v[90:93]
	v_mfma_f32_16x16x32_bf16 v[78:81], v[156:159], v[212:215], v[78:81]
	v_mfma_f32_16x16x32_bf16 v[74:77], v[164:167], v[212:215], v[74:77]
	v_mfma_f32_16x16x32_bf16 v[126:129], v[160:163], v[192:195], v[126:129]
	v_mfma_f32_16x16x32_bf16 v[122:125], v[168:171], v[192:195], v[122:125]
	v_mfma_f32_16x16x32_bf16 v[110:113], v[160:163], v[200:203], v[110:113]
	v_mfma_f32_16x16x32_bf16 v[106:109], v[168:171], v[200:203], v[106:109]
	v_mfma_f32_16x16x32_bf16 v[94:97], v[160:163], v[208:211], v[94:97]
	v_mfma_f32_16x16x32_bf16 v[90:93], v[168:171], v[208:211], v[90:93]
	v_mfma_f32_16x16x32_bf16 v[78:81], v[160:163], v[216:219], v[78:81]
	v_mfma_f32_16x16x32_bf16 v[74:77], v[168:171], v[216:219], v[74:77]
	v_mfma_f32_16x16x32_bf16 v[118:121], v[172:175], v[188:191], v[118:121]
	v_mfma_f32_16x16x32_bf16 v[114:117], v[180:183], v[188:191], v[114:117]
	v_mfma_f32_16x16x32_bf16 v[102:105], v[172:175], v[196:199], v[102:105]
	v_mfma_f32_16x16x32_bf16 v[98:101], v[180:183], v[196:199], v[98:101]
	v_mfma_f32_16x16x32_bf16 v[86:89], v[172:175], v[204:207], v[86:89]
	v_mfma_f32_16x16x32_bf16 v[82:85], v[180:183], v[204:207], v[82:85]
	v_mfma_f32_16x16x32_bf16 v[70:73], v[172:175], v[212:215], v[70:73]
	v_mfma_f32_16x16x32_bf16 v[66:69], v[180:183], v[212:215], v[66:69]
	v_mfma_f32_16x16x32_bf16 v[118:121], v[176:179], v[192:195], v[118:121]
	v_mfma_f32_16x16x32_bf16 v[114:117], v[184:187], v[192:195], v[114:117]
	v_mfma_f32_16x16x32_bf16 v[102:105], v[176:179], v[200:203], v[102:105]
	v_mfma_f32_16x16x32_bf16 v[98:101], v[184:187], v[200:203], v[98:101]
	v_mfma_f32_16x16x32_bf16 v[86:89], v[176:179], v[208:211], v[86:89]
	v_mfma_f32_16x16x32_bf16 v[82:85], v[184:187], v[208:211], v[82:85]
	v_mfma_f32_16x16x32_bf16 v[70:73], v[176:179], v[216:219], v[70:73]
	v_mfma_f32_16x16x32_bf16 v[66:69], v[184:187], v[216:219], v[66:69]
	s_barrier
	s_add_i32 s38, s56, s3
	s_mov_b32 m0, s38
	ds_read_b128 v[188:191], v154 offset:49152
	ds_read_b128 v[192:195], v154 offset:50176
	ds_read_b128 v[196:199], v154 offset:51200
	ds_read_b128 v[200:203], v154 offset:52224
	ds_read_b128 v[204:207], v154 offset:53248
	ds_read_b128 v[208:211], v154 offset:54272
	ds_read_b128 v[212:215], v154 offset:55296
	ds_read_b128 v[216:219], v154 offset:56320
	s_add_u32 s98, s36, 0x80
	s_addc_u32 s99, s37, 0
	global_load_lds_dwordx4 v132, s[98:99]
	s_add_i32 m0, s38, 0x2000
	s_nop 0
	global_load_lds_dwordx4 v136, s[98:99]
	s_add_u32 s36, s36, 0x80080
	s_addc_u32 s37, s37, 0
	s_add_i32 s38, s57, s3
	s_mov_b32 m0, s38
	s_nop 0
	global_load_lds_dwordx4 v132, s[36:37]
	s_add_i32 m0, s38, 0x2000
	s_nop 0
	global_load_lds_dwordx4 v136, s[36:37]
	s_mov_b32 m0, s47
	s_nop 0
	s_add_u32 s100, s100, 0x80
	s_addc_u32 s101, s101, 0
	global_load_lds_dwordx4 v138, s[100:101]
	s_mov_b32 m0, s48
	s_nop 0
	global_load_lds_dwordx4 v140, s[100:101]
	s_waitcnt vmcnt(8)
	s_waitcnt lgkmcnt(0)
	s_barrier
	s_waitcnt lgkmcnt(0)
	v_mfma_f32_16x16x32_bf16 v[62:65], v[156:159], v[188:191], v[62:65]
	v_mfma_f32_16x16x32_bf16 v[58:61], v[164:167], v[188:191], v[58:61]
	v_mfma_f32_16x16x32_bf16 v[46:49], v[156:159], v[196:199], v[46:49]
	v_mfma_f32_16x16x32_bf16 v[42:45], v[164:167], v[196:199], v[42:45]
	v_mfma_f32_16x16x32_bf16 v[30:33], v[156:159], v[204:207], v[30:33]
	v_mfma_f32_16x16x32_bf16 v[26:29], v[164:167], v[204:207], v[26:29]
	v_mfma_f32_16x16x32_bf16 v[14:17], v[156:159], v[212:215], v[14:17]
	v_mfma_f32_16x16x32_bf16 v[10:13], v[164:167], v[212:215], v[10:13]
	v_mfma_f32_16x16x32_bf16 v[62:65], v[160:163], v[192:195], v[62:65]
	v_mfma_f32_16x16x32_bf16 v[58:61], v[168:171], v[192:195], v[58:61]
	v_mfma_f32_16x16x32_bf16 v[46:49], v[160:163], v[200:203], v[46:49]
	v_mfma_f32_16x16x32_bf16 v[42:45], v[168:171], v[200:203], v[42:45]
	v_mfma_f32_16x16x32_bf16 v[30:33], v[160:163], v[208:211], v[30:33]
	v_mfma_f32_16x16x32_bf16 v[26:29], v[168:171], v[208:211], v[26:29]
	v_mfma_f32_16x16x32_bf16 v[14:17], v[160:163], v[216:219], v[14:17]
	v_mfma_f32_16x16x32_bf16 v[10:13], v[168:171], v[216:219], v[10:13]
	v_mfma_f32_16x16x32_bf16 v[54:57], v[172:175], v[188:191], v[54:57]
	v_mfma_f32_16x16x32_bf16 v[50:53], v[180:183], v[188:191], v[50:53]
	v_mfma_f32_16x16x32_bf16 v[38:41], v[172:175], v[196:199], v[38:41]
	v_mfma_f32_16x16x32_bf16 v[34:37], v[180:183], v[196:199], v[34:37]
	v_mfma_f32_16x16x32_bf16 v[22:25], v[172:175], v[204:207], v[22:25]
	v_mfma_f32_16x16x32_bf16 v[18:21], v[180:183], v[204:207], v[18:21]
	v_mfma_f32_16x16x32_bf16 v[6:9], v[172:175], v[212:215], v[6:9]
	v_mfma_f32_16x16x32_bf16 v[2:5], v[180:183], v[212:215], v[2:5]
	v_mfma_f32_16x16x32_bf16 v[54:57], v[176:179], v[192:195], v[54:57]
	v_mfma_f32_16x16x32_bf16 v[50:53], v[184:187], v[192:195], v[50:53]
	v_mfma_f32_16x16x32_bf16 v[38:41], v[176:179], v[200:203], v[38:41]
	v_mfma_f32_16x16x32_bf16 v[34:37], v[184:187], v[200:203], v[34:37]
	v_mfma_f32_16x16x32_bf16 v[22:25], v[176:179], v[208:211], v[22:25]
	v_mfma_f32_16x16x32_bf16 v[18:21], v[184:187], v[208:211], v[18:21]
	v_mfma_f32_16x16x32_bf16 v[6:9], v[176:179], v[216:219], v[6:9]
	v_mfma_f32_16x16x32_bf16 v[2:5], v[184:187], v[216:219], v[2:5]
	s_barrier
	s_add_i32 s55, s55, 2
	s_add_u32 s30, s30, 0x100
	s_addc_u32 s31, s31, 0
	s_cmp_gt_u32 s55, 29
	s_cbranch_scc0 .LBB0_999
	s_and_b64 vcc, exec, s[8:9]
	s_cbranch_vccz .LBB0_1002
	s_barrier

; #define PG8_STAGE(bufoff, gbase, RR, ld) do { _Pragma("unroll") for (int _i = 0; _i < 2; ++_i) \
;         __builtin_amdgcn_global_load_lds((const unsigned*)((const char*)(gbase) + (RR)[_i] * (ld) + C2[_i]), (LAS unsigned*)(lds + (bufoff) + ldsw + _i * 8192), 16, 0, 0); } while (0)
; #define PG8_LDA(dst, b, h) do { _Pragma("unroll") for (int m = 0; m < 4; ++m) _Pragma("unroll") for (int k = 0; k < 2; ++k) dst[m][k] = *(const LAS bf16x8*)(lds + PG8_SA(b, h) + aoff + m * 2048 + k * 1024); } while (0)
; #define PG8_LDB(dst, b, h) do { _Pragma("unroll") for (int n = 0; n < 2; ++n) _Pragma("unroll") for (int k = 0; k < 2; ++k) dst[n][k] = *(const LAS bf16x8*)(lds + PG8_SB(b, h) + boff + n * 2048 + k * 1024); } while (0)
; #define PG8_MMA(ai, bj, At, Bt) do { __builtin_amdgcn_s_setprio(1); _Pragma("unroll") for (int m = 0; m < 4; ++m) _Pragma("unroll") for (int n = 0; n < 2; ++n) _Pragma("unroll") for (int k = 0; k < 2; ++k) \
;         acc[ai][bj][m][n] = __builtin_amdgcn_mfma_f32_16x16x32_bf16(Bt[n][k], At[m][k], acc[ai][bj][m][n], 0, 0, 0); __builtin_amdgcn_s_setprio(0); } while (0)
; #define PG8_WAIT_V(n) asm volatile("s_waitcnt vmcnt(" #n ")" ::: "memory")
; #define PG8_WAIT_L(n) asm volatile("s_waitcnt lgkmcnt(" #n ")" ::: "memory")
; #define PG8_BAR __builtin_amdgcn_s_barrier()
; #define PG8_SCHED __builtin_amdgcn_sched_barrier(0)
; template <class Sched, class Epi>
; __device__ __forceinline__ void gemm_run(LAS unsigned char* lds, const Sched& S, const Epi& E) {
;     ...
;             PG8_LDB(B0, 0, 0); PG8_LDB(B1, 0, 1); PG8_SCHED; PG8_LDA(At, 0, 0); PG8_STAGE(PG8_SA(1, 1), a1 + (size_t)HALF * lda, RA, lda);
;             PG8_WAIT_V(8); PG8_WAIT_L(0); PG8_BAR; PG8_MMA(0, 0, At, B0); PG8_MMA(0, 1, At, B1); PG8_BAR; PG8_SCHED;
;             PG8_LDA(At, 0, 1); PG8_STAGE(PG8_SB(0, 0), b2, RB, lb2); PG8_STAGE(PG8_SB(0, 1), b2 + (size_t)HALF * lb2, RB, lb2); PG8_STAGE(PG8_SA(0, 0), a2, RA, la2);
;             PG8_WAIT_V(8); PG8_WAIT_L(0); PG8_BAR; PG8_MMA(1, 0, At, B0); PG8_MMA(1, 1, At, B1); PG8_BAR; PG8_SCHED;
;             PG8_LDB(B0, 1, 0); PG8_LDB(B1, 1, 1); PG8_SCHED; PG8_LDA(At, 1, 0); PG8_STAGE(PG8_SA(0, 1), a2 + (size_t)HALF * la2, RA, la2);
;             PG8_WAIT_V(8); PG8_WAIT_L(0); PG8_BAR; PG8_MMA(0, 0, At, B0); PG8_MMA(0, 1, At, B1); PG8_BAR; PG8_SCHED;
.LBB0_1124:
	ds_read_b128 v[154:157], v150
	ds_read_b128 v[158:161], v150 offset:1024
	ds_read_b128 v[162:165], v150 offset:2048
	ds_read_b128 v[166:169], v150 offset:3072
	ds_read_b128 v[170:173], v151
	ds_read_b128 v[174:177], v151 offset:1024
	ds_read_b128 v[178:181], v151 offset:2048
	ds_read_b128 v[182:185], v151 offset:3072
	s_add_u32 s36, s28, s30
	s_addc_u32 s37, s29, s31
	s_mov_b32 s98, s36
	s_mov_b32 s99, s37
	s_add_u32 s36, s36, 0x100
	s_addc_u32 s37, s37, 0
	s_add_u32 s58, s55, s30
	s_addc_u32 s59, s56, s31
	s_cmpk_eq_i32 s30, 0x2b00
	s_cselect_b32 s39, s19, s37
	s_cselect_b32 s38, s18, s36
	s_cselect_b32 s37, s23, s59
	s_cselect_b32 s36, s22, s58
	s_mov_b64 s[100:101], s[38:39]
	s_add_i32 m0, s33, 0xc000
	ds_read_b128 v[186:189], v152
	ds_read_b128 v[190:193], v152 offset:1024
	ds_read_b128 v[194:197], v152 offset:2048
	ds_read_b128 v[198:201], v152 offset:3072
	ds_read_b128 v[202:205], v152 offset:4096
	ds_read_b128 v[206:209], v152 offset:5120
	ds_read_b128 v[210:213], v152 offset:6144
	ds_read_b128 v[214:217], v152 offset:7168
	global_load_lds_dwordx4 v142, s[98:99]
	s_add_i32 m0, s33, 0xe000
	s_nop 0
	global_load_lds_dwordx4 v144, s[98:99]
	s_waitcnt vmcnt(8)
	s_waitcnt lgkmcnt(0)
	s_barrier
	s_waitcnt lgkmcnt(0)
	v_mfma_f32_16x16x32_bf16 v[126:129], v[154:157], v[186:189], v[126:129]
	v_mfma_f32_16x16x32_bf16 v[122:125], v[162:165], v[186:189], v[122:125]
	v_mfma_f32_16x16x32_bf16 v[110:113], v[154:157], v[194:197], v[110:113]
	v_mfma_f32_16x16x32_bf16 v[106:109], v[162:165], v[194:197], v[106:109]
	v_mfma_f32_16x16x32_bf16 v[94:97], v[154:157], v[202:205], v[94:97]
	v_mfma_f32_16x16x32_bf16 v[90:93], v[162:165], v[202:205], v[90:93]
	v_mfma_f32_16x16x32_bf16 v[78:81], v[154:157], v[210:213], v[78:81]
	v_mfma_f32_16x16x32_bf16 v[74:77], v[162:165], v[210:213], v[74:77]
	v_mfma_f32_16x16x32_bf16 v[126:129], v[158:161], v[190:193], v[126:129]
	v_mfma_f32_16x16x32_bf16 v[122:125], v[166:169], v[190:193], v[122:125]
	v_mfma_f32_16x16x32_bf16 v[110:113], v[158:161], v[198:201], v[110:113]
	v_mfma_f32_16x16x32_bf16 v[106:109], v[166:169], v[198:201], v[106:109]
	v_mfma_f32_16x16x32_bf16 v[94:97], v[158:161], v[206:209], v[94:97]
	v_mfma_f32_16x16x32_bf16 v[90:93], v[166:169], v[206:209], v[90:93]
	v_mfma_f32_16x16x32_bf16 v[78:81], v[158:161], v[214:217], v[78:81]
	v_mfma_f32_16x16x32_bf16 v[74:77], v[166:169], v[214:217], v[74:77]
	v_mfma_f32_16x16x32_bf16 v[118:121], v[170:173], v[186:189], v[118:121]
	v_mfma_f32_16x16x32_bf16 v[114:117], v[178:181], v[186:189], v[114:117]
	v_mfma_f32_16x16x32_bf16 v[102:105], v[170:173], v[194:197], v[102:105]
	v_mfma_f32_16x16x32_bf16 v[98:101], v[178:181], v[194:197], v[98:101]
	v_mfma_f32_16x16x32_bf16 v[86:89], v[170:173], v[202:205], v[86:89]
	v_mfma_f32_16x16x32_bf16 v[82:85], v[178:181], v[202:205], v[82:85]
	v_mfma_f32_16x16x32_bf16 v[70:73], v[170:173], v[210:213], v[70:73]
	v_mfma_f32_16x16x32_bf16 v[66:69], v[178:181], v[210:213], v[66:69]
	v_mfma_f32_16x16x32_bf16 v[118:121], v[174:177], v[190:193], v[118:121]
	v_mfma_f32_16x16x32_bf16 v[114:117], v[182:185], v[190:193], v[114:117]
	v_mfma_f32_16x16x32_bf16 v[102:105], v[174:177], v[198:201], v[102:105]
	v_mfma_f32_16x16x32_bf16 v[98:101], v[182:185], v[198:201], v[98:101]
	v_mfma_f32_16x16x32_bf16 v[86:89], v[174:177], v[206:209], v[86:89]
	v_mfma_f32_16x16x32_bf16 v[82:85], v[182:185], v[206:209], v[82:85]
	v_mfma_f32_16x16x32_bf16 v[70:73], v[174:177], v[214:217], v[70:73]
	v_mfma_f32_16x16x32_bf16 v[66:69], v[182:185], v[214:217], v[66:69]
	s_barrier
	s_add_i32 s58, s49, s3
	s_mov_b32 m0, s58
	ds_read_b128 v[186:189], v152 offset:16384
	ds_read_b128 v[190:193], v152 offset:17408
	ds_read_b128 v[194:197], v152 offset:18432
	ds_read_b128 v[198:201], v152 offset:19456
	ds_read_b128 v[202:205], v152 offset:20480
	ds_read_b128 v[206:209], v152 offset:21504
	ds_read_b128 v[210:213], v152 offset:22528
	ds_read_b128 v[214:217], v152 offset:23552
	global_load_lds_dwordx4 v132, s[36:37]
	s_add_i32 m0, s58, 0x2000
	s_add_u32 s58, s36, 0x160000
	s_addc_u32 s59, s37, 0
	s_add_i32 s60, s50, s3
	global_load_lds_dwordx4 v134, s[36:37]
	s_mov_b32 m0, s60
	s_nop 0
	global_load_lds_dwordx4 v132, s[58:59]
	s_add_i32 m0, s60, 0x2000
	s_nop 0
	global_load_lds_dwordx4 v134, s[58:59]
	s_mov_b32 m0, s33
	s_nop 0
	global_load_lds_dwordx4 v136, s[38:39]
	s_mov_b32 m0, s35
	s_nop 0
	global_load_lds_dwordx4 v138, s[38:39]
	s_waitcnt vmcnt(8)
	s_waitcnt lgkmcnt(0)
	s_barrier
	s_waitcnt lgkmcnt(0)
	v_mfma_f32_16x16x32_bf16 v[62:65], v[154:157], v[186:189], v[62:65]
	v_mfma_f32_16x16x32_bf16 v[58:61], v[162:165], v[186:189], v[58:61]
	v_mfma_f32_16x16x32_bf16 v[46:49], v[154:157], v[194:197], v[46:49]
	v_mfma_f32_16x16x32_bf16 v[42:45], v[162:165], v[194:197], v[42:45]
	v_mfma_f32_16x16x32_bf16 v[30:33], v[154:157], v[202:205], v[30:33]
	v_mfma_f32_16x16x32_bf16 v[26:29], v[162:165], v[202:205], v[26:29]
	v_mfma_f32_16x16x32_bf16 v[14:17], v[154:157], v[210:213], v[14:17]
	v_mfma_f32_16x16x32_bf16 v[10:13], v[162:165], v[210:213], v[10:13]
	v_mfma_f32_16x16x32_bf16 v[62:65], v[158:161], v[190:193], v[62:65]
	v_mfma_f32_16x16x32_bf16 v[58:61], v[166:169], v[190:193], v[58:61]
	v_mfma_f32_16x16x32_bf16 v[46:49], v[158:161], v[198:201], v[46:49]
	v_mfma_f32_16x16x32_bf16 v[42:45], v[166:169], v[198:201], v[42:45]
	v_mfma_f32_16x16x32_bf16 v[30:33], v[158:161], v[206:209], v[30:33]
	v_mfma_f32_16x16x32_bf16 v[26:29], v[166:169], v[206:209], v[26:29]
	v_mfma_f32_16x16x32_bf16 v[14:17], v[158:161], v[214:217], v[14:17]
	v_mfma_f32_16x16x32_bf16 v[10:13], v[166:169], v[214:217], v[10:13]
	v_mfma_f32_16x16x32_bf16 v[54:57], v[170:173], v[186:189], v[54:57]
	v_mfma_f32_16x16x32_bf16 v[50:53], v[178:181], v[186:189], v[50:53]
	v_mfma_f32_16x16x32_bf16 v[38:41], v[170:173], v[194:197], v[38:41]
	v_mfma_f32_16x16x32_bf16 v[34:37], v[178:181], v[194:197], v[34:37]
	v_mfma_f32_16x16x32_bf16 v[22:25], v[170:173], v[202:205], v[22:25]
	v_mfma_f32_16x16x32_bf16 v[18:21], v[178:181], v[202:205], v[18:21]
	v_mfma_f32_16x16x32_bf16 v[6:9], v[170:173], v[210:213], v[6:9]
	v_mfma_f32_16x16x32_bf16 v[2:5], v[178:181], v[210:213], v[2:5]
	v_mfma_f32_16x16x32_bf16 v[54:57], v[174:177], v[190:193], v[54:57]
	v_mfma_f32_16x16x32_bf16 v[50:53], v[182:185], v[190:193], v[50:53]
	v_mfma_f32_16x16x32_bf16 v[38:41], v[174:177], v[198:201], v[38:41]
	v_mfma_f32_16x16x32_bf16 v[34:37], v[182:185], v[198:201], v[34:37]
	v_mfma_f32_16x16x32_bf16 v[22:25], v[174:177], v[206:209], v[22:25]
	v_mfma_f32_16x16x32_bf16 v[18:21], v[182:185], v[206:209], v[18:21]
	v_mfma_f32_16x16x32_bf16 v[6:9], v[174:177], v[214:217], v[6:9]
	v_mfma_f32_16x16x32_bf16 v[2:5], v[182:185], v[214:217], v[2:5]
	s_barrier
; #define PG8_STAGE(bufoff, gbase, RR, ld) do { _Pragma("unroll") for (int _i = 0; _i < 2; ++_i) \
;         __builtin_amdgcn_global_load_lds((const unsigned*)((const char*)(gbase) + (RR)[_i] * (ld) + C2[_i]), (LAS unsigned*)(lds + (bufoff) + ldsw + _i * 8192), 16, 0, 0); } while (0)
; #define PG8_LDA(dst, b, h) do { _Pragma("unroll") for (int m = 0; m < 4; ++m) _Pragma("unroll") for (int k = 0; k < 2; ++k) dst[m][k] = *(const LAS bf16x8*)(lds + PG8_SA(b, h) + aoff + m * 2048 + k * 1024); } while (0)
; #define PG8_LDB(dst, b, h) do { _Pragma("unroll") for (int n = 0; n < 2; ++n) _Pragma("unroll") for (int k = 0; k < 2; ++k) dst[n][k] = *(const LAS bf16x8*)(lds + PG8_SB(b, h) + boff + n * 2048 + k * 1024); } while (0)
; #define PG8_MMA(ai, bj, At, Bt) do { __builtin_amdgcn_s_setprio(1); _Pragma("unroll") for (int m = 0; m < 4; ++m) _Pragma("unroll") for (int n = 0; n < 2; ++n) _Pragma("unroll") for (int k = 0; k < 2; ++k) \
;         acc[ai][bj][m][n] = __builtin_amdgcn_mfma_f32_16x16x32_bf16(Bt[n][k], At[m][k], acc[ai][bj][m][n], 0, 0, 0); __builtin_amdgcn_s_setprio(0); } while (0)
; #define PG8_WAIT_V(n) asm volatile("s_waitcnt vmcnt(" #n ")" ::: "memory")
; #define PG8_WAIT_L(n) asm volatile("s_waitcnt lgkmcnt(" #n ")" ::: "memory")
; #define PG8_BAR __builtin_amdgcn_s_barrier()
; #define PG8_SCHED __builtin_amdgcn_sched_barrier(0)
; template <class Sched, class Epi>
; __device__ __forceinline__ void gemm_run(LAS unsigned char* lds, const Sched& S, const Epi& E) {
;     ...
;             PG8_LDB(B0, 1, 0); PG8_LDB(B1, 1, 1); PG8_SCHED; PG8_LDA(At, 1, 0); PG8_STAGE(PG8_SA(0, 1), a2 + (size_t)HALF * la2, RA, la2);
;             PG8_WAIT_V(8); PG8_WAIT_L(0); PG8_BAR; PG8_MMA(0, 0, At, B0); PG8_MMA(0, 1, At, B1); PG8_BAR; PG8_SCHED;
;             PG8_LDA(At, 1, 1); PG8_STAGE(PG8_SB(1, 0), b3, RB, lb2); PG8_STAGE(PG8_SB(1, 1), b3 + (size_t)HALF * lb2, RB, lb2); PG8_STAGE(PG8_SA(1, 0), a3, RA, la2);
;             PG8_WAIT_V(8); PG8_WAIT_L(0); PG8_BAR; PG8_MMA(1, 0, At, B0); PG8_MMA(1, 1, At, B1); PG8_BAR; PG8_SCHED;
;         }
;         if (wr == 0) PG8_BAR;
	s_add_i32 s58, 0, 0x18000
	s_add_i32 s59, 0, 0x1c000
	ds_read_b128 v[154:157], v150 offset:32768
	ds_read_b128 v[158:161], v150 offset:33792
	ds_read_b128 v[162:165], v150 offset:34816
	ds_read_b128 v[166:169], v150 offset:35840
	ds_read_b128 v[170:173], v151 offset:32768
	ds_read_b128 v[174:177], v151 offset:33792
	ds_read_b128 v[178:181], v151 offset:34816
	ds_read_b128 v[182:185], v151 offset:35840
	s_add_u32 s38, s38, 0x160000
	s_addc_u32 s39, s39, 0
	s_mov_b32 m0, s40
	ds_read_b128 v[186:189], v152 offset:32768
	ds_read_b128 v[190:193], v152 offset:33792
	ds_read_b128 v[194:197], v152 offset:34816
	ds_read_b128 v[198:201], v152 offset:35840
	ds_read_b128 v[202:205], v152 offset:36864
	ds_read_b128 v[206:209], v152 offset:37888
	ds_read_b128 v[210:213], v152 offset:38912
	ds_read_b128 v[214:217], v152 offset:39936
	global_load_lds_dwordx4 v136, s[38:39]
	s_mov_b32 m0, s41
	s_nop 0
	global_load_lds_dwordx4 v138, s[38:39]
	s_waitcnt vmcnt(8)
	s_waitcnt lgkmcnt(0)
	s_barrier
	s_waitcnt lgkmcnt(0)
	v_mfma_f32_16x16x32_bf16 v[126:129], v[154:157], v[186:189], v[126:129]
	v_mfma_f32_16x16x32_bf16 v[122:125], v[162:165], v[186:189], v[122:125]
	v_mfma_f32_16x16x32_bf16 v[110:113], v[154:157], v[194:197], v[110:113]
	v_mfma_f32_16x16x32_bf16 v[106:109], v[162:165], v[194:197], v[106:109]
	v_mfma_f32_16x16x32_bf16 v[94:97], v[154:157], v[202:205], v[94:97]
	v_mfma_f32_16x16x32_bf16 v[90:93], v[162:165], v[202:205], v[90:93]
	v_mfma_f32_16x16x32_bf16 v[78:81], v[154:157], v[210:213], v[78:81]
	v_mfma_f32_16x16x32_bf16 v[74:77], v[162:165], v[210:213], v[74:77]
	v_mfma_f32_16x16x32_bf16 v[126:129], v[158:161], v[190:193], v[126:129]
	v_mfma_f32_16x16x32_bf16 v[122:125], v[166:169], v[190:193], v[122:125]
	v_mfma_f32_16x16x32_bf16 v[110:113], v[158:161], v[198:201], v[110:113]
	v_mfma_f32_16x16x32_bf16 v[106:109], v[166:169], v[198:201], v[106:109]
	v_mfma_f32_16x16x32_bf16 v[94:97], v[158:161], v[206:209], v[94:97]
	v_mfma_f32_16x16x32_bf16 v[90:93], v[166:169], v[206:209], v[90:93]
	v_mfma_f32_16x16x32_bf16 v[78:81], v[158:161], v[214:217], v[78:81]
	v_mfma_f32_16x16x32_bf16 v[74:77], v[166:169], v[214:217], v[74:77]
	v_mfma_f32_16x16x32_bf16 v[118:121], v[170:173], v[186:189], v[118:121]
	v_mfma_f32_16x16x32_bf16 v[114:117], v[178:181], v[186:189], v[114:117]
	v_mfma_f32_16x16x32_bf16 v[102:105], v[170:173], v[194:197], v[102:105]
	v_mfma_f32_16x16x32_bf16 v[98:101], v[178:181], v[194:197], v[98:101]
	v_mfma_f32_16x16x32_bf16 v[86:89], v[170:173], v[202:205], v[86:89]
	v_mfma_f32_16x16x32_bf16 v[82:85], v[178:181], v[202:205], v[82:85]
	v_mfma_f32_16x16x32_bf16 v[70:73], v[170:173], v[210:213], v[70:73]
	v_mfma_f32_16x16x32_bf16 v[66:69], v[178:181], v[210:213], v[66:69]
	v_mfma_f32_16x16x32_bf16 v[118:121], v[174:177], v[190:193], v[118:121]
	v_mfma_f32_16x16x32_bf16 v[114:117], v[182:185], v[190:193], v[114:117]
	v_mfma_f32_16x16x32_bf16 v[102:105], v[174:177], v[198:201], v[102:105]
	v_mfma_f32_16x16x32_bf16 v[98:101], v[182:185], v[198:201], v[98:101]
	v_mfma_f32_16x16x32_bf16 v[86:89], v[174:177], v[206:209], v[86:89]
	v_mfma_f32_16x16x32_bf16 v[82:85], v[182:185], v[206:209], v[82:85]
	v_mfma_f32_16x16x32_bf16 v[70:73], v[174:177], v[214:217], v[70:73]
	v_mfma_f32_16x16x32_bf16 v[66:69], v[182:185], v[214:217], v[66:69]
	s_barrier
	s_add_i32 s38, s58, s3
	s_mov_b32 m0, s38
	ds_read_b128 v[186:189], v152 offset:49152
	ds_read_b128 v[190:193], v152 offset:50176
	ds_read_b128 v[194:197], v152 offset:51200
	ds_read_b128 v[198:201], v152 offset:52224
	ds_read_b128 v[202:205], v152 offset:53248
	ds_read_b128 v[206:209], v152 offset:54272
	ds_read_b128 v[210:213], v152 offset:55296
	ds_read_b128 v[214:217], v152 offset:56320
	s_add_u32 s98, s36, 0x80
	s_addc_u32 s99, s37, 0
	global_load_lds_dwordx4 v132, s[98:99]
	s_add_i32 m0, s38, 0x2000
	s_nop 0
	global_load_lds_dwordx4 v134, s[98:99]
	s_add_u32 s36, s36, 0x160080
	s_addc_u32 s37, s37, 0
	s_add_i32 s38, s59, s3
	s_mov_b32 m0, s38
	s_nop 0
	global_load_lds_dwordx4 v132, s[36:37]
	s_add_i32 m0, s38, 0x2000
	s_nop 0
	global_load_lds_dwordx4 v134, s[36:37]
	s_mov_b32 m0, s43
	s_nop 0
	s_add_u32 s100, s100, 0x80
	s_addc_u32 s101, s101, 0
	global_load_lds_dwordx4 v136, s[100:101]
	s_mov_b32 m0, s44
	s_nop 0
	global_load_lds_dwordx4 v138, s[100:101]
	s_waitcnt vmcnt(8)
	s_waitcnt lgkmcnt(0)
	s_barrier
	s_waitcnt lgkmcnt(0)
	v_mfma_f32_16x16x32_bf16 v[62:65], v[154:157], v[186:189], v[62:65]
	v_mfma_f32_16x16x32_bf16 v[58:61], v[162:165], v[186:189], v[58:61]
	v_mfma_f32_16x16x32_bf16 v[46:49], v[154:157], v[194:197], v[46:49]
	v_mfma_f32_16x16x32_bf16 v[42:45], v[162:165], v[194:197], v[42:45]
	v_mfma_f32_16x16x32_bf16 v[30:33], v[154:157], v[202:205], v[30:33]
	v_mfma_f32_16x16x32_bf16 v[26:29], v[162:165], v[202:205], v[26:29]
	v_mfma_f32_16x16x32_bf16 v[14:17], v[154:157], v[210:213], v[14:17]
	v_mfma_f32_16x16x32_bf16 v[10:13], v[162:165], v[210:213], v[10:13]
	v_mfma_f32_16x16x32_bf16 v[62:65], v[158:161], v[190:193], v[62:65]
	v_mfma_f32_16x16x32_bf16 v[58:61], v[166:169], v[190:193], v[58:61]
	v_mfma_f32_16x16x32_bf16 v[46:49], v[158:161], v[198:201], v[46:49]
	v_mfma_f32_16x16x32_bf16 v[42:45], v[166:169], v[198:201], v[42:45]
	v_mfma_f32_16x16x32_bf16 v[30:33], v[158:161], v[206:209], v[30:33]
	v_mfma_f32_16x16x32_bf16 v[26:29], v[166:169], v[206:209], v[26:29]
	v_mfma_f32_16x16x32_bf16 v[14:17], v[158:161], v[214:217], v[14:17]
	v_mfma_f32_16x16x32_bf16 v[10:13], v[166:169], v[214:217], v[10:13]
	v_mfma_f32_16x16x32_bf16 v[54:57], v[170:173], v[186:189], v[54:57]
	v_mfma_f32_16x16x32_bf16 v[50:53], v[178:181], v[186:189], v[50:53]
	v_mfma_f32_16x16x32_bf16 v[38:41], v[170:173], v[194:197], v[38:41]
	v_mfma_f32_16x16x32_bf16 v[34:37], v[178:181], v[194:197], v[34:37]
	v_mfma_f32_16x16x32_bf16 v[22:25], v[170:173], v[202:205], v[22:25]
	v_mfma_f32_16x16x32_bf16 v[18:21], v[178:181], v[202:205], v[18:21]
	v_mfma_f32_16x16x32_bf16 v[6:9], v[170:173], v[210:213], v[6:9]
	v_mfma_f32_16x16x32_bf16 v[2:5], v[178:181], v[210:213], v[2:5]
	v_mfma_f32_16x16x32_bf16 v[54:57], v[174:177], v[190:193], v[54:57]
	v_mfma_f32_16x16x32_bf16 v[50:53], v[182:185], v[190:193], v[50:53]
	v_mfma_f32_16x16x32_bf16 v[38:41], v[174:177], v[198:201], v[38:41]
	v_mfma_f32_16x16x32_bf16 v[34:37], v[182:185], v[198:201], v[34:37]
	v_mfma_f32_16x16x32_bf16 v[22:25], v[174:177], v[206:209], v[22:25]
	v_mfma_f32_16x16x32_bf16 v[18:21], v[182:185], v[206:209], v[18:21]
	v_mfma_f32_16x16x32_bf16 v[6:9], v[174:177], v[214:217], v[6:9]
	v_mfma_f32_16x16x32_bf16 v[2:5], v[182:185], v[214:217], v[2:5]
	s_barrier
	s_add_i32 s57, s57, 2
	s_add_u32 s30, s30, 0x100
	s_addc_u32 s31, s31, 0
	s_cmpk_gt_u32 s57, 0x55
	s_cbranch_scc0 .LBB0_1124
	s_and_b64 vcc, exec, s[12:13]
	s_cbranch_vccz .LBB0_1127
	s_barrier
